# back-edge rotation (tail half): K-loop counter/pointer increments and exit compare moved from behind the loop-back barrier into the last MFMA block, all seven GEMM K-loops
# speedup vs baseline: 1.0126x; 1.0126x over previous
; #define PG8_STAGE(bufoff, gbase, voff) do { _Pragma("unroll") for (int _i = 0; _i < 2; ++_i) \
;         __builtin_amdgcn_global_load_lds((const unsigned*)((const char*)(gbase) + (voff)[_i]), (PG8_LAS unsigned*)(lds + (bufoff) + ldsw + _i * 8192), 16, 0, 0); } while (0)
; #define PG8_LDA(dst, b, h) do { _Pragma("unroll") for (int m = 0; m < 4; ++m) _Pragma("unroll") for (int k = 0; k < 2; ++k) dst[m][k] = *(const PG8_LAS bf16x8*)(lds + PG8_SA(b, h) + aoff + m * 2048 + k * 1024); } while (0)
; #define PG8_LDB(dst, b, h) do { _Pragma("unroll") for (int n = 0; n < 2; ++n) _Pragma("unroll") for (int k = 0; k < 2; ++k) dst[n][k] = *(const PG8_LAS bf16x8*)(lds + PG8_SB(b, h) + boff + n * 2048 + k * 1024); } while (0)
; template <class Epi, class Sched, bool ALIGN_EPI = false, bool SP2 = false>
; __device__ __forceinline__ void gemm_phase(PG8_LAS unsigned char* lds, const Gemm g, const Sched& S, const Epi& E) {
;     ...
;         for (int t = 0; t < nt; t += 2) {
;             const bool last = (t == nt - 2);
;             const char* a1 = cA + (size_t)(t + 1) * kstep;
;             const char* a2 = last ? nA : cA + (size_t)(t + 2) * kstep; const char* b2 = last ? nB : cB + (size_t)(t + 2) * kstep;
;             const char* a3 = a2 + kstep; const char* b3 = b2 + kstep;
;             if (last && has_next) S.a_ready(nxt);
;             if constexpr (SP2) {
;             PG8_LDB(B0, 0, 0); PG8_LDB(B1, 0, 1); PG8_SCHED; PG8_LDA(At, 0, 0); PG8_STAGE(PG8_SA(1, 1), a1 + hstep, voffA);
;             PG8_WAIT_V(8); PG8_WAIT_L(0); PG8_BAR; PG8_MMA(0, 0, At, B0); PG8_MMA(0, 1, At, B1); PG8_BAR; PG8_SCHED;
;             PG8_LDA(At, 0, 1); PG8_STAGE(PG8_SB(0, 0), b2, voffB); PG8_STAGE(PG8_SB(0, 1), b2 + hstep, voffB); PG8_STAGE(PG8_SA(0, 0), a2, voffA);
;             PG8_WAIT_V(8); PG8_WAIT_L(0); PG8_BAR; PG8_MMA(1, 0, At, B0); PG8_MMA(1, 1, At, B1); PG8_BAR; PG8_SCHED;
;             PG8_LDB(B0, 1, 0); PG8_LDB(B1, 1, 1); PG8_SCHED; PG8_LDA(At, 1, 0); PG8_STAGE(PG8_SA(0, 1), a2 + hstep, voffA);
;             PG8_WAIT_V(8); PG8_WAIT_L(0); PG8_BAR; PG8_MMA(0, 0, At, B0); PG8_MMA(0, 1, At, B1); PG8_BAR; PG8_SCHED;
;             PG8_LDA(At, 1, 1); PG8_STAGE(PG8_SB(1, 0), b3, voffB); PG8_STAGE(PG8_SB(1, 1), b3 + hstep, voffB); PG8_STAGE(PG8_SA(1, 0), a3, voffA);
;             PG8_WAIT_V(8); PG8_WAIT_L(0); PG8_BAR; PG8_MMA(1, 0, At, B0); PG8_MMA(1, 1, At, B1); PG8_BAR; PG8_SCHED;
.LBB0_133:
	s_add_u32 s18, s16, 0xfffc0080
	s_addc_u32 s19, s17, -1
	s_add_i32 s41, 0, 0x10000
	s_cmp_eq_u32 s40, 12
	s_cselect_b32 s21, s1, s19
	s_cselect_b32 s20, s11, s18
	v_add_u32_e32 v156, s41, v159
	s_cselect_b32 s19, s9, s39
	s_cselect_b32 s18, s33, s38
	s_add_i32 s44, 0, 0x14000
	ds_read_b128 v[144:147], v156
	ds_read_b128 v[148:151], v156 offset:1024
	ds_read_b128 v[152:155], v156 offset:2048
	ds_read_b128 v[162:165], v156 offset:3072
	v_add_u32_e32 v156, s44, v159
	ds_read_b128 v[166:169], v156
	ds_read_b128 v[170:173], v156 offset:1024
	ds_read_b128 v[174:177], v156 offset:2048
	ds_read_b128 v[178:181], v156 offset:3072
	v_lshl_add_u64 v[156:157], s[16:17], 0, v[140:141]
	s_add_i32 m0, s24, 0xc000
	ds_read_b128 v[182:185], v161
	ds_read_b128 v[194:197], v161 offset:1024
	ds_read_b128 v[198:201], v161 offset:2048
	ds_read_b128 v[202:205], v161 offset:3072
	ds_read_b128 v[210:213], v161 offset:4096
	ds_read_b128 v[214:217], v161 offset:5120
	ds_read_b128 v[218:221], v161 offset:6144
	ds_read_b128 v[222:225], v161 offset:7168
	global_load_lds_dwordx4 v[156:157], off
	v_lshl_add_u64 v[156:157], s[16:17], 0, v[142:143]
	s_add_i32 m0, s24, 0xe000
	s_nop 0
	global_load_lds_dwordx4 v[156:157], off
	s_waitcnt vmcnt(8)
	s_waitcnt lgkmcnt(0)
	s_barrier
	s_setprio 1
	s_waitcnt lgkmcnt(0)
	v_mfma_f32_16x16x32_bf16 v[124:127], v[144:147], v[182:185], v[124:127]
	v_mfma_f32_16x16x32_bf16 v[120:123], v[152:155], v[182:185], v[120:123]
	v_mfma_f32_16x16x32_bf16 v[108:111], v[144:147], v[198:201], v[108:111]
	v_mfma_f32_16x16x32_bf16 v[104:107], v[152:155], v[198:201], v[104:107]
	v_mfma_f32_16x16x32_bf16 v[92:95], v[144:147], v[210:213], v[92:95]
	v_mfma_f32_16x16x32_bf16 v[88:91], v[152:155], v[210:213], v[88:91]
	v_mfma_f32_16x16x32_bf16 v[76:79], v[144:147], v[218:221], v[76:79]
	v_mfma_f32_16x16x32_bf16 v[72:75], v[152:155], v[218:221], v[72:75]
	v_mfma_f32_16x16x32_bf16 v[124:127], v[148:151], v[194:197], v[124:127]
	v_mfma_f32_16x16x32_bf16 v[120:123], v[162:165], v[194:197], v[120:123]
	v_mfma_f32_16x16x32_bf16 v[108:111], v[148:151], v[202:205], v[108:111]
	v_mfma_f32_16x16x32_bf16 v[104:107], v[162:165], v[202:205], v[104:107]
	v_mfma_f32_16x16x32_bf16 v[92:95], v[148:151], v[214:217], v[92:95]
	v_mfma_f32_16x16x32_bf16 v[88:91], v[162:165], v[214:217], v[88:91]
	v_mfma_f32_16x16x32_bf16 v[76:79], v[148:151], v[222:225], v[76:79]
	v_mfma_f32_16x16x32_bf16 v[72:75], v[162:165], v[222:225], v[72:75]
	s_setprio 0
	s_setprio 1
	v_mfma_f32_16x16x32_bf16 v[116:119], v[166:169], v[182:185], v[116:119]
	v_mfma_f32_16x16x32_bf16 v[112:115], v[174:177], v[182:185], v[112:115]
	v_mfma_f32_16x16x32_bf16 v[100:103], v[166:169], v[198:201], v[100:103]
	v_mfma_f32_16x16x32_bf16 v[96:99], v[174:177], v[198:201], v[96:99]
	v_mfma_f32_16x16x32_bf16 v[84:87], v[166:169], v[210:213], v[84:87]
	v_mfma_f32_16x16x32_bf16 v[80:83], v[174:177], v[210:213], v[80:83]
	v_mfma_f32_16x16x32_bf16 v[68:71], v[166:169], v[218:221], v[68:71]
	v_mfma_f32_16x16x32_bf16 v[64:67], v[174:177], v[218:221], v[64:67]
	v_mfma_f32_16x16x32_bf16 v[116:119], v[170:173], v[194:197], v[116:119]
	v_mfma_f32_16x16x32_bf16 v[112:115], v[178:181], v[194:197], v[112:115]
	v_mfma_f32_16x16x32_bf16 v[100:103], v[170:173], v[202:205], v[100:103]
	v_mfma_f32_16x16x32_bf16 v[96:99], v[178:181], v[202:205], v[96:99]
	v_mfma_f32_16x16x32_bf16 v[84:87], v[170:173], v[214:217], v[84:87]
	v_mfma_f32_16x16x32_bf16 v[80:83], v[178:181], v[214:217], v[80:83]
	v_mfma_f32_16x16x32_bf16 v[68:71], v[170:173], v[222:225], v[68:71]
	v_mfma_f32_16x16x32_bf16 v[64:67], v[178:181], v[222:225], v[64:67]
	s_setprio 0
	s_barrier
	s_add_i32 s41, s41, s23
	v_lshl_add_u64 v[156:157], s[18:19], 0, v[130:131]
	s_mov_b32 m0, s41
	ds_read_b128 v[182:185], v161 offset:16384
	ds_read_b128 v[194:197], v161 offset:17408
	ds_read_b128 v[198:201], v161 offset:18432
	ds_read_b128 v[202:205], v161 offset:19456
	ds_read_b128 v[210:213], v161 offset:20480
	ds_read_b128 v[214:217], v161 offset:21504
	ds_read_b128 v[218:221], v161 offset:22528
	ds_read_b128 v[222:225], v161 offset:23552
	global_load_lds_dwordx4 v[156:157], off
	s_add_i32 m0, s41, 0x2000
	s_add_u32 s42, s18, 0x40000
	v_lshl_add_u64 v[186:187], s[18:19], 0, v[134:135]
	s_addc_u32 s43, s19, 0
	s_add_i32 s41, s44, s23
	global_load_lds_dwordx4 v[186:187], off
	v_lshl_add_u64 v[190:191], s[42:43], 0, v[130:131]
	s_mov_b32 m0, s41
	v_lshl_add_u64 v[226:227], s[20:21], 0, v[132:133]
	global_load_lds_dwordx4 v[190:191], off
	v_lshl_add_u64 v[190:191], s[42:43], 0, v[134:135]
	s_add_i32 m0, s41, 0x2000
	s_nop 0
	global_load_lds_dwordx4 v[190:191], off
	v_lshl_add_u64 v[190:191], s[20:21], 0, v[128:129]
	s_mov_b32 m0, s24
	s_nop 0
	global_load_lds_dwordx4 v[190:191], off
	s_mov_b32 m0, s25
	s_nop 0
	global_load_lds_dwordx4 v[226:227], off
	s_waitcnt vmcnt(8)
	s_waitcnt lgkmcnt(0)
	s_barrier
; #define PG8_STAGE(bufoff, gbase, voff) do { _Pragma("unroll") for (int _i = 0; _i < 2; ++_i) \
;         __builtin_amdgcn_global_load_lds((const unsigned*)((const char*)(gbase) + (voff)[_i]), (PG8_LAS unsigned*)(lds + (bufoff) + ldsw + _i * 8192), 16, 0, 0); } while (0)
; #define PG8_LDA(dst, b, h) do { _Pragma("unroll") for (int m = 0; m < 4; ++m) _Pragma("unroll") for (int k = 0; k < 2; ++k) dst[m][k] = *(const PG8_LAS bf16x8*)(lds + PG8_SA(b, h) + aoff + m * 2048 + k * 1024); } while (0)
; #define PG8_LDB(dst, b, h) do { _Pragma("unroll") for (int n = 0; n < 2; ++n) _Pragma("unroll") for (int k = 0; k < 2; ++k) dst[n][k] = *(const PG8_LAS bf16x8*)(lds + PG8_SB(b, h) + boff + n * 2048 + k * 1024); } while (0)
; #define PG8_MMA(ai, bj, At, Bt) do { __builtin_amdgcn_s_setprio(1); _Pragma("unroll") for (int m = 0; m < 4; ++m) _Pragma("unroll") for (int n = 0; n < 2; ++n) _Pragma("unroll") for (int k = 0; k < 2; ++k) \
;         acc[ai][bj][m][n] = __builtin_amdgcn_mfma_f32_16x16x32_bf16(Bt[n][k], At[m][k], acc[ai][bj][m][n], 0, 0, 0); __builtin_amdgcn_s_setprio(0); } while (0)
; #define PG8_WAIT_V(n) asm volatile("s_waitcnt vmcnt(" #n ")" ::: "memory")
; #define PG8_WAIT_L(n) asm volatile("s_waitcnt lgkmcnt(" #n ")" ::: "memory")
; #define PG8_BAR __builtin_amdgcn_s_barrier()
; #define PG8_SCHED __builtin_amdgcn_sched_barrier(0)
; template <class Epi, class Sched, bool ALIGN_EPI = false, bool SP2 = false>
; __device__ __forceinline__ void gemm_phase(PG8_LAS unsigned char* lds, const Gemm g, const Sched& S, const Epi& E) {
;     ...
;             PG8_WAIT_V(8); PG8_WAIT_L(0); PG8_BAR; PG8_MMA(0, 0, At, B0); PG8_MMA(0, 1, At, B1); PG8_BAR; PG8_SCHED;
;             PG8_LDA(At, 0, 1); PG8_STAGE(PG8_SB(0, 0), b2, voffB); PG8_STAGE(PG8_SB(0, 1), b2 + hstep, voffB); PG8_STAGE(PG8_SA(0, 0), a2, voffA);
;             PG8_WAIT_V(8); PG8_WAIT_L(0); PG8_BAR; PG8_MMA(1, 0, At, B0); PG8_MMA(1, 1, At, B1); PG8_BAR; PG8_SCHED;
;             PG8_LDB(B0, 1, 0); PG8_LDB(B1, 1, 1); PG8_SCHED; PG8_LDA(At, 1, 0); PG8_STAGE(PG8_SA(0, 1), a2 + hstep, voffA);
;             PG8_WAIT_V(8); PG8_WAIT_L(0); PG8_BAR; PG8_MMA(0, 0, At, B0); PG8_MMA(0, 1, At, B1); PG8_BAR; PG8_SCHED;
;             PG8_LDA(At, 1, 1); PG8_STAGE(PG8_SB(1, 0), b3, voffB); PG8_STAGE(PG8_SB(1, 1), b3 + hstep, voffB); PG8_STAGE(PG8_SA(1, 0), a3, voffA);
	s_setprio 1
	s_waitcnt lgkmcnt(0)
	v_mfma_f32_16x16x32_bf16 v[60:63], v[144:147], v[182:185], v[60:63]
	v_mfma_f32_16x16x32_bf16 v[56:59], v[152:155], v[182:185], v[56:59]
	v_mfma_f32_16x16x32_bf16 v[44:47], v[144:147], v[198:201], v[44:47]
	v_mfma_f32_16x16x32_bf16 v[40:43], v[152:155], v[198:201], v[40:43]
	v_mfma_f32_16x16x32_bf16 v[28:31], v[144:147], v[210:213], v[28:31]
	v_mfma_f32_16x16x32_bf16 v[24:27], v[152:155], v[210:213], v[24:27]
	v_mfma_f32_16x16x32_bf16 v[12:15], v[144:147], v[218:221], v[12:15]
	v_mfma_f32_16x16x32_bf16 v[8:11], v[152:155], v[218:221], v[8:11]
	v_mfma_f32_16x16x32_bf16 v[60:63], v[148:151], v[194:197], v[60:63]
	v_mfma_f32_16x16x32_bf16 v[56:59], v[162:165], v[194:197], v[56:59]
	v_mfma_f32_16x16x32_bf16 v[44:47], v[148:151], v[202:205], v[44:47]
	v_mfma_f32_16x16x32_bf16 v[40:43], v[162:165], v[202:205], v[40:43]
	v_mfma_f32_16x16x32_bf16 v[28:31], v[148:151], v[214:217], v[28:31]
	v_mfma_f32_16x16x32_bf16 v[24:27], v[162:165], v[214:217], v[24:27]
	v_mfma_f32_16x16x32_bf16 v[12:15], v[148:151], v[222:225], v[12:15]
	v_mfma_f32_16x16x32_bf16 v[8:11], v[162:165], v[222:225], v[8:11]
	s_setprio 0
	s_setprio 1
	v_mfma_f32_16x16x32_bf16 v[52:55], v[166:169], v[182:185], v[52:55]
	v_mfma_f32_16x16x32_bf16 v[48:51], v[174:177], v[182:185], v[48:51]
	v_mfma_f32_16x16x32_bf16 v[36:39], v[166:169], v[198:201], v[36:39]
	v_mfma_f32_16x16x32_bf16 v[32:35], v[174:177], v[198:201], v[32:35]
	v_mfma_f32_16x16x32_bf16 v[20:23], v[166:169], v[210:213], v[20:23]
	v_mfma_f32_16x16x32_bf16 v[16:19], v[174:177], v[210:213], v[16:19]
	v_mfma_f32_16x16x32_bf16 v[4:7], v[166:169], v[218:221], v[4:7]
	v_mfma_f32_16x16x32_bf16 v[0:3], v[174:177], v[218:221], v[0:3]
	v_mfma_f32_16x16x32_bf16 v[52:55], v[170:173], v[194:197], v[52:55]
	v_mfma_f32_16x16x32_bf16 v[48:51], v[178:181], v[194:197], v[48:51]
	v_mfma_f32_16x16x32_bf16 v[36:39], v[170:173], v[202:205], v[36:39]
	v_mfma_f32_16x16x32_bf16 v[32:35], v[178:181], v[202:205], v[32:35]
	v_mfma_f32_16x16x32_bf16 v[20:23], v[170:173], v[214:217], v[20:23]
	v_mfma_f32_16x16x32_bf16 v[16:19], v[178:181], v[214:217], v[16:19]
	v_mfma_f32_16x16x32_bf16 v[4:7], v[170:173], v[222:225], v[4:7]
	v_mfma_f32_16x16x32_bf16 v[0:3], v[178:181], v[222:225], v[0:3]
	s_setprio 0
	s_barrier
	s_add_i32 s41, 0, 0x18000
	s_add_i32 s42, 0, 0x1c000
	v_add_u32_e32 v162, s41, v159
	v_add_u32_e32 v178, s42, v159
	ds_read_b128 v[144:147], v162
	ds_read_b128 v[148:151], v162 offset:1024
	ds_read_b128 v[152:155], v162 offset:2048
	ds_read_b128 v[162:165], v162 offset:3072
	ds_read_b128 v[166:169], v178
	ds_read_b128 v[170:173], v178 offset:1024
	ds_read_b128 v[174:177], v178 offset:2048
	ds_read_b128 v[178:181], v178 offset:3072
	s_add_u32 s20, s20, 0x40000
	s_addc_u32 s21, s21, 0
	s_mov_b32 m0, s26
	v_lshl_add_u64 v[228:229], s[20:21], 0, v[128:129]
	ds_read_b128 v[182:185], v161 offset:32768
	ds_read_b128 v[194:197], v161 offset:33792
	ds_read_b128 v[198:201], v161 offset:34816
	ds_read_b128 v[202:205], v161 offset:35840
	ds_read_b128 v[210:213], v161 offset:36864
	ds_read_b128 v[214:217], v161 offset:37888
	ds_read_b128 v[218:221], v161 offset:38912
	ds_read_b128 v[222:225], v161 offset:39936
	global_load_lds_dwordx4 v[228:229], off
	v_lshl_add_u64 v[228:229], s[20:21], 0, v[132:133]
	s_mov_b32 m0, s27
	s_nop 0
	global_load_lds_dwordx4 v[228:229], off
	s_waitcnt vmcnt(8)
	s_waitcnt lgkmcnt(0)
	s_barrier
	s_setprio 1
	s_waitcnt lgkmcnt(0)
	v_mfma_f32_16x16x32_bf16 v[124:127], v[144:147], v[182:185], v[124:127]
	v_mfma_f32_16x16x32_bf16 v[120:123], v[152:155], v[182:185], v[120:123]
	v_mfma_f32_16x16x32_bf16 v[108:111], v[144:147], v[198:201], v[108:111]
	v_mfma_f32_16x16x32_bf16 v[104:107], v[152:155], v[198:201], v[104:107]
	v_mfma_f32_16x16x32_bf16 v[92:95], v[144:147], v[210:213], v[92:95]
	v_mfma_f32_16x16x32_bf16 v[88:91], v[152:155], v[210:213], v[88:91]
	v_mfma_f32_16x16x32_bf16 v[76:79], v[144:147], v[218:221], v[76:79]
	v_mfma_f32_16x16x32_bf16 v[72:75], v[152:155], v[218:221], v[72:75]
	v_mfma_f32_16x16x32_bf16 v[124:127], v[148:151], v[194:197], v[124:127]
	v_mfma_f32_16x16x32_bf16 v[120:123], v[162:165], v[194:197], v[120:123]
	v_mfma_f32_16x16x32_bf16 v[108:111], v[148:151], v[202:205], v[108:111]
	v_mfma_f32_16x16x32_bf16 v[104:107], v[162:165], v[202:205], v[104:107]
	v_mfma_f32_16x16x32_bf16 v[92:95], v[148:151], v[214:217], v[92:95]
	v_mfma_f32_16x16x32_bf16 v[88:91], v[162:165], v[214:217], v[88:91]
	v_mfma_f32_16x16x32_bf16 v[76:79], v[148:151], v[222:225], v[76:79]
	v_mfma_f32_16x16x32_bf16 v[72:75], v[162:165], v[222:225], v[72:75]
	s_setprio 0
	s_setprio 1
	v_mfma_f32_16x16x32_bf16 v[116:119], v[166:169], v[182:185], v[116:119]
	v_mfma_f32_16x16x32_bf16 v[112:115], v[174:177], v[182:185], v[112:115]
	v_mfma_f32_16x16x32_bf16 v[100:103], v[166:169], v[198:201], v[100:103]
	v_mfma_f32_16x16x32_bf16 v[96:99], v[174:177], v[198:201], v[96:99]
	v_mfma_f32_16x16x32_bf16 v[84:87], v[166:169], v[210:213], v[84:87]
	v_mfma_f32_16x16x32_bf16 v[80:83], v[174:177], v[210:213], v[80:83]
	v_mfma_f32_16x16x32_bf16 v[68:71], v[166:169], v[218:221], v[68:71]
	v_mfma_f32_16x16x32_bf16 v[64:67], v[174:177], v[218:221], v[64:67]
	v_mfma_f32_16x16x32_bf16 v[116:119], v[170:173], v[194:197], v[116:119]
	v_mfma_f32_16x16x32_bf16 v[112:115], v[178:181], v[194:197], v[112:115]
	v_mfma_f32_16x16x32_bf16 v[100:103], v[170:173], v[202:205], v[100:103]
	v_mfma_f32_16x16x32_bf16 v[96:99], v[178:181], v[202:205], v[96:99]
	v_mfma_f32_16x16x32_bf16 v[84:87], v[170:173], v[214:217], v[84:87]
	v_mfma_f32_16x16x32_bf16 v[80:83], v[178:181], v[214:217], v[80:83]
	v_mfma_f32_16x16x32_bf16 v[68:71], v[170:173], v[222:225], v[68:71]
	v_mfma_f32_16x16x32_bf16 v[64:67], v[178:181], v[222:225], v[64:67]
	s_setprio 0
	s_barrier
; #define PG8_STAGE(bufoff, gbase, voff) do { _Pragma("unroll") for (int _i = 0; _i < 2; ++_i) \
;         __builtin_amdgcn_global_load_lds((const unsigned*)((const char*)(gbase) + (voff)[_i]), (PG8_LAS unsigned*)(lds + (bufoff) + ldsw + _i * 8192), 16, 0, 0); } while (0)
; #define PG8_LDA(dst, b, h) do { _Pragma("unroll") for (int m = 0; m < 4; ++m) _Pragma("unroll") for (int k = 0; k < 2; ++k) dst[m][k] = *(const PG8_LAS bf16x8*)(lds + PG8_SA(b, h) + aoff + m * 2048 + k * 1024); } while (0)
; #define PG8_MMA(ai, bj, At, Bt) do { __builtin_amdgcn_s_setprio(1); _Pragma("unroll") for (int m = 0; m < 4; ++m) _Pragma("unroll") for (int n = 0; n < 2; ++n) _Pragma("unroll") for (int k = 0; k < 2; ++k) \
;         acc[ai][bj][m][n] = __builtin_amdgcn_mfma_f32_16x16x32_bf16(Bt[n][k], At[m][k], acc[ai][bj][m][n], 0, 0, 0); __builtin_amdgcn_s_setprio(0); } while (0)
; #define PG8_WAIT_V(n) asm volatile("s_waitcnt vmcnt(" #n ")" ::: "memory")
; #define PG8_WAIT_L(n) asm volatile("s_waitcnt lgkmcnt(" #n ")" ::: "memory")
; #define PG8_BAR __builtin_amdgcn_s_barrier()
; #define PG8_SCHED __builtin_amdgcn_sched_barrier(0)
; template <class Epi, class Sched, bool ALIGN_EPI = false, bool SP2 = false>
; __device__ __forceinline__ void gemm_phase(PG8_LAS unsigned char* lds, const Gemm g, const Sched& S, const Epi& E) {
;     ...
;         for (int t = 0; t < nt; t += 2) {
;             const bool last = (t == nt - 2);
;             const char* a1 = cA + (size_t)(t + 1) * kstep;
;             const char* a2 = last ? nA : cA + (size_t)(t + 2) * kstep; const char* b2 = last ? nB : cB + (size_t)(t + 2) * kstep;
;     ...
;             PG8_LDA(At, 1, 1); PG8_STAGE(PG8_SB(1, 0), b3, voffB); PG8_STAGE(PG8_SB(1, 1), b3 + hstep, voffB); PG8_STAGE(PG8_SA(1, 0), a3, voffA);
;             PG8_WAIT_V(8); PG8_WAIT_L(0); PG8_BAR; PG8_MMA(1, 0, At, B0); PG8_MMA(1, 1, At, B1); PG8_BAR; PG8_SCHED;
	s_add_i32 s20, s41, s23
	v_lshl_add_u64 v[156:157], v[156:157], 0, s[46:47]
	s_mov_b32 m0, s20
	ds_read_b128 v[182:185], v161 offset:49152
	ds_read_b128 v[194:197], v161 offset:50176
	ds_read_b128 v[198:201], v161 offset:51200
	ds_read_b128 v[202:205], v161 offset:52224
	ds_read_b128 v[210:213], v161 offset:53248
	ds_read_b128 v[214:217], v161 offset:54272
	ds_read_b128 v[218:221], v161 offset:55296
	ds_read_b128 v[222:225], v161 offset:56320
	global_load_lds_dwordx4 v[156:157], off
	s_add_i32 m0, s20, 0x2000
	s_add_u32 s18, s18, 0x40080
	v_lshl_add_u64 v[156:157], v[186:187], 0, s[46:47]
	s_addc_u32 s19, s19, 0
	s_add_i32 s20, s42, s23
	global_load_lds_dwordx4 v[156:157], off
	v_lshl_add_u64 v[156:157], s[18:19], 0, v[130:131]
	s_mov_b32 m0, s20
	s_nop 0
	global_load_lds_dwordx4 v[156:157], off
	v_lshl_add_u64 v[156:157], s[18:19], 0, v[134:135]
	s_add_i32 m0, s20, 0x2000
	s_nop 0
	global_load_lds_dwordx4 v[156:157], off
	v_lshl_add_u64 v[156:157], v[190:191], 0, s[46:47]
	s_mov_b32 m0, s30
	s_nop 0
	global_load_lds_dwordx4 v[156:157], off
	v_lshl_add_u64 v[156:157], v[226:227], 0, s[46:47]
	s_mov_b32 m0, s31
	s_nop 0
	global_load_lds_dwordx4 v[156:157], off
	s_waitcnt vmcnt(8)
	s_waitcnt lgkmcnt(0)
	s_barrier
	s_setprio 1
	s_waitcnt lgkmcnt(0)
	v_mfma_f32_16x16x32_bf16 v[60:63], v[144:147], v[182:185], v[60:63]
	v_mfma_f32_16x16x32_bf16 v[56:59], v[152:155], v[182:185], v[56:59]
	v_mfma_f32_16x16x32_bf16 v[44:47], v[144:147], v[198:201], v[44:47]
	v_mfma_f32_16x16x32_bf16 v[40:43], v[152:155], v[198:201], v[40:43]
	v_mfma_f32_16x16x32_bf16 v[28:31], v[144:147], v[210:213], v[28:31]
	v_mfma_f32_16x16x32_bf16 v[24:27], v[152:155], v[210:213], v[24:27]
	v_mfma_f32_16x16x32_bf16 v[12:15], v[144:147], v[218:221], v[12:15]
	v_mfma_f32_16x16x32_bf16 v[8:11], v[152:155], v[218:221], v[8:11]
	v_mfma_f32_16x16x32_bf16 v[60:63], v[148:151], v[194:197], v[60:63]
	v_mfma_f32_16x16x32_bf16 v[56:59], v[162:165], v[194:197], v[56:59]
	v_mfma_f32_16x16x32_bf16 v[44:47], v[148:151], v[202:205], v[44:47]
	v_mfma_f32_16x16x32_bf16 v[40:43], v[162:165], v[202:205], v[40:43]
	v_mfma_f32_16x16x32_bf16 v[28:31], v[148:151], v[214:217], v[28:31]
	v_mfma_f32_16x16x32_bf16 v[24:27], v[162:165], v[214:217], v[24:27]
	v_mfma_f32_16x16x32_bf16 v[12:15], v[148:151], v[222:225], v[12:15]
	v_mfma_f32_16x16x32_bf16 v[8:11], v[162:165], v[222:225], v[8:11]
	s_setprio 0
	s_setprio 1
	v_mfma_f32_16x16x32_bf16 v[52:55], v[166:169], v[182:185], v[52:55]
	v_mfma_f32_16x16x32_bf16 v[48:51], v[174:177], v[182:185], v[48:51]
	s_add_i32 s40, s40, 2
	s_add_u32 s16, s16, 0x100
	s_addc_u32 s17, s17, 0
	s_add_u32 s38, s38, 0x100
	s_addc_u32 s39, s39, 0
	s_cmp_gt_u32 s40, 13
	v_mfma_f32_16x16x32_bf16 v[36:39], v[166:169], v[198:201], v[36:39]
	v_mfma_f32_16x16x32_bf16 v[32:35], v[174:177], v[198:201], v[32:35]
	v_mfma_f32_16x16x32_bf16 v[20:23], v[166:169], v[210:213], v[20:23]
	v_mfma_f32_16x16x32_bf16 v[16:19], v[174:177], v[210:213], v[16:19]
	v_mfma_f32_16x16x32_bf16 v[4:7], v[166:169], v[218:221], v[4:7]
	v_mfma_f32_16x16x32_bf16 v[0:3], v[174:177], v[218:221], v[0:3]
	v_mfma_f32_16x16x32_bf16 v[52:55], v[170:173], v[194:197], v[52:55]
	v_mfma_f32_16x16x32_bf16 v[48:51], v[178:181], v[194:197], v[48:51]
	v_mfma_f32_16x16x32_bf16 v[36:39], v[170:173], v[202:205], v[36:39]
	v_mfma_f32_16x16x32_bf16 v[32:35], v[178:181], v[202:205], v[32:35]
	v_mfma_f32_16x16x32_bf16 v[20:23], v[170:173], v[214:217], v[20:23]
	v_mfma_f32_16x16x32_bf16 v[16:19], v[178:181], v[214:217], v[16:19]
	v_mfma_f32_16x16x32_bf16 v[4:7], v[170:173], v[222:225], v[4:7]
	v_mfma_f32_16x16x32_bf16 v[0:3], v[178:181], v[222:225], v[0:3]
	s_setprio 0
	s_barrier
	s_cbranch_scc0 .LBB0_133
	s_and_b64 vcc, exec, s[6:7]
	s_cbranch_vccz .LBB0_136
	s_barrier

; #define PG8_STAGE(bufoff, gbase, voff) do { _Pragma("unroll") for (int _i = 0; _i < 2; ++_i) \
;         __builtin_amdgcn_global_load_lds((const unsigned*)((const char*)(gbase) + (voff)[_i]), (PG8_LAS unsigned*)(lds + (bufoff) + ldsw + _i * 8192), 16, 0, 0); } while (0)
; #define PG8_LDA(dst, b, h) do { _Pragma("unroll") for (int m = 0; m < 4; ++m) _Pragma("unroll") for (int k = 0; k < 2; ++k) dst[m][k] = *(const PG8_LAS bf16x8*)(lds + PG8_SA(b, h) + aoff + m * 2048 + k * 1024); } while (0)
; #define PG8_LDB(dst, b, h) do { _Pragma("unroll") for (int n = 0; n < 2; ++n) _Pragma("unroll") for (int k = 0; k < 2; ++k) dst[n][k] = *(const PG8_LAS bf16x8*)(lds + PG8_SB(b, h) + boff + n * 2048 + k * 1024); } while (0)
; template <class Epi, class Sched, bool ALIGN_EPI = false, bool SP2 = false>
; __device__ __forceinline__ void gemm_phase(PG8_LAS unsigned char* lds, const Gemm g, const Sched& S, const Epi& E) {
;     ...
;         for (int t = 0; t < nt; t += 2) {
;             const bool last = (t == nt - 2);
;             const char* a1 = cA + (size_t)(t + 1) * kstep;
;             const char* a2 = last ? nA : cA + (size_t)(t + 2) * kstep; const char* b2 = last ? nB : cB + (size_t)(t + 2) * kstep;
;             const char* a3 = a2 + kstep; const char* b3 = b2 + kstep;
;             if (last && has_next) S.a_ready(nxt);
;             if constexpr (SP2) {
;             PG8_LDB(B0, 0, 0); PG8_LDB(B1, 0, 1); PG8_SCHED; PG8_LDA(At, 0, 0); PG8_STAGE(PG8_SA(1, 1), a1 + hstep, voffA);
;             PG8_WAIT_V(8); PG8_WAIT_L(0); PG8_BAR; PG8_MMA(0, 0, At, B0); PG8_MMA(0, 1, At, B1); PG8_BAR; PG8_SCHED;
;             PG8_LDA(At, 0, 1); PG8_STAGE(PG8_SB(0, 0), b2, voffB); PG8_STAGE(PG8_SB(0, 1), b2 + hstep, voffB); PG8_STAGE(PG8_SA(0, 0), a2, voffA);
;             PG8_WAIT_V(8); PG8_WAIT_L(0); PG8_BAR; PG8_MMA(1, 0, At, B0); PG8_MMA(1, 1, At, B1); PG8_BAR; PG8_SCHED;
;             PG8_LDB(B0, 1, 0); PG8_LDB(B1, 1, 1); PG8_SCHED; PG8_LDA(At, 1, 0); PG8_STAGE(PG8_SA(0, 1), a2 + hstep, voffA);
;             PG8_WAIT_V(8); PG8_WAIT_L(0); PG8_BAR; PG8_MMA(0, 0, At, B0); PG8_MMA(0, 1, At, B1); PG8_BAR; PG8_SCHED;
;             PG8_LDA(At, 1, 1); PG8_STAGE(PG8_SB(1, 0), b3, voffB); PG8_STAGE(PG8_SB(1, 1), b3 + hstep, voffB); PG8_STAGE(PG8_SA(1, 0), a3, voffA);
;             PG8_WAIT_V(8); PG8_WAIT_L(0); PG8_BAR; PG8_MMA(1, 0, At, B0); PG8_MMA(1, 1, At, B1); PG8_BAR; PG8_SCHED;
.LBB0_529:
	s_add_u32 s6, s4, 0xebb40080
	s_addc_u32 s7, s5, -1
	s_cmp_lg_u32 s21, 12
	s_cselect_b32 s6, s6, 0
	s_cselect_b32 s7, s7, 0
	s_add_u32 s8, s2, s6
	s_addc_u32 s9, s3, s7
	s_add_i32 s22, 0, 0x10000
	s_add_u32 s6, s0, s6
	s_addc_u32 s7, s1, s7
	s_add_i32 s24, 0, 0x14000
	v_add_u32_e32 v158, s22, v144
	v_add_u32_e32 v174, s24, v144
	ds_read_b128 v[146:149], v158
	ds_read_b128 v[150:153], v158 offset:1024
	ds_read_b128 v[154:157], v158 offset:2048
	ds_read_b128 v[158:161], v158 offset:3072
	ds_read_b128 v[162:165], v174
	ds_read_b128 v[166:169], v174 offset:1024
	ds_read_b128 v[170:173], v174 offset:2048
	ds_read_b128 v[174:177], v174 offset:3072
	v_lshl_add_u64 v[186:187], v[136:137], 0, s[4:5]
	s_add_i32 m0, s16, 0xc000
	ds_read_b128 v[178:181], v145
	ds_read_b128 v[182:185], v145 offset:1024
	ds_read_b128 v[194:197], v145 offset:2048
	ds_read_b128 v[198:201], v145 offset:3072
	ds_read_b128 v[202:205], v145 offset:4096
	ds_read_b128 v[210:213], v145 offset:5120
	ds_read_b128 v[214:217], v145 offset:6144
	ds_read_b128 v[218:221], v145 offset:7168
	global_load_lds_dwordx4 v[186:187], off
	v_lshl_add_u64 v[186:187], v[134:135], 0, s[4:5]
	s_add_i32 m0, s16, 0xe000
	s_nop 0
	global_load_lds_dwordx4 v[186:187], off
	s_waitcnt vmcnt(8)
	s_waitcnt lgkmcnt(0)
	s_barrier
	s_setprio 1
	s_waitcnt lgkmcnt(0)
	v_mfma_f32_16x16x32_bf16 v[124:127], v[146:149], v[178:181], v[124:127]
	v_mfma_f32_16x16x32_bf16 v[120:123], v[154:157], v[178:181], v[120:123]
	v_mfma_f32_16x16x32_bf16 v[108:111], v[146:149], v[194:197], v[108:111]
	v_mfma_f32_16x16x32_bf16 v[104:107], v[154:157], v[194:197], v[104:107]
	v_mfma_f32_16x16x32_bf16 v[92:95], v[146:149], v[202:205], v[92:95]
	v_mfma_f32_16x16x32_bf16 v[88:91], v[154:157], v[202:205], v[88:91]
	v_mfma_f32_16x16x32_bf16 v[76:79], v[146:149], v[214:217], v[76:79]
	v_mfma_f32_16x16x32_bf16 v[72:75], v[154:157], v[214:217], v[72:75]
	v_mfma_f32_16x16x32_bf16 v[124:127], v[150:153], v[182:185], v[124:127]
	v_mfma_f32_16x16x32_bf16 v[120:123], v[158:161], v[182:185], v[120:123]
	v_mfma_f32_16x16x32_bf16 v[108:111], v[150:153], v[198:201], v[108:111]
	v_mfma_f32_16x16x32_bf16 v[104:107], v[158:161], v[198:201], v[104:107]
	v_mfma_f32_16x16x32_bf16 v[92:95], v[150:153], v[210:213], v[92:95]
	v_mfma_f32_16x16x32_bf16 v[88:91], v[158:161], v[210:213], v[88:91]
	v_mfma_f32_16x16x32_bf16 v[76:79], v[150:153], v[218:221], v[76:79]
	v_mfma_f32_16x16x32_bf16 v[72:75], v[158:161], v[218:221], v[72:75]
	s_setprio 0
	s_setprio 1
	v_mfma_f32_16x16x32_bf16 v[116:119], v[162:165], v[178:181], v[116:119]
	v_mfma_f32_16x16x32_bf16 v[112:115], v[170:173], v[178:181], v[112:115]
	v_mfma_f32_16x16x32_bf16 v[100:103], v[162:165], v[194:197], v[100:103]
	v_mfma_f32_16x16x32_bf16 v[96:99], v[170:173], v[194:197], v[96:99]
	v_mfma_f32_16x16x32_bf16 v[84:87], v[162:165], v[202:205], v[84:87]
	v_mfma_f32_16x16x32_bf16 v[80:83], v[170:173], v[202:205], v[80:83]
	v_mfma_f32_16x16x32_bf16 v[68:71], v[162:165], v[214:217], v[68:71]
	v_mfma_f32_16x16x32_bf16 v[64:67], v[170:173], v[214:217], v[64:67]
	v_mfma_f32_16x16x32_bf16 v[116:119], v[166:169], v[182:185], v[116:119]
	v_mfma_f32_16x16x32_bf16 v[112:115], v[174:177], v[182:185], v[112:115]
	v_mfma_f32_16x16x32_bf16 v[100:103], v[166:169], v[198:201], v[100:103]
	v_mfma_f32_16x16x32_bf16 v[96:99], v[174:177], v[198:201], v[96:99]
	v_mfma_f32_16x16x32_bf16 v[84:87], v[166:169], v[210:213], v[84:87]
	v_mfma_f32_16x16x32_bf16 v[80:83], v[174:177], v[210:213], v[80:83]
	v_mfma_f32_16x16x32_bf16 v[68:71], v[166:169], v[218:221], v[68:71]
	v_mfma_f32_16x16x32_bf16 v[64:67], v[174:177], v[218:221], v[64:67]
	s_setprio 0
	s_barrier
	s_add_i32 s22, s22, s15
	v_lshl_add_u64 v[186:187], s[6:7], 0, v[188:189]
	s_mov_b32 m0, s22
	ds_read_b128 v[178:181], v145 offset:16384
	ds_read_b128 v[182:185], v145 offset:17408
	ds_read_b128 v[194:197], v145 offset:18432
	ds_read_b128 v[198:201], v145 offset:19456
	ds_read_b128 v[202:205], v145 offset:20480
	ds_read_b128 v[210:213], v145 offset:21504
	ds_read_b128 v[214:217], v145 offset:22528
	ds_read_b128 v[218:221], v145 offset:23552
	global_load_lds_dwordx4 v[186:187], off
	s_add_i32 m0, s22, 0x2000
	s_add_u32 s22, s6, 0x40000
	v_lshl_add_u64 v[190:191], s[6:7], 0, v[128:129]
	s_addc_u32 s23, s7, 0
	s_add_i32 s24, s24, s15
	global_load_lds_dwordx4 v[190:191], off
	v_lshl_add_u64 v[222:223], s[22:23], 0, v[188:189]
	s_mov_b32 m0, s24
	v_lshl_add_u64 v[224:225], s[8:9], 0, v[130:131]
	global_load_lds_dwordx4 v[222:223], off
	v_lshl_add_u64 v[222:223], s[22:23], 0, v[128:129]
	s_add_i32 m0, s24, 0x2000
	s_nop 0
	global_load_lds_dwordx4 v[222:223], off
	v_lshl_add_u64 v[222:223], s[8:9], 0, v[132:133]
	s_mov_b32 m0, s16
	s_nop 0
	global_load_lds_dwordx4 v[222:223], off
	s_mov_b32 m0, s12
	s_nop 0
	global_load_lds_dwordx4 v[224:225], off
	s_waitcnt vmcnt(8)
	s_waitcnt lgkmcnt(0)
	s_barrier
; #define PG8_STAGE(bufoff, gbase, voff) do { _Pragma("unroll") for (int _i = 0; _i < 2; ++_i) \
;         __builtin_amdgcn_global_load_lds((const unsigned*)((const char*)(gbase) + (voff)[_i]), (PG8_LAS unsigned*)(lds + (bufoff) + ldsw + _i * 8192), 16, 0, 0); } while (0)
; #define PG8_LDA(dst, b, h) do { _Pragma("unroll") for (int m = 0; m < 4; ++m) _Pragma("unroll") for (int k = 0; k < 2; ++k) dst[m][k] = *(const PG8_LAS bf16x8*)(lds + PG8_SA(b, h) + aoff + m * 2048 + k * 1024); } while (0)
; #define PG8_LDB(dst, b, h) do { _Pragma("unroll") for (int n = 0; n < 2; ++n) _Pragma("unroll") for (int k = 0; k < 2; ++k) dst[n][k] = *(const PG8_LAS bf16x8*)(lds + PG8_SB(b, h) + boff + n * 2048 + k * 1024); } while (0)
; #define PG8_MMA(ai, bj, At, Bt) do { __builtin_amdgcn_s_setprio(1); _Pragma("unroll") for (int m = 0; m < 4; ++m) _Pragma("unroll") for (int n = 0; n < 2; ++n) _Pragma("unroll") for (int k = 0; k < 2; ++k) \
;         acc[ai][bj][m][n] = __builtin_amdgcn_mfma_f32_16x16x32_bf16(Bt[n][k], At[m][k], acc[ai][bj][m][n], 0, 0, 0); __builtin_amdgcn_s_setprio(0); } while (0)
; #define PG8_WAIT_V(n) asm volatile("s_waitcnt vmcnt(" #n ")" ::: "memory")
; #define PG8_WAIT_L(n) asm volatile("s_waitcnt lgkmcnt(" #n ")" ::: "memory")
; #define PG8_BAR __builtin_amdgcn_s_barrier()
; #define PG8_SCHED __builtin_amdgcn_sched_barrier(0)
; template <class Epi, class Sched, bool ALIGN_EPI = false, bool SP2 = false>
; __device__ __forceinline__ void gemm_phase(PG8_LAS unsigned char* lds, const Gemm g, const Sched& S, const Epi& E) {
;     ...
;             PG8_WAIT_V(8); PG8_WAIT_L(0); PG8_BAR; PG8_MMA(0, 0, At, B0); PG8_MMA(0, 1, At, B1); PG8_BAR; PG8_SCHED;
;             PG8_LDA(At, 0, 1); PG8_STAGE(PG8_SB(0, 0), b2, voffB); PG8_STAGE(PG8_SB(0, 1), b2 + hstep, voffB); PG8_STAGE(PG8_SA(0, 0), a2, voffA);
;             PG8_WAIT_V(8); PG8_WAIT_L(0); PG8_BAR; PG8_MMA(1, 0, At, B0); PG8_MMA(1, 1, At, B1); PG8_BAR; PG8_SCHED;
;             PG8_LDB(B0, 1, 0); PG8_LDB(B1, 1, 1); PG8_SCHED; PG8_LDA(At, 1, 0); PG8_STAGE(PG8_SA(0, 1), a2 + hstep, voffA);
;             PG8_WAIT_V(8); PG8_WAIT_L(0); PG8_BAR; PG8_MMA(0, 0, At, B0); PG8_MMA(0, 1, At, B1); PG8_BAR; PG8_SCHED;
;             PG8_LDA(At, 1, 1); PG8_STAGE(PG8_SB(1, 0), b3, voffB); PG8_STAGE(PG8_SB(1, 1), b3 + hstep, voffB); PG8_STAGE(PG8_SA(1, 0), a3, voffA);
	s_setprio 1
	s_waitcnt lgkmcnt(0)
	v_mfma_f32_16x16x32_bf16 v[60:63], v[146:149], v[178:181], v[60:63]
	v_mfma_f32_16x16x32_bf16 v[56:59], v[154:157], v[178:181], v[56:59]
	v_mfma_f32_16x16x32_bf16 v[44:47], v[146:149], v[194:197], v[44:47]
	v_mfma_f32_16x16x32_bf16 v[40:43], v[154:157], v[194:197], v[40:43]
	v_mfma_f32_16x16x32_bf16 v[28:31], v[146:149], v[202:205], v[28:31]
	v_mfma_f32_16x16x32_bf16 v[24:27], v[154:157], v[202:205], v[24:27]
	v_mfma_f32_16x16x32_bf16 v[12:15], v[146:149], v[214:217], v[12:15]
	v_mfma_f32_16x16x32_bf16 v[8:11], v[154:157], v[214:217], v[8:11]
	v_mfma_f32_16x16x32_bf16 v[60:63], v[150:153], v[182:185], v[60:63]
	v_mfma_f32_16x16x32_bf16 v[56:59], v[158:161], v[182:185], v[56:59]
	v_mfma_f32_16x16x32_bf16 v[44:47], v[150:153], v[198:201], v[44:47]
	v_mfma_f32_16x16x32_bf16 v[40:43], v[158:161], v[198:201], v[40:43]
	v_mfma_f32_16x16x32_bf16 v[28:31], v[150:153], v[210:213], v[28:31]
	v_mfma_f32_16x16x32_bf16 v[24:27], v[158:161], v[210:213], v[24:27]
	v_mfma_f32_16x16x32_bf16 v[12:15], v[150:153], v[218:221], v[12:15]
	v_mfma_f32_16x16x32_bf16 v[8:11], v[158:161], v[218:221], v[8:11]
	s_setprio 0
	s_setprio 1
	v_mfma_f32_16x16x32_bf16 v[52:55], v[162:165], v[178:181], v[52:55]
	v_mfma_f32_16x16x32_bf16 v[48:51], v[170:173], v[178:181], v[48:51]
	v_mfma_f32_16x16x32_bf16 v[36:39], v[162:165], v[194:197], v[36:39]
	v_mfma_f32_16x16x32_bf16 v[32:35], v[170:173], v[194:197], v[32:35]
	v_mfma_f32_16x16x32_bf16 v[20:23], v[162:165], v[202:205], v[20:23]
	v_mfma_f32_16x16x32_bf16 v[16:19], v[170:173], v[202:205], v[16:19]
	v_mfma_f32_16x16x32_bf16 v[4:7], v[162:165], v[214:217], v[4:7]
	v_mfma_f32_16x16x32_bf16 v[0:3], v[170:173], v[214:217], v[0:3]
	v_mfma_f32_16x16x32_bf16 v[52:55], v[166:169], v[182:185], v[52:55]
	v_mfma_f32_16x16x32_bf16 v[48:51], v[174:177], v[182:185], v[48:51]
	v_mfma_f32_16x16x32_bf16 v[36:39], v[166:169], v[198:201], v[36:39]
	v_mfma_f32_16x16x32_bf16 v[32:35], v[174:177], v[198:201], v[32:35]
	v_mfma_f32_16x16x32_bf16 v[20:23], v[166:169], v[210:213], v[20:23]
	v_mfma_f32_16x16x32_bf16 v[16:19], v[174:177], v[210:213], v[16:19]
	v_mfma_f32_16x16x32_bf16 v[4:7], v[166:169], v[218:221], v[4:7]
	v_mfma_f32_16x16x32_bf16 v[0:3], v[174:177], v[218:221], v[0:3]
	s_setprio 0
	s_barrier
	s_add_i32 s22, 0, 0x18000
	s_add_i32 s23, 0, 0x1c000
	v_add_u32_e32 v158, s22, v144
	v_add_u32_e32 v174, s23, v144
	ds_read_b128 v[146:149], v158
	ds_read_b128 v[150:153], v158 offset:1024
	ds_read_b128 v[154:157], v158 offset:2048
	ds_read_b128 v[158:161], v158 offset:3072
	ds_read_b128 v[162:165], v174
	ds_read_b128 v[166:169], v174 offset:1024
	ds_read_b128 v[170:173], v174 offset:2048
	ds_read_b128 v[174:177], v174 offset:3072
	s_add_u32 s8, s8, 0x40000
	s_addc_u32 s9, s9, 0
	s_mov_b32 m0, s13
	v_lshl_add_u64 v[226:227], s[8:9], 0, v[132:133]
	ds_read_b128 v[178:181], v145 offset:32768
	ds_read_b128 v[182:185], v145 offset:33792
	ds_read_b128 v[194:197], v145 offset:34816
	ds_read_b128 v[198:201], v145 offset:35840
	ds_read_b128 v[202:205], v145 offset:36864
	ds_read_b128 v[210:213], v145 offset:37888
	ds_read_b128 v[214:217], v145 offset:38912
	ds_read_b128 v[218:221], v145 offset:39936
	global_load_lds_dwordx4 v[226:227], off
	v_lshl_add_u64 v[226:227], s[8:9], 0, v[130:131]
	s_mov_b32 m0, s17
	s_nop 0
	global_load_lds_dwordx4 v[226:227], off
	s_waitcnt vmcnt(8)
	s_waitcnt lgkmcnt(0)
	s_barrier
	s_setprio 1
	s_waitcnt lgkmcnt(0)
	v_mfma_f32_16x16x32_bf16 v[124:127], v[146:149], v[178:181], v[124:127]
	v_mfma_f32_16x16x32_bf16 v[120:123], v[154:157], v[178:181], v[120:123]
	v_mfma_f32_16x16x32_bf16 v[108:111], v[146:149], v[194:197], v[108:111]
	v_mfma_f32_16x16x32_bf16 v[104:107], v[154:157], v[194:197], v[104:107]
	v_mfma_f32_16x16x32_bf16 v[92:95], v[146:149], v[202:205], v[92:95]
	v_mfma_f32_16x16x32_bf16 v[88:91], v[154:157], v[202:205], v[88:91]
	v_mfma_f32_16x16x32_bf16 v[76:79], v[146:149], v[214:217], v[76:79]
	v_mfma_f32_16x16x32_bf16 v[72:75], v[154:157], v[214:217], v[72:75]
	v_mfma_f32_16x16x32_bf16 v[124:127], v[150:153], v[182:185], v[124:127]
	v_mfma_f32_16x16x32_bf16 v[120:123], v[158:161], v[182:185], v[120:123]
	v_mfma_f32_16x16x32_bf16 v[108:111], v[150:153], v[198:201], v[108:111]
	v_mfma_f32_16x16x32_bf16 v[104:107], v[158:161], v[198:201], v[104:107]
	v_mfma_f32_16x16x32_bf16 v[92:95], v[150:153], v[210:213], v[92:95]
	v_mfma_f32_16x16x32_bf16 v[88:91], v[158:161], v[210:213], v[88:91]
	v_mfma_f32_16x16x32_bf16 v[76:79], v[150:153], v[218:221], v[76:79]
	v_mfma_f32_16x16x32_bf16 v[72:75], v[158:161], v[218:221], v[72:75]
	s_setprio 0
	s_setprio 1
	v_mfma_f32_16x16x32_bf16 v[116:119], v[162:165], v[178:181], v[116:119]
	v_mfma_f32_16x16x32_bf16 v[112:115], v[170:173], v[178:181], v[112:115]
	v_mfma_f32_16x16x32_bf16 v[100:103], v[162:165], v[194:197], v[100:103]
	v_mfma_f32_16x16x32_bf16 v[96:99], v[170:173], v[194:197], v[96:99]
	v_mfma_f32_16x16x32_bf16 v[84:87], v[162:165], v[202:205], v[84:87]
	v_mfma_f32_16x16x32_bf16 v[80:83], v[170:173], v[202:205], v[80:83]
	v_mfma_f32_16x16x32_bf16 v[68:71], v[162:165], v[214:217], v[68:71]
	v_mfma_f32_16x16x32_bf16 v[64:67], v[170:173], v[214:217], v[64:67]
	v_mfma_f32_16x16x32_bf16 v[116:119], v[166:169], v[182:185], v[116:119]
	v_mfma_f32_16x16x32_bf16 v[112:115], v[174:177], v[182:185], v[112:115]
	v_mfma_f32_16x16x32_bf16 v[100:103], v[166:169], v[198:201], v[100:103]
	v_mfma_f32_16x16x32_bf16 v[96:99], v[174:177], v[198:201], v[96:99]
	v_mfma_f32_16x16x32_bf16 v[84:87], v[166:169], v[210:213], v[84:87]
	v_mfma_f32_16x16x32_bf16 v[80:83], v[174:177], v[210:213], v[80:83]
	v_mfma_f32_16x16x32_bf16 v[68:71], v[166:169], v[218:221], v[68:71]
	v_mfma_f32_16x16x32_bf16 v[64:67], v[174:177], v[218:221], v[64:67]
	s_setprio 0
	s_barrier
; #define PG8_STAGE(bufoff, gbase, voff) do { _Pragma("unroll") for (int _i = 0; _i < 2; ++_i) \
;         __builtin_amdgcn_global_load_lds((const unsigned*)((const char*)(gbase) + (voff)[_i]), (PG8_LAS unsigned*)(lds + (bufoff) + ldsw + _i * 8192), 16, 0, 0); } while (0)
; #define PG8_LDA(dst, b, h) do { _Pragma("unroll") for (int m = 0; m < 4; ++m) _Pragma("unroll") for (int k = 0; k < 2; ++k) dst[m][k] = *(const PG8_LAS bf16x8*)(lds + PG8_SA(b, h) + aoff + m * 2048 + k * 1024); } while (0)
; #define PG8_MMA(ai, bj, At, Bt) do { __builtin_amdgcn_s_setprio(1); _Pragma("unroll") for (int m = 0; m < 4; ++m) _Pragma("unroll") for (int n = 0; n < 2; ++n) _Pragma("unroll") for (int k = 0; k < 2; ++k) \
;         acc[ai][bj][m][n] = __builtin_amdgcn_mfma_f32_16x16x32_bf16(Bt[n][k], At[m][k], acc[ai][bj][m][n], 0, 0, 0); __builtin_amdgcn_s_setprio(0); } while (0)
; #define PG8_WAIT_V(n) asm volatile("s_waitcnt vmcnt(" #n ")" ::: "memory")
; #define PG8_WAIT_L(n) asm volatile("s_waitcnt lgkmcnt(" #n ")" ::: "memory")
; #define PG8_BAR __builtin_amdgcn_s_barrier()
; #define PG8_SCHED __builtin_amdgcn_sched_barrier(0)
; template <class Epi, class Sched, bool ALIGN_EPI = false, bool SP2 = false>
; __device__ __forceinline__ void gemm_phase(PG8_LAS unsigned char* lds, const Gemm g, const Sched& S, const Epi& E) {
;     ...
;         for (int t = 0; t < nt; t += 2) {
;             const bool last = (t == nt - 2);
;             const char* a1 = cA + (size_t)(t + 1) * kstep;
;             const char* a2 = last ? nA : cA + (size_t)(t + 2) * kstep; const char* b2 = last ? nB : cB + (size_t)(t + 2) * kstep;
;     ...
;             PG8_LDA(At, 1, 1); PG8_STAGE(PG8_SB(1, 0), b3, voffB); PG8_STAGE(PG8_SB(1, 1), b3 + hstep, voffB); PG8_STAGE(PG8_SA(1, 0), a3, voffA);
;             PG8_WAIT_V(8); PG8_WAIT_L(0); PG8_BAR; PG8_MMA(1, 0, At, B0); PG8_MMA(1, 1, At, B1); PG8_BAR; PG8_SCHED;
	s_add_i32 s8, s22, s15
	v_lshl_add_u64 v[186:187], v[186:187], 0, s[26:27]
	s_mov_b32 m0, s8
	ds_read_b128 v[178:181], v145 offset:49152
	ds_read_b128 v[182:185], v145 offset:50176
	ds_read_b128 v[194:197], v145 offset:51200
	ds_read_b128 v[198:201], v145 offset:52224
	ds_read_b128 v[202:205], v145 offset:53248
	ds_read_b128 v[210:213], v145 offset:54272
	ds_read_b128 v[214:217], v145 offset:55296
	ds_read_b128 v[218:221], v145 offset:56320
	global_load_lds_dwordx4 v[186:187], off
	s_add_i32 m0, s8, 0x2000
	s_add_u32 s6, s6, 0x40080
	v_lshl_add_u64 v[186:187], v[190:191], 0, s[26:27]
	s_addc_u32 s7, s7, 0
	s_add_i32 s8, s23, s15
	global_load_lds_dwordx4 v[186:187], off
	v_lshl_add_u64 v[186:187], s[6:7], 0, v[188:189]
	s_mov_b32 m0, s8
	s_nop 0
	global_load_lds_dwordx4 v[186:187], off
	v_lshl_add_u64 v[186:187], s[6:7], 0, v[128:129]
	s_add_i32 m0, s8, 0x2000
	s_nop 0
	global_load_lds_dwordx4 v[186:187], off
	v_lshl_add_u64 v[186:187], v[222:223], 0, s[26:27]
	s_mov_b32 m0, s19
	s_nop 0
	global_load_lds_dwordx4 v[186:187], off
	v_lshl_add_u64 v[186:187], v[224:225], 0, s[26:27]
	s_mov_b32 m0, s20
	s_nop 0
	global_load_lds_dwordx4 v[186:187], off
	s_waitcnt vmcnt(8)
	s_waitcnt lgkmcnt(0)
	s_barrier
	s_setprio 1
	s_waitcnt lgkmcnt(0)
	v_mfma_f32_16x16x32_bf16 v[60:63], v[146:149], v[178:181], v[60:63]
	v_mfma_f32_16x16x32_bf16 v[56:59], v[154:157], v[178:181], v[56:59]
	v_mfma_f32_16x16x32_bf16 v[44:47], v[146:149], v[194:197], v[44:47]
	v_mfma_f32_16x16x32_bf16 v[40:43], v[154:157], v[194:197], v[40:43]
	v_mfma_f32_16x16x32_bf16 v[28:31], v[146:149], v[202:205], v[28:31]
	v_mfma_f32_16x16x32_bf16 v[24:27], v[154:157], v[202:205], v[24:27]
	v_mfma_f32_16x16x32_bf16 v[12:15], v[146:149], v[214:217], v[12:15]
	v_mfma_f32_16x16x32_bf16 v[8:11], v[154:157], v[214:217], v[8:11]
	v_mfma_f32_16x16x32_bf16 v[60:63], v[150:153], v[182:185], v[60:63]
	v_mfma_f32_16x16x32_bf16 v[56:59], v[158:161], v[182:185], v[56:59]
	v_mfma_f32_16x16x32_bf16 v[44:47], v[150:153], v[198:201], v[44:47]
	v_mfma_f32_16x16x32_bf16 v[40:43], v[158:161], v[198:201], v[40:43]
	v_mfma_f32_16x16x32_bf16 v[28:31], v[150:153], v[210:213], v[28:31]
	v_mfma_f32_16x16x32_bf16 v[24:27], v[158:161], v[210:213], v[24:27]
	v_mfma_f32_16x16x32_bf16 v[12:15], v[150:153], v[218:221], v[12:15]
	v_mfma_f32_16x16x32_bf16 v[8:11], v[158:161], v[218:221], v[8:11]
	s_setprio 0
	s_setprio 1
	v_mfma_f32_16x16x32_bf16 v[52:55], v[162:165], v[178:181], v[52:55]
	v_mfma_f32_16x16x32_bf16 v[48:51], v[170:173], v[178:181], v[48:51]
	s_add_i32 s21, s21, 2
	s_add_u32 s4, s4, 0x100
	s_addc_u32 s5, s5, 0
	s_cmp_gt_u32 s21, 13
	v_mfma_f32_16x16x32_bf16 v[36:39], v[162:165], v[194:197], v[36:39]
	v_mfma_f32_16x16x32_bf16 v[32:35], v[170:173], v[194:197], v[32:35]
	v_mfma_f32_16x16x32_bf16 v[20:23], v[162:165], v[202:205], v[20:23]
	v_mfma_f32_16x16x32_bf16 v[16:19], v[170:173], v[202:205], v[16:19]
	v_mfma_f32_16x16x32_bf16 v[4:7], v[162:165], v[214:217], v[4:7]
	v_mfma_f32_16x16x32_bf16 v[0:3], v[170:173], v[214:217], v[0:3]
	v_mfma_f32_16x16x32_bf16 v[52:55], v[166:169], v[182:185], v[52:55]
	v_mfma_f32_16x16x32_bf16 v[48:51], v[174:177], v[182:185], v[48:51]
	v_mfma_f32_16x16x32_bf16 v[36:39], v[166:169], v[198:201], v[36:39]
	v_mfma_f32_16x16x32_bf16 v[32:35], v[174:177], v[198:201], v[32:35]
	v_mfma_f32_16x16x32_bf16 v[20:23], v[166:169], v[210:213], v[20:23]
	v_mfma_f32_16x16x32_bf16 v[16:19], v[174:177], v[210:213], v[16:19]
	v_mfma_f32_16x16x32_bf16 v[4:7], v[166:169], v[218:221], v[4:7]
	v_mfma_f32_16x16x32_bf16 v[0:3], v[174:177], v[218:221], v[0:3]
	s_setprio 0
	s_barrier
	s_cbranch_scc0 .LBB0_529
	s_cmpk_lt_u32 s14, 0x100
	s_cbranch_scc0 .LBB0_532
	s_barrier

; #define PG8_STAGE(bufoff, gbase, voff) do { _Pragma("unroll") for (int _i = 0; _i < 2; ++_i) \
;         __builtin_amdgcn_global_load_lds((const unsigned*)((const char*)(gbase) + (voff)[_i]), (PG8_LAS unsigned*)(lds + (bufoff) + ldsw + _i * 8192), 16, 0, 0); } while (0)
; #define PG8_LDA(dst, b, h) do { _Pragma("unroll") for (int m = 0; m < 4; ++m) _Pragma("unroll") for (int k = 0; k < 2; ++k) dst[m][k] = *(const PG8_LAS bf16x8*)(lds + PG8_SA(b, h) + aoff + m * 2048 + k * 1024); } while (0)
; #define PG8_LDB(dst, b, h) do { _Pragma("unroll") for (int n = 0; n < 2; ++n) _Pragma("unroll") for (int k = 0; k < 2; ++k) dst[n][k] = *(const PG8_LAS bf16x8*)(lds + PG8_SB(b, h) + boff + n * 2048 + k * 1024); } while (0)
; template <class Epi, class Sched, bool ALIGN_EPI = false, bool SP2 = false>
; __device__ __forceinline__ void gemm_phase(PG8_LAS unsigned char* lds, const Gemm g, const Sched& S, const Epi& E) {
;     ...
;         for (int t = 0; t < nt; t += 2) {
;             const bool last = (t == nt - 2);
;             const char* a1 = cA + (size_t)(t + 1) * kstep;
;             const char* a2 = last ? nA : cA + (size_t)(t + 2) * kstep; const char* b2 = last ? nB : cB + (size_t)(t + 2) * kstep;
;             const char* a3 = a2 + kstep; const char* b3 = b2 + kstep;
;             if (last && has_next) S.a_ready(nxt);
;             if constexpr (SP2) {
;             PG8_LDB(B0, 0, 0); PG8_LDB(B1, 0, 1); PG8_SCHED; PG8_LDA(At, 0, 0); PG8_STAGE(PG8_SA(1, 1), a1 + hstep, voffA);
;             PG8_WAIT_V(8); PG8_WAIT_L(0); PG8_BAR; PG8_MMA(0, 0, At, B0); PG8_MMA(0, 1, At, B1); PG8_BAR; PG8_SCHED;
;             PG8_LDA(At, 0, 1); PG8_STAGE(PG8_SB(0, 0), b2, voffB); PG8_STAGE(PG8_SB(0, 1), b2 + hstep, voffB); PG8_STAGE(PG8_SA(0, 0), a2, voffA);
;             PG8_WAIT_V(8); PG8_WAIT_L(0); PG8_BAR; PG8_MMA(1, 0, At, B0); PG8_MMA(1, 1, At, B1); PG8_BAR; PG8_SCHED;
;             PG8_LDB(B0, 1, 0); PG8_LDB(B1, 1, 1); PG8_SCHED; PG8_LDA(At, 1, 0); PG8_STAGE(PG8_SA(0, 1), a2 + hstep, voffA);
;             PG8_WAIT_V(8); PG8_WAIT_L(0); PG8_BAR; PG8_MMA(0, 0, At, B0); PG8_MMA(0, 1, At, B1); PG8_BAR; PG8_SCHED;
;             PG8_LDA(At, 1, 1); PG8_STAGE(PG8_SB(1, 0), b3, voffB); PG8_STAGE(PG8_SB(1, 1), b3 + hstep, voffB); PG8_STAGE(PG8_SA(1, 0), a3, voffA);
;             PG8_WAIT_V(8); PG8_WAIT_L(0); PG8_BAR; PG8_MMA(1, 0, At, B0); PG8_MMA(1, 1, At, B1); PG8_BAR; PG8_SCHED;
.LBB0_706:
	s_add_u32 s6, s4, 0xebb40080
	s_addc_u32 s7, s5, -1
	s_cmp_lg_u32 s21, 12
	s_cselect_b32 s6, s6, 0
	s_cselect_b32 s7, s7, 0
	s_add_u32 s8, s2, s6
	s_addc_u32 s9, s3, s7
	s_add_i32 s22, 0, 0x10000
	s_add_u32 s6, s0, s6
	s_addc_u32 s7, s1, s7
	s_add_i32 s24, 0, 0x14000
	v_add_u32_e32 v154, s22, v140
	v_add_u32_e32 v170, s24, v140
	ds_read_b128 v[142:145], v154
	ds_read_b128 v[146:149], v154 offset:1024
	ds_read_b128 v[150:153], v154 offset:2048
	ds_read_b128 v[154:157], v154 offset:3072
	ds_read_b128 v[158:161], v170
	ds_read_b128 v[162:165], v170 offset:1024
	ds_read_b128 v[166:169], v170 offset:2048
	ds_read_b128 v[170:173], v170 offset:3072
	v_lshl_add_u64 v[186:187], v[134:135], 0, s[4:5]
	s_add_i32 m0, s14, 0xc000
	ds_read_b128 v[174:177], v141
	ds_read_b128 v[178:181], v141 offset:1024
	ds_read_b128 v[182:185], v141 offset:2048
	ds_read_b128 v[194:197], v141 offset:3072
	ds_read_b128 v[198:201], v141 offset:4096
	ds_read_b128 v[202:205], v141 offset:5120
	ds_read_b128 v[210:213], v141 offset:6144
	ds_read_b128 v[214:217], v141 offset:7168
	global_load_lds_dwordx4 v[186:187], off
	v_lshl_add_u64 v[186:187], v[136:137], 0, s[4:5]
	s_add_i32 m0, s14, 0xe000
	s_nop 0
	global_load_lds_dwordx4 v[186:187], off
	s_waitcnt vmcnt(8)
	s_waitcnt lgkmcnt(0)
	s_barrier
	s_setprio 1
	s_waitcnt lgkmcnt(0)
	v_mfma_f32_16x16x32_bf16 v[124:127], v[142:145], v[174:177], v[124:127]
	v_mfma_f32_16x16x32_bf16 v[120:123], v[150:153], v[174:177], v[120:123]
	v_mfma_f32_16x16x32_bf16 v[108:111], v[142:145], v[182:185], v[108:111]
	v_mfma_f32_16x16x32_bf16 v[104:107], v[150:153], v[182:185], v[104:107]
	v_mfma_f32_16x16x32_bf16 v[92:95], v[142:145], v[198:201], v[92:95]
	v_mfma_f32_16x16x32_bf16 v[88:91], v[150:153], v[198:201], v[88:91]
	v_mfma_f32_16x16x32_bf16 v[76:79], v[142:145], v[210:213], v[76:79]
	v_mfma_f32_16x16x32_bf16 v[72:75], v[150:153], v[210:213], v[72:75]
	v_mfma_f32_16x16x32_bf16 v[124:127], v[146:149], v[178:181], v[124:127]
	v_mfma_f32_16x16x32_bf16 v[120:123], v[154:157], v[178:181], v[120:123]
	v_mfma_f32_16x16x32_bf16 v[108:111], v[146:149], v[194:197], v[108:111]
	v_mfma_f32_16x16x32_bf16 v[104:107], v[154:157], v[194:197], v[104:107]
	v_mfma_f32_16x16x32_bf16 v[92:95], v[146:149], v[202:205], v[92:95]
	v_mfma_f32_16x16x32_bf16 v[88:91], v[154:157], v[202:205], v[88:91]
	v_mfma_f32_16x16x32_bf16 v[76:79], v[146:149], v[214:217], v[76:79]
	v_mfma_f32_16x16x32_bf16 v[72:75], v[154:157], v[214:217], v[72:75]
	s_setprio 0
	s_setprio 1
	v_mfma_f32_16x16x32_bf16 v[116:119], v[158:161], v[174:177], v[116:119]
	v_mfma_f32_16x16x32_bf16 v[112:115], v[166:169], v[174:177], v[112:115]
	v_mfma_f32_16x16x32_bf16 v[100:103], v[158:161], v[182:185], v[100:103]
	v_mfma_f32_16x16x32_bf16 v[96:99], v[166:169], v[182:185], v[96:99]
	v_mfma_f32_16x16x32_bf16 v[84:87], v[158:161], v[198:201], v[84:87]
	v_mfma_f32_16x16x32_bf16 v[80:83], v[166:169], v[198:201], v[80:83]
	v_mfma_f32_16x16x32_bf16 v[68:71], v[158:161], v[210:213], v[68:71]
	v_mfma_f32_16x16x32_bf16 v[64:67], v[166:169], v[210:213], v[64:67]
	v_mfma_f32_16x16x32_bf16 v[116:119], v[162:165], v[178:181], v[116:119]
	v_mfma_f32_16x16x32_bf16 v[112:115], v[170:173], v[178:181], v[112:115]
	v_mfma_f32_16x16x32_bf16 v[100:103], v[162:165], v[194:197], v[100:103]
	v_mfma_f32_16x16x32_bf16 v[96:99], v[170:173], v[194:197], v[96:99]
	v_mfma_f32_16x16x32_bf16 v[84:87], v[162:165], v[202:205], v[84:87]
	v_mfma_f32_16x16x32_bf16 v[80:83], v[170:173], v[202:205], v[80:83]
	v_mfma_f32_16x16x32_bf16 v[68:71], v[162:165], v[214:217], v[68:71]
	v_mfma_f32_16x16x32_bf16 v[64:67], v[170:173], v[214:217], v[64:67]
	s_setprio 0
	s_barrier
	s_add_i32 s22, s22, s13
	v_lshl_add_u64 v[186:187], s[6:7], 0, v[188:189]
	s_mov_b32 m0, s22
	ds_read_b128 v[174:177], v141 offset:16384
	ds_read_b128 v[178:181], v141 offset:17408
	ds_read_b128 v[182:185], v141 offset:18432
	ds_read_b128 v[194:197], v141 offset:19456
	ds_read_b128 v[198:201], v141 offset:20480
	ds_read_b128 v[202:205], v141 offset:21504
	ds_read_b128 v[210:213], v141 offset:22528
	ds_read_b128 v[214:217], v141 offset:23552
	global_load_lds_dwordx4 v[186:187], off
	s_add_i32 m0, s22, 0x2000
	s_add_u32 s22, s6, 0x40000
	v_lshl_add_u64 v[190:191], s[6:7], 0, v[132:133]
	s_addc_u32 s23, s7, 0
	s_add_i32 s24, s24, s13
	global_load_lds_dwordx4 v[190:191], off
	v_lshl_add_u64 v[218:219], s[22:23], 0, v[188:189]
	s_mov_b32 m0, s24
	v_lshl_add_u64 v[220:221], s[8:9], 0, v[130:131]
	global_load_lds_dwordx4 v[218:219], off
	v_lshl_add_u64 v[218:219], s[22:23], 0, v[132:133]
	s_add_i32 m0, s24, 0x2000
	s_nop 0
	global_load_lds_dwordx4 v[218:219], off
	v_lshl_add_u64 v[218:219], s[8:9], 0, v[128:129]
	s_mov_b32 m0, s14
	s_nop 0
	global_load_lds_dwordx4 v[218:219], off
	s_mov_b32 m0, s15
	s_nop 0
	global_load_lds_dwordx4 v[220:221], off
	s_waitcnt vmcnt(8)
	s_waitcnt lgkmcnt(0)
	s_barrier
; #define PG8_STAGE(bufoff, gbase, voff) do { _Pragma("unroll") for (int _i = 0; _i < 2; ++_i) \
;         __builtin_amdgcn_global_load_lds((const unsigned*)((const char*)(gbase) + (voff)[_i]), (PG8_LAS unsigned*)(lds + (bufoff) + ldsw + _i * 8192), 16, 0, 0); } while (0)
; #define PG8_LDA(dst, b, h) do { _Pragma("unroll") for (int m = 0; m < 4; ++m) _Pragma("unroll") for (int k = 0; k < 2; ++k) dst[m][k] = *(const PG8_LAS bf16x8*)(lds + PG8_SA(b, h) + aoff + m * 2048 + k * 1024); } while (0)
; #define PG8_LDB(dst, b, h) do { _Pragma("unroll") for (int n = 0; n < 2; ++n) _Pragma("unroll") for (int k = 0; k < 2; ++k) dst[n][k] = *(const PG8_LAS bf16x8*)(lds + PG8_SB(b, h) + boff + n * 2048 + k * 1024); } while (0)
; #define PG8_MMA(ai, bj, At, Bt) do { __builtin_amdgcn_s_setprio(1); _Pragma("unroll") for (int m = 0; m < 4; ++m) _Pragma("unroll") for (int n = 0; n < 2; ++n) _Pragma("unroll") for (int k = 0; k < 2; ++k) \
;         acc[ai][bj][m][n] = __builtin_amdgcn_mfma_f32_16x16x32_bf16(Bt[n][k], At[m][k], acc[ai][bj][m][n], 0, 0, 0); __builtin_amdgcn_s_setprio(0); } while (0)
; #define PG8_WAIT_V(n) asm volatile("s_waitcnt vmcnt(" #n ")" ::: "memory")
; #define PG8_WAIT_L(n) asm volatile("s_waitcnt lgkmcnt(" #n ")" ::: "memory")
; #define PG8_BAR __builtin_amdgcn_s_barrier()
; #define PG8_SCHED __builtin_amdgcn_sched_barrier(0)
; template <class Epi, class Sched, bool ALIGN_EPI = false, bool SP2 = false>
; __device__ __forceinline__ void gemm_phase(PG8_LAS unsigned char* lds, const Gemm g, const Sched& S, const Epi& E) {
;     ...
;             PG8_WAIT_V(8); PG8_WAIT_L(0); PG8_BAR; PG8_MMA(0, 0, At, B0); PG8_MMA(0, 1, At, B1); PG8_BAR; PG8_SCHED;
;             PG8_LDA(At, 0, 1); PG8_STAGE(PG8_SB(0, 0), b2, voffB); PG8_STAGE(PG8_SB(0, 1), b2 + hstep, voffB); PG8_STAGE(PG8_SA(0, 0), a2, voffA);
;             PG8_WAIT_V(8); PG8_WAIT_L(0); PG8_BAR; PG8_MMA(1, 0, At, B0); PG8_MMA(1, 1, At, B1); PG8_BAR; PG8_SCHED;
;             PG8_LDB(B0, 1, 0); PG8_LDB(B1, 1, 1); PG8_SCHED; PG8_LDA(At, 1, 0); PG8_STAGE(PG8_SA(0, 1), a2 + hstep, voffA);
;             PG8_WAIT_V(8); PG8_WAIT_L(0); PG8_BAR; PG8_MMA(0, 0, At, B0); PG8_MMA(0, 1, At, B1); PG8_BAR; PG8_SCHED;
;             PG8_LDA(At, 1, 1); PG8_STAGE(PG8_SB(1, 0), b3, voffB); PG8_STAGE(PG8_SB(1, 1), b3 + hstep, voffB); PG8_STAGE(PG8_SA(1, 0), a3, voffA);
	s_setprio 1
	s_waitcnt lgkmcnt(0)
	v_mfma_f32_16x16x32_bf16 v[60:63], v[142:145], v[174:177], v[60:63]
	v_mfma_f32_16x16x32_bf16 v[56:59], v[150:153], v[174:177], v[56:59]
	v_mfma_f32_16x16x32_bf16 v[44:47], v[142:145], v[182:185], v[44:47]
	v_mfma_f32_16x16x32_bf16 v[40:43], v[150:153], v[182:185], v[40:43]
	v_mfma_f32_16x16x32_bf16 v[28:31], v[142:145], v[198:201], v[28:31]
	v_mfma_f32_16x16x32_bf16 v[24:27], v[150:153], v[198:201], v[24:27]
	v_mfma_f32_16x16x32_bf16 v[12:15], v[142:145], v[210:213], v[12:15]
	v_mfma_f32_16x16x32_bf16 v[8:11], v[150:153], v[210:213], v[8:11]
	v_mfma_f32_16x16x32_bf16 v[60:63], v[146:149], v[178:181], v[60:63]
	v_mfma_f32_16x16x32_bf16 v[56:59], v[154:157], v[178:181], v[56:59]
	v_mfma_f32_16x16x32_bf16 v[44:47], v[146:149], v[194:197], v[44:47]
	v_mfma_f32_16x16x32_bf16 v[40:43], v[154:157], v[194:197], v[40:43]
	v_mfma_f32_16x16x32_bf16 v[28:31], v[146:149], v[202:205], v[28:31]
	v_mfma_f32_16x16x32_bf16 v[24:27], v[154:157], v[202:205], v[24:27]
	v_mfma_f32_16x16x32_bf16 v[12:15], v[146:149], v[214:217], v[12:15]
	v_mfma_f32_16x16x32_bf16 v[8:11], v[154:157], v[214:217], v[8:11]
	s_setprio 0
	s_setprio 1
	v_mfma_f32_16x16x32_bf16 v[52:55], v[158:161], v[174:177], v[52:55]
	v_mfma_f32_16x16x32_bf16 v[48:51], v[166:169], v[174:177], v[48:51]
	v_mfma_f32_16x16x32_bf16 v[36:39], v[158:161], v[182:185], v[36:39]
	v_mfma_f32_16x16x32_bf16 v[32:35], v[166:169], v[182:185], v[32:35]
	v_mfma_f32_16x16x32_bf16 v[20:23], v[158:161], v[198:201], v[20:23]
	v_mfma_f32_16x16x32_bf16 v[16:19], v[166:169], v[198:201], v[16:19]
	v_mfma_f32_16x16x32_bf16 v[4:7], v[158:161], v[210:213], v[4:7]
	v_mfma_f32_16x16x32_bf16 v[0:3], v[166:169], v[210:213], v[0:3]
	v_mfma_f32_16x16x32_bf16 v[52:55], v[162:165], v[178:181], v[52:55]
	v_mfma_f32_16x16x32_bf16 v[48:51], v[170:173], v[178:181], v[48:51]
	v_mfma_f32_16x16x32_bf16 v[36:39], v[162:165], v[194:197], v[36:39]
	v_mfma_f32_16x16x32_bf16 v[32:35], v[170:173], v[194:197], v[32:35]
	v_mfma_f32_16x16x32_bf16 v[20:23], v[162:165], v[202:205], v[20:23]
	v_mfma_f32_16x16x32_bf16 v[16:19], v[170:173], v[202:205], v[16:19]
	v_mfma_f32_16x16x32_bf16 v[4:7], v[162:165], v[214:217], v[4:7]
	v_mfma_f32_16x16x32_bf16 v[0:3], v[170:173], v[214:217], v[0:3]
	s_setprio 0
	s_barrier
	s_add_i32 s22, 0, 0x18000
	s_add_i32 s23, 0, 0x1c000
	v_add_u32_e32 v154, s22, v140
	v_add_u32_e32 v170, s23, v140
	ds_read_b128 v[142:145], v154
	ds_read_b128 v[146:149], v154 offset:1024
	ds_read_b128 v[150:153], v154 offset:2048
	ds_read_b128 v[154:157], v154 offset:3072
	ds_read_b128 v[158:161], v170
	ds_read_b128 v[162:165], v170 offset:1024
	ds_read_b128 v[166:169], v170 offset:2048
	ds_read_b128 v[170:173], v170 offset:3072
	s_add_u32 s8, s8, 0x40000
	s_addc_u32 s9, s9, 0
	s_mov_b32 m0, s16
	v_lshl_add_u64 v[222:223], s[8:9], 0, v[128:129]
	ds_read_b128 v[174:177], v141 offset:32768
	ds_read_b128 v[178:181], v141 offset:33792
	ds_read_b128 v[182:185], v141 offset:34816
	ds_read_b128 v[194:197], v141 offset:35840
	ds_read_b128 v[198:201], v141 offset:36864
	ds_read_b128 v[202:205], v141 offset:37888
	ds_read_b128 v[210:213], v141 offset:38912
	ds_read_b128 v[214:217], v141 offset:39936
	global_load_lds_dwordx4 v[222:223], off
	v_lshl_add_u64 v[222:223], s[8:9], 0, v[130:131]
	s_mov_b32 m0, s17
	s_nop 0
	global_load_lds_dwordx4 v[222:223], off
	s_waitcnt vmcnt(8)
	s_waitcnt lgkmcnt(0)
	s_barrier
	s_setprio 1
	s_waitcnt lgkmcnt(0)
	v_mfma_f32_16x16x32_bf16 v[124:127], v[142:145], v[174:177], v[124:127]
	v_mfma_f32_16x16x32_bf16 v[120:123], v[150:153], v[174:177], v[120:123]
	v_mfma_f32_16x16x32_bf16 v[108:111], v[142:145], v[182:185], v[108:111]
	v_mfma_f32_16x16x32_bf16 v[104:107], v[150:153], v[182:185], v[104:107]
	v_mfma_f32_16x16x32_bf16 v[92:95], v[142:145], v[198:201], v[92:95]
	v_mfma_f32_16x16x32_bf16 v[88:91], v[150:153], v[198:201], v[88:91]
	v_mfma_f32_16x16x32_bf16 v[76:79], v[142:145], v[210:213], v[76:79]
	v_mfma_f32_16x16x32_bf16 v[72:75], v[150:153], v[210:213], v[72:75]
	v_mfma_f32_16x16x32_bf16 v[124:127], v[146:149], v[178:181], v[124:127]
	v_mfma_f32_16x16x32_bf16 v[120:123], v[154:157], v[178:181], v[120:123]
	v_mfma_f32_16x16x32_bf16 v[108:111], v[146:149], v[194:197], v[108:111]
	v_mfma_f32_16x16x32_bf16 v[104:107], v[154:157], v[194:197], v[104:107]
	v_mfma_f32_16x16x32_bf16 v[92:95], v[146:149], v[202:205], v[92:95]
	v_mfma_f32_16x16x32_bf16 v[88:91], v[154:157], v[202:205], v[88:91]
	v_mfma_f32_16x16x32_bf16 v[76:79], v[146:149], v[214:217], v[76:79]
	v_mfma_f32_16x16x32_bf16 v[72:75], v[154:157], v[214:217], v[72:75]
	s_setprio 0
	s_setprio 1
	v_mfma_f32_16x16x32_bf16 v[116:119], v[158:161], v[174:177], v[116:119]
	v_mfma_f32_16x16x32_bf16 v[112:115], v[166:169], v[174:177], v[112:115]
	v_mfma_f32_16x16x32_bf16 v[100:103], v[158:161], v[182:185], v[100:103]
	v_mfma_f32_16x16x32_bf16 v[96:99], v[166:169], v[182:185], v[96:99]
	v_mfma_f32_16x16x32_bf16 v[84:87], v[158:161], v[198:201], v[84:87]
	v_mfma_f32_16x16x32_bf16 v[80:83], v[166:169], v[198:201], v[80:83]
	v_mfma_f32_16x16x32_bf16 v[68:71], v[158:161], v[210:213], v[68:71]
	v_mfma_f32_16x16x32_bf16 v[64:67], v[166:169], v[210:213], v[64:67]
	v_mfma_f32_16x16x32_bf16 v[116:119], v[162:165], v[178:181], v[116:119]
	v_mfma_f32_16x16x32_bf16 v[112:115], v[170:173], v[178:181], v[112:115]
	v_mfma_f32_16x16x32_bf16 v[100:103], v[162:165], v[194:197], v[100:103]
	v_mfma_f32_16x16x32_bf16 v[96:99], v[170:173], v[194:197], v[96:99]
	v_mfma_f32_16x16x32_bf16 v[84:87], v[162:165], v[202:205], v[84:87]
	v_mfma_f32_16x16x32_bf16 v[80:83], v[170:173], v[202:205], v[80:83]
	v_mfma_f32_16x16x32_bf16 v[68:71], v[162:165], v[214:217], v[68:71]
	v_mfma_f32_16x16x32_bf16 v[64:67], v[170:173], v[214:217], v[64:67]
	s_setprio 0
	s_barrier
; #define PG8_STAGE(bufoff, gbase, voff) do { _Pragma("unroll") for (int _i = 0; _i < 2; ++_i) \
;         __builtin_amdgcn_global_load_lds((const unsigned*)((const char*)(gbase) + (voff)[_i]), (PG8_LAS unsigned*)(lds + (bufoff) + ldsw + _i * 8192), 16, 0, 0); } while (0)
; #define PG8_LDA(dst, b, h) do { _Pragma("unroll") for (int m = 0; m < 4; ++m) _Pragma("unroll") for (int k = 0; k < 2; ++k) dst[m][k] = *(const PG8_LAS bf16x8*)(lds + PG8_SA(b, h) + aoff + m * 2048 + k * 1024); } while (0)
; #define PG8_MMA(ai, bj, At, Bt) do { __builtin_amdgcn_s_setprio(1); _Pragma("unroll") for (int m = 0; m < 4; ++m) _Pragma("unroll") for (int n = 0; n < 2; ++n) _Pragma("unroll") for (int k = 0; k < 2; ++k) \
;         acc[ai][bj][m][n] = __builtin_amdgcn_mfma_f32_16x16x32_bf16(Bt[n][k], At[m][k], acc[ai][bj][m][n], 0, 0, 0); __builtin_amdgcn_s_setprio(0); } while (0)
; #define PG8_WAIT_V(n) asm volatile("s_waitcnt vmcnt(" #n ")" ::: "memory")
; #define PG8_WAIT_L(n) asm volatile("s_waitcnt lgkmcnt(" #n ")" ::: "memory")
; #define PG8_BAR __builtin_amdgcn_s_barrier()
; #define PG8_SCHED __builtin_amdgcn_sched_barrier(0)
;     __device__ __forceinline__ void operator()(const f32x4 (&acc)[2][2][4][2], const Unit& u, int wr, int wc, int fr, int fq) const {
;     ...
;             for (int m = 0; m < 4; ++m) { const size_t off = (size_t)(row0 + ai * HALF + m * 16) * 1024 + col0;
; #pragma unroll
;                 for (int bj = 0; bj < 2; ++bj) { const u32x4 gw = *(const u32x4*)(Gt + off + bj * HALF);
; template <class Epi, class Sched, bool ALIGN_EPI = false, bool SP2 = false>
; __device__ __forceinline__ void gemm_phase(PG8_LAS unsigned char* lds, const Gemm g, const Sched& S, const Epi& E) {
;     ...
;             PG8_LDA(At, 1, 1); PG8_STAGE(PG8_SB(1, 0), b3, voffB); PG8_STAGE(PG8_SB(1, 1), b3 + hstep, voffB); PG8_STAGE(PG8_SA(1, 0), a3, voffA);
;             PG8_WAIT_V(8); PG8_WAIT_L(0); PG8_BAR; PG8_MMA(1, 0, At, B0); PG8_MMA(1, 1, At, B1); PG8_BAR; PG8_SCHED;
	s_add_i32 s8, s22, s13
	v_lshl_add_u64 v[186:187], v[186:187], 0, s[26:27]
	s_mov_b32 m0, s8
	ds_read_b128 v[174:177], v141 offset:49152
	ds_read_b128 v[178:181], v141 offset:50176
	ds_read_b128 v[182:185], v141 offset:51200
	ds_read_b128 v[194:197], v141 offset:52224
	ds_read_b128 v[198:201], v141 offset:53248
	ds_read_b128 v[202:205], v141 offset:54272
	ds_read_b128 v[210:213], v141 offset:55296
	ds_read_b128 v[214:217], v141 offset:56320
	global_load_lds_dwordx4 v[186:187], off
	s_add_i32 m0, s8, 0x2000
	s_add_u32 s6, s6, 0x40080
	v_lshl_add_u64 v[186:187], v[190:191], 0, s[26:27]
	s_addc_u32 s7, s7, 0
	s_add_i32 s8, s23, s13
	global_load_lds_dwordx4 v[186:187], off
	v_lshl_add_u64 v[186:187], s[6:7], 0, v[188:189]
	s_mov_b32 m0, s8
	s_nop 0
	global_load_lds_dwordx4 v[186:187], off
	v_lshl_add_u64 v[186:187], s[6:7], 0, v[132:133]
	s_add_i32 m0, s8, 0x2000
	s_nop 0
	global_load_lds_dwordx4 v[186:187], off
	v_lshl_add_u64 v[186:187], v[218:219], 0, s[26:27]
	s_mov_b32 m0, s19
	s_nop 0
	global_load_lds_dwordx4 v[186:187], off
	v_lshl_add_u64 v[186:187], v[220:221], 0, s[26:27]
	s_mov_b32 m0, s20
	s_nop 0
	global_load_lds_dwordx4 v[186:187], off
	s_waitcnt vmcnt(8)
	s_waitcnt lgkmcnt(0)
	s_barrier
	s_setprio 1
	s_waitcnt lgkmcnt(0)
	v_mfma_f32_16x16x32_bf16 v[60:63], v[142:145], v[174:177], v[60:63]
	v_mfma_f32_16x16x32_bf16 v[56:59], v[150:153], v[174:177], v[56:59]
	v_mfma_f32_16x16x32_bf16 v[44:47], v[142:145], v[182:185], v[44:47]
	v_mfma_f32_16x16x32_bf16 v[40:43], v[150:153], v[182:185], v[40:43]
	v_mfma_f32_16x16x32_bf16 v[28:31], v[142:145], v[198:201], v[28:31]
	v_mfma_f32_16x16x32_bf16 v[24:27], v[150:153], v[198:201], v[24:27]
	v_mfma_f32_16x16x32_bf16 v[12:15], v[142:145], v[210:213], v[12:15]
	v_mfma_f32_16x16x32_bf16 v[8:11], v[150:153], v[210:213], v[8:11]
	v_mfma_f32_16x16x32_bf16 v[60:63], v[146:149], v[178:181], v[60:63]
	v_mfma_f32_16x16x32_bf16 v[56:59], v[154:157], v[178:181], v[56:59]
	v_mfma_f32_16x16x32_bf16 v[44:47], v[146:149], v[194:197], v[44:47]
	v_mfma_f32_16x16x32_bf16 v[40:43], v[154:157], v[194:197], v[40:43]
	v_mfma_f32_16x16x32_bf16 v[28:31], v[146:149], v[202:205], v[28:31]
	v_mfma_f32_16x16x32_bf16 v[24:27], v[154:157], v[202:205], v[24:27]
	v_mfma_f32_16x16x32_bf16 v[12:15], v[146:149], v[214:217], v[12:15]
	v_mfma_f32_16x16x32_bf16 v[8:11], v[154:157], v[214:217], v[8:11]
	s_setprio 0
	s_setprio 1
	v_mfma_f32_16x16x32_bf16 v[52:55], v[158:161], v[174:177], v[52:55]
	v_mfma_f32_16x16x32_bf16 v[48:51], v[166:169], v[174:177], v[48:51]
	s_add_i32 s21, s21, 2
	s_add_u32 s4, s4, 0x100
	s_addc_u32 s5, s5, 0
	s_cmp_gt_u32 s21, 13
	v_mfma_f32_16x16x32_bf16 v[36:39], v[158:161], v[182:185], v[36:39]
	v_mfma_f32_16x16x32_bf16 v[32:35], v[166:169], v[182:185], v[32:35]
	v_mfma_f32_16x16x32_bf16 v[20:23], v[158:161], v[198:201], v[20:23]
	v_mfma_f32_16x16x32_bf16 v[16:19], v[166:169], v[198:201], v[16:19]
	v_mfma_f32_16x16x32_bf16 v[4:7], v[158:161], v[210:213], v[4:7]
	v_mfma_f32_16x16x32_bf16 v[0:3], v[166:169], v[210:213], v[0:3]
	v_mfma_f32_16x16x32_bf16 v[52:55], v[162:165], v[178:181], v[52:55]
	v_mfma_f32_16x16x32_bf16 v[48:51], v[170:173], v[178:181], v[48:51]
	v_mfma_f32_16x16x32_bf16 v[36:39], v[162:165], v[194:197], v[36:39]
	v_mfma_f32_16x16x32_bf16 v[32:35], v[170:173], v[194:197], v[32:35]
	v_mfma_f32_16x16x32_bf16 v[20:23], v[162:165], v[202:205], v[20:23]
	v_mfma_f32_16x16x32_bf16 v[16:19], v[170:173], v[202:205], v[16:19]
	v_mfma_f32_16x16x32_bf16 v[4:7], v[162:165], v[214:217], v[4:7]
	v_mfma_f32_16x16x32_bf16 v[0:3], v[170:173], v[214:217], v[0:3]
	s_setprio 0
	s_barrier
	s_cbranch_scc0 .LBB0_706
	v_lshl_add_u32 v128, s11, 8, v138
	v_or_b32_e32 v129, s18, v139
	v_lshlrev_b32_e32 v128, 11, v128
	v_lshl_add_u32 v128, v129, 1, v128
	s_lshl_b32 s4, s12, 9
	v_add_u32_e32 v128, s4, v128
	v_readlane_b32 s2, v254, 42
	v_readlane_b32 s3, v254, 43
	v_readlane_b32 s0, v254, 21
	v_readlane_b32 s1, v254, 22
	s_mov_b64 s[4:5], s[2:3]
	global_load_dwordx4 v[142:145], v128, s[4:5]
	global_load_dwordx4 v[146:149], v128, s[4:5] offset:256
	s_add_u32 s4, s2, 0x8000
	s_addc_u32 s5, s3, 0
	global_load_dwordx4 v[150:153], v128, s[4:5]
	global_load_dwordx4 v[154:157], v128, s[4:5] offset:256
	s_add_u32 s4, s2, 0x10000
	s_addc_u32 s5, s3, 0
	global_load_dwordx4 v[158:161], v128, s[4:5]
	global_load_dwordx4 v[162:165], v128, s[4:5] offset:256
	s_add_u32 s4, s2, 0x18000
	s_addc_u32 s5, s3, 0
	global_load_dwordx4 v[166:169], v128, s[4:5]
	global_load_dwordx4 v[170:173], v128, s[4:5] offset:256
	s_add_u32 s4, s2, 0x40000
	s_addc_u32 s5, s3, 0
	global_load_dwordx4 v[174:177], v128, s[4:5]
	global_load_dwordx4 v[178:181], v128, s[4:5] offset:256
	s_add_u32 s4, s2, 0x48000
	s_addc_u32 s5, s3, 0
	global_load_dwordx4 v[182:185], v128, s[4:5]
	global_load_dwordx4 v[194:197], v128, s[4:5] offset:256
	s_add_u32 s4, s2, 0x50000
	s_addc_u32 s5, s3, 0
	global_load_dwordx4 v[198:201], v128, s[4:5]
	global_load_dwordx4 v[202:205], v128, s[4:5] offset:256
	s_add_u32 s4, s2, 0x58000
	s_addc_u32 s5, s3, 0
	global_load_dwordx4 v[210:213], v128, s[4:5]
	global_load_dwordx4 v[214:217], v128, s[4:5] offset:256
	s_cmpk_lt_u32 s10, 0x100
	s_cbranch_scc0 .LBB0_709
	s_barrier

; #define PG8_STAGE(bufoff, gbase, voff) do { _Pragma("unroll") for (int _i = 0; _i < 2; ++_i) \
;         __builtin_amdgcn_global_load_lds((const unsigned*)((const char*)(gbase) + (voff)[_i]), (PG8_LAS unsigned*)(lds + (bufoff) + ldsw + _i * 8192), 16, 0, 0); } while (0)
; #define PG8_LDA(dst, b, h) do { _Pragma("unroll") for (int m = 0; m < 4; ++m) _Pragma("unroll") for (int k = 0; k < 2; ++k) dst[m][k] = *(const PG8_LAS bf16x8*)(lds + PG8_SA(b, h) + aoff + m * 2048 + k * 1024); } while (0)
; #define PG8_LDB(dst, b, h) do { _Pragma("unroll") for (int n = 0; n < 2; ++n) _Pragma("unroll") for (int k = 0; k < 2; ++k) dst[n][k] = *(const PG8_LAS bf16x8*)(lds + PG8_SB(b, h) + boff + n * 2048 + k * 1024); } while (0)
; #define PG8_MMA(ai, bj, At, Bt) do { __builtin_amdgcn_s_setprio(1); _Pragma("unroll") for (int m = 0; m < 4; ++m) _Pragma("unroll") for (int n = 0; n < 2; ++n) _Pragma("unroll") for (int k = 0; k < 2; ++k) \
;         acc[ai][bj][m][n] = __builtin_amdgcn_mfma_f32_16x16x32_bf16(Bt[n][k], At[m][k], acc[ai][bj][m][n], 0, 0, 0); __builtin_amdgcn_s_setprio(0); } while (0)
; #define PG8_WAIT_V(n) asm volatile("s_waitcnt vmcnt(" #n ")" ::: "memory")
; #define PG8_BAR __builtin_amdgcn_s_barrier()
; template <class Epi, class Sched, bool ALIGN_EPI = false, bool SP2 = false>
; __device__ __forceinline__ void gemm_phase(PG8_LAS unsigned char* lds, const Gemm g, const Sched& S, const Epi& E) {
;     ...
;         for (int t = 0; t < nt; t += 2) {
;             const bool last = (t == nt - 2);
;             const char* a1 = cA + (size_t)(t + 1) * kstep;
;             const char* a2 = last ? nA : cA + (size_t)(t + 2) * kstep; const char* b2 = last ? nB : cB + (size_t)(t + 2) * kstep;
;             const char* a3 = a2 + kstep; const char* b3 = b2 + kstep;
;             if (last && has_next) S.a_ready(nxt);
;             if constexpr (SP2) {
;             PG8_LDB(B0, 0, 0); PG8_LDB(B1, 0, 1); PG8_SCHED; PG8_LDA(At, 0, 0); PG8_STAGE(PG8_SA(1, 1), a1 + hstep, voffA);
;             PG8_WAIT_V(8); PG8_WAIT_L(0); PG8_BAR; PG8_MMA(0, 0, At, B0); PG8_MMA(0, 1, At, B1); PG8_BAR; PG8_SCHED;
;             PG8_LDA(At, 0, 1); PG8_STAGE(PG8_SB(0, 0), b2, voffB); PG8_STAGE(PG8_SB(0, 1), b2 + hstep, voffB); PG8_STAGE(PG8_SA(0, 0), a2, voffA);
;             PG8_WAIT_V(8); PG8_WAIT_L(0); PG8_BAR; PG8_MMA(1, 0, At, B0); PG8_MMA(1, 1, At, B1); PG8_BAR; PG8_SCHED;
.LBB0_725:
	s_add_u32 s20, s18, 0xfffc0080
	s_addc_u32 s21, s19, -1
	s_add_i32 s40, 0, 0x10000
	s_cmp_eq_u32 s39, 12
	s_cselect_b32 s23, s9, s21
	s_cselect_b32 s22, s15, s20
	v_add_u32_e32 v144, s40, v147
	s_cselect_b32 s21, s7, s38
	s_cselect_b32 s20, s17, s33
	s_add_i32 s42, 0, 0x14000
	ds_read_b128 v[140:143], v144
	ds_read_b128 v[150:153], v144 offset:1024
	ds_read_b128 v[154:157], v144 offset:2048
	ds_read_b128 v[158:161], v144 offset:3072
	v_add_u32_e32 v144, s42, v147
	ds_read_b128 v[162:165], v144
	ds_read_b128 v[166:169], v144 offset:1024
	ds_read_b128 v[170:173], v144 offset:2048
	ds_read_b128 v[174:177], v144 offset:3072
	v_lshl_add_u64 v[144:145], s[18:19], 0, v[136:137]
	s_add_i32 m0, s28, 0xc000
	ds_read_b128 v[178:181], v148
	ds_read_b128 v[182:185], v148 offset:1024
	ds_read_b128 v[194:197], v148 offset:2048
	ds_read_b128 v[198:201], v148 offset:3072
	ds_read_b128 v[202:205], v148 offset:4096
	ds_read_b128 v[210:213], v148 offset:5120
	ds_read_b128 v[214:217], v148 offset:6144
	ds_read_b128 v[218:221], v148 offset:7168
	global_load_lds_dwordx4 v[144:145], off
	v_lshl_add_u64 v[144:145], s[18:19], 0, v[138:139]
	s_add_i32 m0, s28, 0xe000
	s_nop 0
	global_load_lds_dwordx4 v[144:145], off
	s_waitcnt vmcnt(8)
	s_waitcnt lgkmcnt(0)
	s_barrier
	s_setprio 1
	s_waitcnt lgkmcnt(0)
	v_mfma_f32_16x16x32_bf16 v[124:127], v[140:143], v[178:181], v[124:127]
	v_mfma_f32_16x16x32_bf16 v[120:123], v[154:157], v[178:181], v[120:123]
	v_mfma_f32_16x16x32_bf16 v[108:111], v[140:143], v[194:197], v[108:111]
	v_mfma_f32_16x16x32_bf16 v[104:107], v[154:157], v[194:197], v[104:107]
	v_mfma_f32_16x16x32_bf16 v[92:95], v[140:143], v[202:205], v[92:95]
	v_mfma_f32_16x16x32_bf16 v[88:91], v[154:157], v[202:205], v[88:91]
	v_mfma_f32_16x16x32_bf16 v[76:79], v[140:143], v[214:217], v[76:79]
	v_mfma_f32_16x16x32_bf16 v[72:75], v[154:157], v[214:217], v[72:75]
	v_mfma_f32_16x16x32_bf16 v[124:127], v[150:153], v[182:185], v[124:127]
	v_mfma_f32_16x16x32_bf16 v[120:123], v[158:161], v[182:185], v[120:123]
	v_mfma_f32_16x16x32_bf16 v[108:111], v[150:153], v[198:201], v[108:111]
	v_mfma_f32_16x16x32_bf16 v[104:107], v[158:161], v[198:201], v[104:107]
	v_mfma_f32_16x16x32_bf16 v[92:95], v[150:153], v[210:213], v[92:95]
	v_mfma_f32_16x16x32_bf16 v[88:91], v[158:161], v[210:213], v[88:91]
	v_mfma_f32_16x16x32_bf16 v[76:79], v[150:153], v[218:221], v[76:79]
	v_mfma_f32_16x16x32_bf16 v[72:75], v[158:161], v[218:221], v[72:75]
	s_setprio 0
	s_setprio 1
	v_mfma_f32_16x16x32_bf16 v[116:119], v[162:165], v[178:181], v[116:119]
	v_mfma_f32_16x16x32_bf16 v[112:115], v[170:173], v[178:181], v[112:115]
	v_mfma_f32_16x16x32_bf16 v[100:103], v[162:165], v[194:197], v[100:103]
	v_mfma_f32_16x16x32_bf16 v[96:99], v[170:173], v[194:197], v[96:99]
	v_mfma_f32_16x16x32_bf16 v[84:87], v[162:165], v[202:205], v[84:87]
	v_mfma_f32_16x16x32_bf16 v[80:83], v[170:173], v[202:205], v[80:83]
	v_mfma_f32_16x16x32_bf16 v[68:71], v[162:165], v[214:217], v[68:71]
	v_mfma_f32_16x16x32_bf16 v[64:67], v[170:173], v[214:217], v[64:67]
	v_mfma_f32_16x16x32_bf16 v[116:119], v[166:169], v[182:185], v[116:119]
	v_mfma_f32_16x16x32_bf16 v[112:115], v[174:177], v[182:185], v[112:115]
	v_mfma_f32_16x16x32_bf16 v[100:103], v[166:169], v[198:201], v[100:103]
	v_mfma_f32_16x16x32_bf16 v[96:99], v[174:177], v[198:201], v[96:99]
	v_mfma_f32_16x16x32_bf16 v[84:87], v[166:169], v[210:213], v[84:87]
	v_mfma_f32_16x16x32_bf16 v[80:83], v[174:177], v[210:213], v[80:83]
	v_mfma_f32_16x16x32_bf16 v[68:71], v[166:169], v[218:221], v[68:71]
	v_mfma_f32_16x16x32_bf16 v[64:67], v[174:177], v[218:221], v[64:67]
	s_setprio 0
	s_barrier
	s_add_i32 s40, s40, s27
	v_lshl_add_u64 v[144:145], s[20:21], 0, v[188:189]
	s_mov_b32 m0, s40
	ds_read_b128 v[178:181], v148 offset:16384
	ds_read_b128 v[182:185], v148 offset:17408
	ds_read_b128 v[194:197], v148 offset:18432
	ds_read_b128 v[198:201], v148 offset:19456
	ds_read_b128 v[202:205], v148 offset:20480
	ds_read_b128 v[210:213], v148 offset:21504
	ds_read_b128 v[214:217], v148 offset:22528
	ds_read_b128 v[218:221], v148 offset:23552
	global_load_lds_dwordx4 v[144:145], off
	s_add_i32 m0, s40, 0x2000
	s_add_u32 s40, s20, 0x40000
	v_lshl_add_u64 v[186:187], s[20:21], 0, v[132:133]
	s_addc_u32 s41, s21, 0
	s_add_i32 s42, s42, s27
	global_load_lds_dwordx4 v[186:187], off
	v_lshl_add_u64 v[190:191], s[40:41], 0, v[188:189]
	s_mov_b32 m0, s42
	v_lshl_add_u64 v[222:223], s[22:23], 0, v[130:131]
	global_load_lds_dwordx4 v[190:191], off
	v_lshl_add_u64 v[190:191], s[40:41], 0, v[132:133]
	s_add_i32 m0, s42, 0x2000
	s_nop 0
	global_load_lds_dwordx4 v[190:191], off
	v_lshl_add_u64 v[190:191], s[22:23], 0, v[128:129]
	s_mov_b32 m0, s28
	s_nop 0
	global_load_lds_dwordx4 v[190:191], off
	s_mov_b32 m0, s29
	s_nop 0
	global_load_lds_dwordx4 v[222:223], off
	s_waitcnt vmcnt(8)
	s_waitcnt lgkmcnt(0)
	s_barrier
; #define PG8_STAGE(bufoff, gbase, voff) do { _Pragma("unroll") for (int _i = 0; _i < 2; ++_i) \
;         __builtin_amdgcn_global_load_lds((const unsigned*)((const char*)(gbase) + (voff)[_i]), (PG8_LAS unsigned*)(lds + (bufoff) + ldsw + _i * 8192), 16, 0, 0); } while (0)
; #define PG8_LDA(dst, b, h) do { _Pragma("unroll") for (int m = 0; m < 4; ++m) _Pragma("unroll") for (int k = 0; k < 2; ++k) dst[m][k] = *(const PG8_LAS bf16x8*)(lds + PG8_SA(b, h) + aoff + m * 2048 + k * 1024); } while (0)
; #define PG8_LDB(dst, b, h) do { _Pragma("unroll") for (int n = 0; n < 2; ++n) _Pragma("unroll") for (int k = 0; k < 2; ++k) dst[n][k] = *(const PG8_LAS bf16x8*)(lds + PG8_SB(b, h) + boff + n * 2048 + k * 1024); } while (0)
; #define PG8_MMA(ai, bj, At, Bt) do { __builtin_amdgcn_s_setprio(1); _Pragma("unroll") for (int m = 0; m < 4; ++m) _Pragma("unroll") for (int n = 0; n < 2; ++n) _Pragma("unroll") for (int k = 0; k < 2; ++k) \
;         acc[ai][bj][m][n] = __builtin_amdgcn_mfma_f32_16x16x32_bf16(Bt[n][k], At[m][k], acc[ai][bj][m][n], 0, 0, 0); __builtin_amdgcn_s_setprio(0); } while (0)
; #define PG8_WAIT_V(n) asm volatile("s_waitcnt vmcnt(" #n ")" ::: "memory")
; #define PG8_WAIT_L(n) asm volatile("s_waitcnt lgkmcnt(" #n ")" ::: "memory")
; #define PG8_BAR __builtin_amdgcn_s_barrier()
; #define PG8_SCHED __builtin_amdgcn_sched_barrier(0)
; template <class Epi, class Sched, bool ALIGN_EPI = false, bool SP2 = false>
; __device__ __forceinline__ void gemm_phase(PG8_LAS unsigned char* lds, const Gemm g, const Sched& S, const Epi& E) {
;     ...
;             PG8_WAIT_V(8); PG8_WAIT_L(0); PG8_BAR; PG8_MMA(1, 0, At, B0); PG8_MMA(1, 1, At, B1); PG8_BAR; PG8_SCHED;
;             PG8_LDB(B0, 1, 0); PG8_LDB(B1, 1, 1); PG8_SCHED; PG8_LDA(At, 1, 0); PG8_STAGE(PG8_SA(0, 1), a2 + hstep, voffA);
;             PG8_WAIT_V(8); PG8_WAIT_L(0); PG8_BAR; PG8_MMA(0, 0, At, B0); PG8_MMA(0, 1, At, B1); PG8_BAR; PG8_SCHED;
	s_setprio 1
	s_waitcnt lgkmcnt(0)
	v_mfma_f32_16x16x32_bf16 v[60:63], v[140:143], v[178:181], v[60:63]
	v_mfma_f32_16x16x32_bf16 v[56:59], v[154:157], v[178:181], v[56:59]
	v_mfma_f32_16x16x32_bf16 v[44:47], v[140:143], v[194:197], v[44:47]
	v_mfma_f32_16x16x32_bf16 v[40:43], v[154:157], v[194:197], v[40:43]
	v_mfma_f32_16x16x32_bf16 v[28:31], v[140:143], v[202:205], v[28:31]
	v_mfma_f32_16x16x32_bf16 v[24:27], v[154:157], v[202:205], v[24:27]
	v_mfma_f32_16x16x32_bf16 v[12:15], v[140:143], v[214:217], v[12:15]
	v_mfma_f32_16x16x32_bf16 v[8:11], v[154:157], v[214:217], v[8:11]
	v_mfma_f32_16x16x32_bf16 v[60:63], v[150:153], v[182:185], v[60:63]
	v_mfma_f32_16x16x32_bf16 v[56:59], v[158:161], v[182:185], v[56:59]
	v_mfma_f32_16x16x32_bf16 v[44:47], v[150:153], v[198:201], v[44:47]
	v_mfma_f32_16x16x32_bf16 v[40:43], v[158:161], v[198:201], v[40:43]
	v_mfma_f32_16x16x32_bf16 v[28:31], v[150:153], v[210:213], v[28:31]
	v_mfma_f32_16x16x32_bf16 v[24:27], v[158:161], v[210:213], v[24:27]
	v_mfma_f32_16x16x32_bf16 v[12:15], v[150:153], v[218:221], v[12:15]
	v_mfma_f32_16x16x32_bf16 v[8:11], v[158:161], v[218:221], v[8:11]
	s_setprio 0
	s_setprio 1
	v_mfma_f32_16x16x32_bf16 v[52:55], v[162:165], v[178:181], v[52:55]
	v_mfma_f32_16x16x32_bf16 v[48:51], v[170:173], v[178:181], v[48:51]
	v_mfma_f32_16x16x32_bf16 v[36:39], v[162:165], v[194:197], v[36:39]
	v_mfma_f32_16x16x32_bf16 v[32:35], v[170:173], v[194:197], v[32:35]
	v_mfma_f32_16x16x32_bf16 v[20:23], v[162:165], v[202:205], v[20:23]
	v_mfma_f32_16x16x32_bf16 v[16:19], v[170:173], v[202:205], v[16:19]
	v_mfma_f32_16x16x32_bf16 v[4:7], v[162:165], v[214:217], v[4:7]
	v_mfma_f32_16x16x32_bf16 v[0:3], v[170:173], v[214:217], v[0:3]
	v_mfma_f32_16x16x32_bf16 v[52:55], v[166:169], v[182:185], v[52:55]
	v_mfma_f32_16x16x32_bf16 v[48:51], v[174:177], v[182:185], v[48:51]
	v_mfma_f32_16x16x32_bf16 v[36:39], v[166:169], v[198:201], v[36:39]
	v_mfma_f32_16x16x32_bf16 v[32:35], v[174:177], v[198:201], v[32:35]
	v_mfma_f32_16x16x32_bf16 v[20:23], v[166:169], v[210:213], v[20:23]
	v_mfma_f32_16x16x32_bf16 v[16:19], v[174:177], v[210:213], v[16:19]
	v_mfma_f32_16x16x32_bf16 v[4:7], v[166:169], v[218:221], v[4:7]
	v_mfma_f32_16x16x32_bf16 v[0:3], v[174:177], v[218:221], v[0:3]
	s_setprio 0
	s_barrier
	s_add_i32 s40, 0, 0x18000
	v_add_u32_e32 v149, s40, v147
	s_add_i32 s41, 0, 0x1c000
	ds_read_b128 v[140:143], v149
	ds_read_b128 v[150:153], v149 offset:1024
	ds_read_b128 v[154:157], v149 offset:2048
	ds_read_b128 v[158:161], v149 offset:3072
	v_add_u32_e32 v149, s41, v147
	ds_read_b128 v[162:165], v149
	ds_read_b128 v[166:169], v149 offset:1024
	ds_read_b128 v[170:173], v149 offset:2048
	ds_read_b128 v[174:177], v149 offset:3072
	s_add_u32 s22, s22, 0x40000
	s_addc_u32 s23, s23, 0
	s_mov_b32 m0, s30
	v_lshl_add_u64 v[224:225], s[22:23], 0, v[128:129]
	ds_read_b128 v[178:181], v148 offset:32768
	ds_read_b128 v[182:185], v148 offset:33792
	ds_read_b128 v[194:197], v148 offset:34816
	ds_read_b128 v[198:201], v148 offset:35840
	ds_read_b128 v[202:205], v148 offset:36864
	ds_read_b128 v[210:213], v148 offset:37888
	ds_read_b128 v[214:217], v148 offset:38912
	ds_read_b128 v[218:221], v148 offset:39936
	global_load_lds_dwordx4 v[224:225], off
	v_lshl_add_u64 v[224:225], s[22:23], 0, v[130:131]
	s_mov_b32 m0, s31
	s_nop 0
	global_load_lds_dwordx4 v[224:225], off
	s_waitcnt vmcnt(8)
	s_waitcnt lgkmcnt(0)
	s_barrier
	s_setprio 1
	s_waitcnt lgkmcnt(0)
	v_mfma_f32_16x16x32_bf16 v[124:127], v[140:143], v[178:181], v[124:127]
	v_mfma_f32_16x16x32_bf16 v[120:123], v[154:157], v[178:181], v[120:123]
	v_mfma_f32_16x16x32_bf16 v[108:111], v[140:143], v[194:197], v[108:111]
	v_mfma_f32_16x16x32_bf16 v[104:107], v[154:157], v[194:197], v[104:107]
	v_mfma_f32_16x16x32_bf16 v[92:95], v[140:143], v[202:205], v[92:95]
	v_mfma_f32_16x16x32_bf16 v[88:91], v[154:157], v[202:205], v[88:91]
	v_mfma_f32_16x16x32_bf16 v[76:79], v[140:143], v[214:217], v[76:79]
	v_mfma_f32_16x16x32_bf16 v[72:75], v[154:157], v[214:217], v[72:75]
	v_mfma_f32_16x16x32_bf16 v[124:127], v[150:153], v[182:185], v[124:127]
	v_mfma_f32_16x16x32_bf16 v[120:123], v[158:161], v[182:185], v[120:123]
	v_mfma_f32_16x16x32_bf16 v[108:111], v[150:153], v[198:201], v[108:111]
	v_mfma_f32_16x16x32_bf16 v[104:107], v[158:161], v[198:201], v[104:107]
	v_mfma_f32_16x16x32_bf16 v[92:95], v[150:153], v[210:213], v[92:95]
	v_mfma_f32_16x16x32_bf16 v[88:91], v[158:161], v[210:213], v[88:91]
	v_mfma_f32_16x16x32_bf16 v[76:79], v[150:153], v[218:221], v[76:79]
	v_mfma_f32_16x16x32_bf16 v[72:75], v[158:161], v[218:221], v[72:75]
	s_setprio 0
	s_setprio 1
	v_mfma_f32_16x16x32_bf16 v[116:119], v[162:165], v[178:181], v[116:119]
	v_mfma_f32_16x16x32_bf16 v[112:115], v[170:173], v[178:181], v[112:115]
	v_mfma_f32_16x16x32_bf16 v[100:103], v[162:165], v[194:197], v[100:103]
	v_mfma_f32_16x16x32_bf16 v[96:99], v[170:173], v[194:197], v[96:99]
	v_mfma_f32_16x16x32_bf16 v[84:87], v[162:165], v[202:205], v[84:87]
	v_mfma_f32_16x16x32_bf16 v[80:83], v[170:173], v[202:205], v[80:83]
	v_mfma_f32_16x16x32_bf16 v[68:71], v[162:165], v[214:217], v[68:71]
	v_mfma_f32_16x16x32_bf16 v[64:67], v[170:173], v[214:217], v[64:67]
	v_mfma_f32_16x16x32_bf16 v[116:119], v[166:169], v[182:185], v[116:119]
	v_mfma_f32_16x16x32_bf16 v[112:115], v[174:177], v[182:185], v[112:115]
	v_mfma_f32_16x16x32_bf16 v[100:103], v[166:169], v[198:201], v[100:103]
	v_mfma_f32_16x16x32_bf16 v[96:99], v[174:177], v[198:201], v[96:99]
	v_mfma_f32_16x16x32_bf16 v[84:87], v[166:169], v[210:213], v[84:87]
	v_mfma_f32_16x16x32_bf16 v[80:83], v[174:177], v[210:213], v[80:83]
	v_mfma_f32_16x16x32_bf16 v[68:71], v[166:169], v[218:221], v[68:71]
	v_mfma_f32_16x16x32_bf16 v[64:67], v[174:177], v[218:221], v[64:67]
	s_setprio 0
	s_barrier
; #define PG8_STAGE(bufoff, gbase, voff) do { _Pragma("unroll") for (int _i = 0; _i < 2; ++_i) \
;         __builtin_amdgcn_global_load_lds((const unsigned*)((const char*)(gbase) + (voff)[_i]), (PG8_LAS unsigned*)(lds + (bufoff) + ldsw + _i * 8192), 16, 0, 0); } while (0)
; #define PG8_LDA(dst, b, h) do { _Pragma("unroll") for (int m = 0; m < 4; ++m) _Pragma("unroll") for (int k = 0; k < 2; ++k) dst[m][k] = *(const PG8_LAS bf16x8*)(lds + PG8_SA(b, h) + aoff + m * 2048 + k * 1024); } while (0)
; #define PG8_MMA(ai, bj, At, Bt) do { __builtin_amdgcn_s_setprio(1); _Pragma("unroll") for (int m = 0; m < 4; ++m) _Pragma("unroll") for (int n = 0; n < 2; ++n) _Pragma("unroll") for (int k = 0; k < 2; ++k) \
;         acc[ai][bj][m][n] = __builtin_amdgcn_mfma_f32_16x16x32_bf16(Bt[n][k], At[m][k], acc[ai][bj][m][n], 0, 0, 0); __builtin_amdgcn_s_setprio(0); } while (0)
; #define PG8_WAIT_V(n) asm volatile("s_waitcnt vmcnt(" #n ")" ::: "memory")
;     __device__ __forceinline__ void operator()(const f32x4 (&acc)[2][2][4][2], const Unit& u, int wr, int wc, int fr, int fq) const {
;     ...
;             for (int m = 0; m < 4; ++m) { const size_t off = (size_t)(row0 + ai * HALF + m * 16) * 1024 + col0;
; #pragma unroll
;                 for (int bj = 0; bj < 2; ++bj) { const u32x4 gw = *(const u32x4*)(Gt + off + bj * HALF);
;                     f32x4 v0 = acc[ai][bj][m][0], v1 = acc[ai][bj][m][1];
;                     v0[0] *= bflo(gw.x); v0[1] *= bfhi(gw.x); v0[2] *= bflo(gw.y); v0[3] *= bfhi(gw.y);
;                     v1[0] *= bflo(gw.z); v1[1] *= bfhi(gw.z); v1[2] *= bflo(gw.w); v1[3] *= bfhi(gw.w);
;                     if (ADD) { const u32x4 pw = *(const u32x4*)(MG + off + bj * HALF);
;                         v0[0] += bflo(pw.x); v0[1] += bfhi(pw.x); v0[2] += bflo(pw.y); v0[3] += bfhi(pw.y);
;                         v1[0] += bflo(pw.z); v1[1] += bfhi(pw.z); v1[2] += bflo(pw.w); v1[3] += bfhi(pw.w); }
; template <class Epi, class Sched, bool ALIGN_EPI = false, bool SP2 = false>
; __device__ __forceinline__ void gemm_phase(PG8_LAS unsigned char* lds, const Gemm g, const Sched& S, const Epi& E) {
;     ...
;             PG8_LDA(At, 1, 1); PG8_STAGE(PG8_SB(1, 0), b3, voffB); PG8_STAGE(PG8_SB(1, 1), b3 + hstep, voffB); PG8_STAGE(PG8_SA(1, 0), a3, voffA);
;             PG8_WAIT_V(8); PG8_WAIT_L(0); PG8_BAR; PG8_MMA(1, 0, At, B0); PG8_MMA(1, 1, At, B1); PG8_BAR; PG8_SCHED;
	s_add_i32 s22, s40, s27
	v_lshl_add_u64 v[144:145], v[144:145], 0, s[44:45]
	s_mov_b32 m0, s22
	ds_read_b128 v[178:181], v148 offset:49152
	ds_read_b128 v[182:185], v148 offset:50176
	ds_read_b128 v[194:197], v148 offset:51200
	ds_read_b128 v[198:201], v148 offset:52224
	ds_read_b128 v[202:205], v148 offset:53248
	ds_read_b128 v[210:213], v148 offset:54272
	ds_read_b128 v[214:217], v148 offset:55296
	ds_read_b128 v[218:221], v148 offset:56320
	global_load_lds_dwordx4 v[144:145], off
	s_add_i32 m0, s22, 0x2000
	s_add_u32 s20, s20, 0x40080
	v_lshl_add_u64 v[144:145], v[186:187], 0, s[44:45]
	s_addc_u32 s21, s21, 0
	s_add_i32 s22, s41, s27
	global_load_lds_dwordx4 v[144:145], off
	v_lshl_add_u64 v[144:145], s[20:21], 0, v[188:189]
	s_mov_b32 m0, s22
	s_nop 0
	global_load_lds_dwordx4 v[144:145], off
	v_lshl_add_u64 v[144:145], s[20:21], 0, v[132:133]
	s_add_i32 m0, s22, 0x2000
	s_nop 0
	global_load_lds_dwordx4 v[144:145], off
	v_lshl_add_u64 v[144:145], v[190:191], 0, s[44:45]
	s_mov_b32 m0, s34
	s_nop 0
	global_load_lds_dwordx4 v[144:145], off
	v_lshl_add_u64 v[144:145], v[222:223], 0, s[44:45]
	s_mov_b32 m0, s35
	s_nop 0
	global_load_lds_dwordx4 v[144:145], off
	s_waitcnt vmcnt(8)
	s_waitcnt lgkmcnt(0)
	s_barrier
	s_setprio 1
	s_waitcnt lgkmcnt(0)
	v_mfma_f32_16x16x32_bf16 v[60:63], v[140:143], v[178:181], v[60:63]
	v_mfma_f32_16x16x32_bf16 v[56:59], v[154:157], v[178:181], v[56:59]
	v_mfma_f32_16x16x32_bf16 v[44:47], v[140:143], v[194:197], v[44:47]
	v_mfma_f32_16x16x32_bf16 v[40:43], v[154:157], v[194:197], v[40:43]
	v_mfma_f32_16x16x32_bf16 v[28:31], v[140:143], v[202:205], v[28:31]
	v_mfma_f32_16x16x32_bf16 v[24:27], v[154:157], v[202:205], v[24:27]
	v_mfma_f32_16x16x32_bf16 v[12:15], v[140:143], v[214:217], v[12:15]
	v_mfma_f32_16x16x32_bf16 v[8:11], v[154:157], v[214:217], v[8:11]
	v_mfma_f32_16x16x32_bf16 v[60:63], v[150:153], v[182:185], v[60:63]
	v_mfma_f32_16x16x32_bf16 v[56:59], v[158:161], v[182:185], v[56:59]
	v_mfma_f32_16x16x32_bf16 v[44:47], v[150:153], v[198:201], v[44:47]
	v_mfma_f32_16x16x32_bf16 v[40:43], v[158:161], v[198:201], v[40:43]
	v_mfma_f32_16x16x32_bf16 v[28:31], v[150:153], v[210:213], v[28:31]
	v_mfma_f32_16x16x32_bf16 v[24:27], v[158:161], v[210:213], v[24:27]
	v_mfma_f32_16x16x32_bf16 v[12:15], v[150:153], v[218:221], v[12:15]
	v_mfma_f32_16x16x32_bf16 v[8:11], v[158:161], v[218:221], v[8:11]
	s_setprio 0
	s_setprio 1
	v_mfma_f32_16x16x32_bf16 v[52:55], v[162:165], v[178:181], v[52:55]
	v_mfma_f32_16x16x32_bf16 v[48:51], v[170:173], v[178:181], v[48:51]
	s_add_i32 s39, s39, 2
	s_add_u32 s18, s18, 0x100
	s_addc_u32 s19, s19, 0
	s_add_u32 s33, s33, 0x100
	s_addc_u32 s38, s38, 0
	s_cmp_gt_u32 s39, 13
	v_mfma_f32_16x16x32_bf16 v[36:39], v[162:165], v[194:197], v[36:39]
	v_mfma_f32_16x16x32_bf16 v[32:35], v[170:173], v[194:197], v[32:35]
	v_mfma_f32_16x16x32_bf16 v[20:23], v[162:165], v[202:205], v[20:23]
	v_mfma_f32_16x16x32_bf16 v[16:19], v[170:173], v[202:205], v[16:19]
	v_mfma_f32_16x16x32_bf16 v[4:7], v[162:165], v[214:217], v[4:7]
	v_mfma_f32_16x16x32_bf16 v[0:3], v[170:173], v[214:217], v[0:3]
	v_mfma_f32_16x16x32_bf16 v[52:55], v[166:169], v[182:185], v[52:55]
	v_mfma_f32_16x16x32_bf16 v[48:51], v[174:177], v[182:185], v[48:51]
	v_mfma_f32_16x16x32_bf16 v[36:39], v[166:169], v[198:201], v[36:39]
	v_mfma_f32_16x16x32_bf16 v[32:35], v[174:177], v[198:201], v[32:35]
	v_mfma_f32_16x16x32_bf16 v[20:23], v[166:169], v[210:213], v[20:23]
	v_mfma_f32_16x16x32_bf16 v[16:19], v[174:177], v[210:213], v[16:19]
	v_mfma_f32_16x16x32_bf16 v[4:7], v[166:169], v[218:221], v[4:7]
	v_mfma_f32_16x16x32_bf16 v[0:3], v[174:177], v[218:221], v[0:3]
	s_setprio 0
	s_barrier
	s_cbranch_scc0 .LBB0_725
	v_lshl_add_u32 v144, s14, 8, v146
	s_lshl_b32 s18, s16, 8
	v_or_b32_e32 v145, s18, v134
	v_lshlrev_b32_e32 v144, 11, v144
	v_lshl_add_u32 v144, v145, 1, v144
	v_readlane_b32 s16, v254, 44
	v_readlane_b32 s17, v254, 45
	v_readlane_b32 s14, v254, 21
	v_readlane_b32 s15, v254, 22
	s_mov_b64 s[18:19], s[16:17]
	s_mov_b64 s[38:39], s[14:15]
	global_load_dwordx4 v[140:143], v144, s[18:19]
	global_load_dwordx4 v[150:153], v144, s[38:39]
	global_load_dwordx4 v[154:157], v144, s[18:19] offset:256
	global_load_dwordx4 v[158:161], v144, s[38:39] offset:256
	s_add_u32 s18, s16, 0x8000
	s_addc_u32 s19, s17, 0
	s_add_u32 s38, s14, 0x8000
	s_addc_u32 s39, s15, 0
	global_load_dwordx4 v[162:165], v144, s[18:19]
	global_load_dwordx4 v[166:169], v144, s[38:39]
	global_load_dwordx4 v[170:173], v144, s[18:19] offset:256
	global_load_dwordx4 v[174:177], v144, s[38:39] offset:256
	s_add_u32 s18, s16, 0x10000
	s_addc_u32 s19, s17, 0
	s_add_u32 s38, s14, 0x10000
	s_addc_u32 s39, s15, 0
	global_load_dwordx4 v[178:181], v144, s[18:19]
	global_load_dwordx4 v[182:185], v144, s[38:39]
	global_load_dwordx4 v[194:197], v144, s[18:19] offset:256
	global_load_dwordx4 v[198:201], v144, s[38:39] offset:256
	s_add_u32 s18, s16, 0x18000
	s_addc_u32 s19, s17, 0
	s_add_u32 s38, s14, 0x18000
	s_addc_u32 s39, s15, 0
	global_load_dwordx4 v[202:205], v144, s[18:19]
	global_load_dwordx4 v[210:213], v144, s[38:39]
	global_load_dwordx4 v[214:217], v144, s[18:19] offset:256
	global_load_dwordx4 v[218:221], v144, s[38:39] offset:256
	s_and_b64 vcc, exec, s[2:3]
	s_cbranch_vccz .LBB0_728
	s_barrier

; #define PG8_STAGE(bufoff, gbase, voff) do { _Pragma("unroll") for (int _i = 0; _i < 2; ++_i) \
;         __builtin_amdgcn_global_load_lds((const unsigned*)((const char*)(gbase) + (voff)[_i]), (PG8_LAS unsigned*)(lds + (bufoff) + ldsw + _i * 8192), 16, 0, 0); } while (0)
; #define PG8_LDA(dst, b, h) do { _Pragma("unroll") for (int m = 0; m < 4; ++m) _Pragma("unroll") for (int k = 0; k < 2; ++k) dst[m][k] = *(const PG8_LAS bf16x8*)(lds + PG8_SA(b, h) + aoff + m * 2048 + k * 1024); } while (0)
; #define PG8_LDB(dst, b, h) do { _Pragma("unroll") for (int n = 0; n < 2; ++n) _Pragma("unroll") for (int k = 0; k < 2; ++k) dst[n][k] = *(const PG8_LAS bf16x8*)(lds + PG8_SB(b, h) + boff + n * 2048 + k * 1024); } while (0)
; #define PG8_MMA(ai, bj, At, Bt) do { __builtin_amdgcn_s_setprio(1); _Pragma("unroll") for (int m = 0; m < 4; ++m) _Pragma("unroll") for (int n = 0; n < 2; ++n) _Pragma("unroll") for (int k = 0; k < 2; ++k) \
;         acc[ai][bj][m][n] = __builtin_amdgcn_mfma_f32_16x16x32_bf16(Bt[n][k], At[m][k], acc[ai][bj][m][n], 0, 0, 0); __builtin_amdgcn_s_setprio(0); } while (0)
; #define PG8_WAIT_V(n) asm volatile("s_waitcnt vmcnt(" #n ")" ::: "memory")
; #define PG8_BAR __builtin_amdgcn_s_barrier()
; template <class Epi, class Sched, bool ALIGN_EPI = false, bool SP2 = false>
; __device__ __forceinline__ void gemm_phase(PG8_LAS unsigned char* lds, const Gemm g, const Sched& S, const Epi& E) {
;     ...
;         for (int t = 0; t < nt; t += 2) {
;             const bool last = (t == nt - 2);
;             const char* a1 = cA + (size_t)(t + 1) * kstep;
;             const char* a2 = last ? nA : cA + (size_t)(t + 2) * kstep; const char* b2 = last ? nB : cB + (size_t)(t + 2) * kstep;
;             const char* a3 = a2 + kstep; const char* b3 = b2 + kstep;
;             if (last && has_next) S.a_ready(nxt);
;             if constexpr (SP2) {
;             PG8_LDB(B0, 0, 0); PG8_LDB(B1, 0, 1); PG8_SCHED; PG8_LDA(At, 0, 0); PG8_STAGE(PG8_SA(1, 1), a1 + hstep, voffA);
;             PG8_WAIT_V(8); PG8_WAIT_L(0); PG8_BAR; PG8_MMA(0, 0, At, B0); PG8_MMA(0, 1, At, B1); PG8_BAR; PG8_SCHED;
;             PG8_LDA(At, 0, 1); PG8_STAGE(PG8_SB(0, 0), b2, voffB); PG8_STAGE(PG8_SB(0, 1), b2 + hstep, voffB); PG8_STAGE(PG8_SA(0, 0), a2, voffA);
;             PG8_WAIT_V(8); PG8_WAIT_L(0); PG8_BAR; PG8_MMA(1, 0, At, B0); PG8_MMA(1, 1, At, B1); PG8_BAR; PG8_SCHED;
.LBB0_874:
	s_add_u32 s28, s26, 0xfffc0080
	s_addc_u32 s29, s27, -1
	s_add_i32 s51, 0, 0x10000
	s_cmp_eq_u32 s9, s1
	s_cselect_b32 s31, s17, s29
	s_cselect_b32 s30, s47, s28
	v_add_u32_e32 v150, s51, v154
	s_cselect_b32 s29, s19, s50
	s_cselect_b32 s28, s48, s49
	s_add_i32 s54, 0, 0x14000
	ds_read_b128 v[128:131], v150
	ds_read_b128 v[132:135], v150 offset:1024
	ds_read_b128 v[146:149], v150 offset:2048
	ds_read_b128 v[158:161], v150 offset:3072
	v_add_u32_e32 v150, s54, v154
	ds_read_b128 v[162:165], v150
	ds_read_b128 v[166:169], v150 offset:1024
	ds_read_b128 v[170:173], v150 offset:2048
	ds_read_b128 v[174:177], v150 offset:3072
	v_lshl_add_u64 v[150:151], s[26:27], 0, v[142:143]
	s_add_i32 m0, s38, 0xc000
	ds_read_b128 v[178:181], v156
	ds_read_b128 v[182:185], v156 offset:1024
	ds_read_b128 v[194:197], v156 offset:2048
	ds_read_b128 v[198:201], v156 offset:3072
	ds_read_b128 v[202:205], v156 offset:4096
	ds_read_b128 v[210:213], v156 offset:5120
	ds_read_b128 v[214:217], v156 offset:6144
	ds_read_b128 v[218:221], v156 offset:7168
	global_load_lds_dwordx4 v[150:151], off
	v_lshl_add_u64 v[150:151], s[26:27], 0, v[144:145]
	s_add_i32 m0, s38, 0xe000
	s_nop 0
	global_load_lds_dwordx4 v[150:151], off
	s_waitcnt vmcnt(8)
	s_waitcnt lgkmcnt(0)
	s_barrier
	s_setprio 1
	s_waitcnt lgkmcnt(0)
	v_mfma_f32_16x16x32_bf16 v[124:127], v[128:131], v[178:181], v[124:127]
	v_mfma_f32_16x16x32_bf16 v[120:123], v[146:149], v[178:181], v[120:123]
	v_mfma_f32_16x16x32_bf16 v[108:111], v[128:131], v[194:197], v[108:111]
	v_mfma_f32_16x16x32_bf16 v[104:107], v[146:149], v[194:197], v[104:107]
	v_mfma_f32_16x16x32_bf16 v[92:95], v[128:131], v[202:205], v[92:95]
	v_mfma_f32_16x16x32_bf16 v[88:91], v[146:149], v[202:205], v[88:91]
	v_mfma_f32_16x16x32_bf16 v[76:79], v[128:131], v[214:217], v[76:79]
	v_mfma_f32_16x16x32_bf16 v[72:75], v[146:149], v[214:217], v[72:75]
	v_mfma_f32_16x16x32_bf16 v[124:127], v[132:135], v[182:185], v[124:127]
	v_mfma_f32_16x16x32_bf16 v[120:123], v[158:161], v[182:185], v[120:123]
	v_mfma_f32_16x16x32_bf16 v[108:111], v[132:135], v[198:201], v[108:111]
	v_mfma_f32_16x16x32_bf16 v[104:107], v[158:161], v[198:201], v[104:107]
	v_mfma_f32_16x16x32_bf16 v[92:95], v[132:135], v[210:213], v[92:95]
	v_mfma_f32_16x16x32_bf16 v[88:91], v[158:161], v[210:213], v[88:91]
	v_mfma_f32_16x16x32_bf16 v[76:79], v[132:135], v[218:221], v[76:79]
	v_mfma_f32_16x16x32_bf16 v[72:75], v[158:161], v[218:221], v[72:75]
	s_setprio 0
	s_setprio 1
	v_mfma_f32_16x16x32_bf16 v[116:119], v[162:165], v[178:181], v[116:119]
	v_mfma_f32_16x16x32_bf16 v[112:115], v[170:173], v[178:181], v[112:115]
	v_mfma_f32_16x16x32_bf16 v[100:103], v[162:165], v[194:197], v[100:103]
	v_mfma_f32_16x16x32_bf16 v[96:99], v[170:173], v[194:197], v[96:99]
	v_mfma_f32_16x16x32_bf16 v[84:87], v[162:165], v[202:205], v[84:87]
	v_mfma_f32_16x16x32_bf16 v[80:83], v[170:173], v[202:205], v[80:83]
	v_mfma_f32_16x16x32_bf16 v[68:71], v[162:165], v[214:217], v[68:71]
	v_mfma_f32_16x16x32_bf16 v[64:67], v[170:173], v[214:217], v[64:67]
	v_mfma_f32_16x16x32_bf16 v[116:119], v[166:169], v[182:185], v[116:119]
	v_mfma_f32_16x16x32_bf16 v[112:115], v[174:177], v[182:185], v[112:115]
	v_mfma_f32_16x16x32_bf16 v[100:103], v[166:169], v[198:201], v[100:103]
	v_mfma_f32_16x16x32_bf16 v[96:99], v[174:177], v[198:201], v[96:99]
	v_mfma_f32_16x16x32_bf16 v[84:87], v[166:169], v[210:213], v[84:87]
	v_mfma_f32_16x16x32_bf16 v[80:83], v[174:177], v[210:213], v[80:83]
	v_mfma_f32_16x16x32_bf16 v[68:71], v[166:169], v[218:221], v[68:71]
	v_mfma_f32_16x16x32_bf16 v[64:67], v[174:177], v[218:221], v[64:67]
	s_setprio 0
	s_barrier
	s_add_i32 s51, s51, s35
	v_lshl_add_u64 v[150:151], s[28:29], 0, v[188:189]
	s_mov_b32 m0, s51
	ds_read_b128 v[178:181], v156 offset:16384
	ds_read_b128 v[182:185], v156 offset:17408
	ds_read_b128 v[194:197], v156 offset:18432
	ds_read_b128 v[198:201], v156 offset:19456
	ds_read_b128 v[202:205], v156 offset:20480
	ds_read_b128 v[210:213], v156 offset:21504
	ds_read_b128 v[214:217], v156 offset:22528
	ds_read_b128 v[218:221], v156 offset:23552
	global_load_lds_dwordx4 v[150:151], off
	s_add_i32 m0, s51, 0x2000
	s_add_u32 s52, s28, 0x40000
	v_lshl_add_u64 v[186:187], s[28:29], 0, v[140:141]
	s_addc_u32 s53, s29, 0
	s_add_i32 s51, s54, s35
	global_load_lds_dwordx4 v[186:187], off
	v_lshl_add_u64 v[190:191], s[52:53], 0, v[188:189]
	s_mov_b32 m0, s51
	v_lshl_add_u64 v[222:223], s[30:31], 0, v[138:139]
	global_load_lds_dwordx4 v[190:191], off
	v_lshl_add_u64 v[190:191], s[52:53], 0, v[140:141]
	s_add_i32 m0, s51, 0x2000
	s_nop 0
	global_load_lds_dwordx4 v[190:191], off
	v_lshl_add_u64 v[190:191], s[30:31], 0, v[136:137]
	s_mov_b32 m0, s38
	s_nop 0
	global_load_lds_dwordx4 v[190:191], off
	s_mov_b32 m0, s39
	s_nop 0
	global_load_lds_dwordx4 v[222:223], off
	s_waitcnt vmcnt(8)
	s_waitcnt lgkmcnt(0)
	s_barrier
; #define PG8_STAGE(bufoff, gbase, voff) do { _Pragma("unroll") for (int _i = 0; _i < 2; ++_i) \
;         __builtin_amdgcn_global_load_lds((const unsigned*)((const char*)(gbase) + (voff)[_i]), (PG8_LAS unsigned*)(lds + (bufoff) + ldsw + _i * 8192), 16, 0, 0); } while (0)
; #define PG8_LDA(dst, b, h) do { _Pragma("unroll") for (int m = 0; m < 4; ++m) _Pragma("unroll") for (int k = 0; k < 2; ++k) dst[m][k] = *(const PG8_LAS bf16x8*)(lds + PG8_SA(b, h) + aoff + m * 2048 + k * 1024); } while (0)
; #define PG8_LDB(dst, b, h) do { _Pragma("unroll") for (int n = 0; n < 2; ++n) _Pragma("unroll") for (int k = 0; k < 2; ++k) dst[n][k] = *(const PG8_LAS bf16x8*)(lds + PG8_SB(b, h) + boff + n * 2048 + k * 1024); } while (0)
; #define PG8_MMA(ai, bj, At, Bt) do { __builtin_amdgcn_s_setprio(1); _Pragma("unroll") for (int m = 0; m < 4; ++m) _Pragma("unroll") for (int n = 0; n < 2; ++n) _Pragma("unroll") for (int k = 0; k < 2; ++k) \
;         acc[ai][bj][m][n] = __builtin_amdgcn_mfma_f32_16x16x32_bf16(Bt[n][k], At[m][k], acc[ai][bj][m][n], 0, 0, 0); __builtin_amdgcn_s_setprio(0); } while (0)
; #define PG8_WAIT_V(n) asm volatile("s_waitcnt vmcnt(" #n ")" ::: "memory")
; #define PG8_WAIT_L(n) asm volatile("s_waitcnt lgkmcnt(" #n ")" ::: "memory")
; #define PG8_BAR __builtin_amdgcn_s_barrier()
; #define PG8_SCHED __builtin_amdgcn_sched_barrier(0)
; template <class Epi, class Sched, bool ALIGN_EPI = false, bool SP2 = false>
; __device__ __forceinline__ void gemm_phase(PG8_LAS unsigned char* lds, const Gemm g, const Sched& S, const Epi& E) {
;     ...
;             PG8_WAIT_V(8); PG8_WAIT_L(0); PG8_BAR; PG8_MMA(1, 0, At, B0); PG8_MMA(1, 1, At, B1); PG8_BAR; PG8_SCHED;
;             PG8_LDB(B0, 1, 0); PG8_LDB(B1, 1, 1); PG8_SCHED; PG8_LDA(At, 1, 0); PG8_STAGE(PG8_SA(0, 1), a2 + hstep, voffA);
;             PG8_WAIT_V(8); PG8_WAIT_L(0); PG8_BAR; PG8_MMA(0, 0, At, B0); PG8_MMA(0, 1, At, B1); PG8_BAR; PG8_SCHED;
	s_setprio 1
	s_waitcnt lgkmcnt(0)
	v_mfma_f32_16x16x32_bf16 v[60:63], v[128:131], v[178:181], v[60:63]
	v_mfma_f32_16x16x32_bf16 v[56:59], v[146:149], v[178:181], v[56:59]
	v_mfma_f32_16x16x32_bf16 v[44:47], v[128:131], v[194:197], v[44:47]
	v_mfma_f32_16x16x32_bf16 v[40:43], v[146:149], v[194:197], v[40:43]
	v_mfma_f32_16x16x32_bf16 v[28:31], v[128:131], v[202:205], v[28:31]
	v_mfma_f32_16x16x32_bf16 v[24:27], v[146:149], v[202:205], v[24:27]
	v_mfma_f32_16x16x32_bf16 v[12:15], v[128:131], v[214:217], v[12:15]
	v_mfma_f32_16x16x32_bf16 v[8:11], v[146:149], v[214:217], v[8:11]
	v_mfma_f32_16x16x32_bf16 v[60:63], v[132:135], v[182:185], v[60:63]
	v_mfma_f32_16x16x32_bf16 v[56:59], v[158:161], v[182:185], v[56:59]
	v_mfma_f32_16x16x32_bf16 v[44:47], v[132:135], v[198:201], v[44:47]
	v_mfma_f32_16x16x32_bf16 v[40:43], v[158:161], v[198:201], v[40:43]
	v_mfma_f32_16x16x32_bf16 v[28:31], v[132:135], v[210:213], v[28:31]
	v_mfma_f32_16x16x32_bf16 v[24:27], v[158:161], v[210:213], v[24:27]
	v_mfma_f32_16x16x32_bf16 v[12:15], v[132:135], v[218:221], v[12:15]
	v_mfma_f32_16x16x32_bf16 v[8:11], v[158:161], v[218:221], v[8:11]
	s_setprio 0
	s_setprio 1
	v_mfma_f32_16x16x32_bf16 v[52:55], v[162:165], v[178:181], v[52:55]
	v_mfma_f32_16x16x32_bf16 v[48:51], v[170:173], v[178:181], v[48:51]
	v_mfma_f32_16x16x32_bf16 v[36:39], v[162:165], v[194:197], v[36:39]
	v_mfma_f32_16x16x32_bf16 v[32:35], v[170:173], v[194:197], v[32:35]
	v_mfma_f32_16x16x32_bf16 v[20:23], v[162:165], v[202:205], v[20:23]
	v_mfma_f32_16x16x32_bf16 v[16:19], v[170:173], v[202:205], v[16:19]
	v_mfma_f32_16x16x32_bf16 v[4:7], v[162:165], v[214:217], v[4:7]
	v_mfma_f32_16x16x32_bf16 v[0:3], v[170:173], v[214:217], v[0:3]
	v_mfma_f32_16x16x32_bf16 v[52:55], v[166:169], v[182:185], v[52:55]
	v_mfma_f32_16x16x32_bf16 v[48:51], v[174:177], v[182:185], v[48:51]
	v_mfma_f32_16x16x32_bf16 v[36:39], v[166:169], v[198:201], v[36:39]
	v_mfma_f32_16x16x32_bf16 v[32:35], v[174:177], v[198:201], v[32:35]
	v_mfma_f32_16x16x32_bf16 v[20:23], v[166:169], v[210:213], v[20:23]
	v_mfma_f32_16x16x32_bf16 v[16:19], v[174:177], v[210:213], v[16:19]
	v_mfma_f32_16x16x32_bf16 v[4:7], v[166:169], v[218:221], v[4:7]
	v_mfma_f32_16x16x32_bf16 v[0:3], v[174:177], v[218:221], v[0:3]
	s_setprio 0
	s_barrier
	s_add_i32 s51, 0, 0x18000
	v_add_u32_e32 v157, s51, v154
	s_add_i32 s52, 0, 0x1c000
	ds_read_b128 v[128:131], v157
	ds_read_b128 v[132:135], v157 offset:1024
	ds_read_b128 v[146:149], v157 offset:2048
	ds_read_b128 v[158:161], v157 offset:3072
	v_add_u32_e32 v157, s52, v154
	ds_read_b128 v[162:165], v157
	ds_read_b128 v[166:169], v157 offset:1024
	ds_read_b128 v[170:173], v157 offset:2048
	ds_read_b128 v[174:177], v157 offset:3072
	s_add_u32 s30, s30, 0x40000
	s_addc_u32 s31, s31, 0
	s_mov_b32 m0, s40
	v_lshl_add_u64 v[224:225], s[30:31], 0, v[136:137]
	ds_read_b128 v[178:181], v156 offset:32768
	ds_read_b128 v[182:185], v156 offset:33792
	ds_read_b128 v[194:197], v156 offset:34816
	ds_read_b128 v[198:201], v156 offset:35840
	ds_read_b128 v[202:205], v156 offset:36864
	ds_read_b128 v[210:213], v156 offset:37888
	ds_read_b128 v[214:217], v156 offset:38912
	ds_read_b128 v[218:221], v156 offset:39936
	global_load_lds_dwordx4 v[224:225], off
	v_lshl_add_u64 v[224:225], s[30:31], 0, v[138:139]
	s_mov_b32 m0, s41
	s_nop 0
	global_load_lds_dwordx4 v[224:225], off
	s_waitcnt vmcnt(8)
	s_waitcnt lgkmcnt(0)
	s_barrier
	s_setprio 1
	s_waitcnt lgkmcnt(0)
	v_mfma_f32_16x16x32_bf16 v[124:127], v[128:131], v[178:181], v[124:127]
	v_mfma_f32_16x16x32_bf16 v[120:123], v[146:149], v[178:181], v[120:123]
	v_mfma_f32_16x16x32_bf16 v[108:111], v[128:131], v[194:197], v[108:111]
	v_mfma_f32_16x16x32_bf16 v[104:107], v[146:149], v[194:197], v[104:107]
	v_mfma_f32_16x16x32_bf16 v[92:95], v[128:131], v[202:205], v[92:95]
	v_mfma_f32_16x16x32_bf16 v[88:91], v[146:149], v[202:205], v[88:91]
	v_mfma_f32_16x16x32_bf16 v[76:79], v[128:131], v[214:217], v[76:79]
	v_mfma_f32_16x16x32_bf16 v[72:75], v[146:149], v[214:217], v[72:75]
	v_mfma_f32_16x16x32_bf16 v[124:127], v[132:135], v[182:185], v[124:127]
	v_mfma_f32_16x16x32_bf16 v[120:123], v[158:161], v[182:185], v[120:123]
	v_mfma_f32_16x16x32_bf16 v[108:111], v[132:135], v[198:201], v[108:111]
	v_mfma_f32_16x16x32_bf16 v[104:107], v[158:161], v[198:201], v[104:107]
	v_mfma_f32_16x16x32_bf16 v[92:95], v[132:135], v[210:213], v[92:95]
	v_mfma_f32_16x16x32_bf16 v[88:91], v[158:161], v[210:213], v[88:91]
	v_mfma_f32_16x16x32_bf16 v[76:79], v[132:135], v[218:221], v[76:79]
	v_mfma_f32_16x16x32_bf16 v[72:75], v[158:161], v[218:221], v[72:75]
	s_setprio 0
	s_setprio 1
	v_mfma_f32_16x16x32_bf16 v[116:119], v[162:165], v[178:181], v[116:119]
	v_mfma_f32_16x16x32_bf16 v[112:115], v[170:173], v[178:181], v[112:115]
	v_mfma_f32_16x16x32_bf16 v[100:103], v[162:165], v[194:197], v[100:103]
	v_mfma_f32_16x16x32_bf16 v[96:99], v[170:173], v[194:197], v[96:99]
	v_mfma_f32_16x16x32_bf16 v[84:87], v[162:165], v[202:205], v[84:87]
	v_mfma_f32_16x16x32_bf16 v[80:83], v[170:173], v[202:205], v[80:83]
	v_mfma_f32_16x16x32_bf16 v[68:71], v[162:165], v[214:217], v[68:71]
	v_mfma_f32_16x16x32_bf16 v[64:67], v[170:173], v[214:217], v[64:67]
	v_mfma_f32_16x16x32_bf16 v[116:119], v[166:169], v[182:185], v[116:119]
	v_mfma_f32_16x16x32_bf16 v[112:115], v[174:177], v[182:185], v[112:115]
	v_mfma_f32_16x16x32_bf16 v[100:103], v[166:169], v[198:201], v[100:103]
	v_mfma_f32_16x16x32_bf16 v[96:99], v[174:177], v[198:201], v[96:99]
	v_mfma_f32_16x16x32_bf16 v[84:87], v[166:169], v[210:213], v[84:87]
	v_mfma_f32_16x16x32_bf16 v[80:83], v[174:177], v[210:213], v[80:83]
	v_mfma_f32_16x16x32_bf16 v[68:71], v[166:169], v[218:221], v[68:71]
	v_mfma_f32_16x16x32_bf16 v[64:67], v[174:177], v[218:221], v[64:67]
	s_setprio 0
	s_barrier
; __device__ __forceinline__ u32x4 pack8(const f32x4 a, const f32x4 b) { u32x4 w; w.x = cvt_pk_bf16(a[0], a[1]); w.y = cvt_pk_bf16(a[2], a[3]); w.z = cvt_pk_bf16(b[0], b[1]); w.w = cvt_pk_bf16(b[2], b[3]); return w; }
; #define PG8_STAGE(bufoff, gbase, voff) do { _Pragma("unroll") for (int _i = 0; _i < 2; ++_i) \
;         __builtin_amdgcn_global_load_lds((const unsigned*)((const char*)(gbase) + (voff)[_i]), (PG8_LAS unsigned*)(lds + (bufoff) + ldsw + _i * 8192), 16, 0, 0); } while (0)
; #define PG8_LDA(dst, b, h) do { _Pragma("unroll") for (int m = 0; m < 4; ++m) _Pragma("unroll") for (int k = 0; k < 2; ++k) dst[m][k] = *(const PG8_LAS bf16x8*)(lds + PG8_SA(b, h) + aoff + m * 2048 + k * 1024); } while (0)
; #define PG8_MMA(ai, bj, At, Bt) do { __builtin_amdgcn_s_setprio(1); _Pragma("unroll") for (int m = 0; m < 4; ++m) _Pragma("unroll") for (int n = 0; n < 2; ++n) _Pragma("unroll") for (int k = 0; k < 2; ++k) \
;         acc[ai][bj][m][n] = __builtin_amdgcn_mfma_f32_16x16x32_bf16(Bt[n][k], At[m][k], acc[ai][bj][m][n], 0, 0, 0); __builtin_amdgcn_s_setprio(0); } while (0)
; #define PG8_BAR __builtin_amdgcn_s_barrier()
;     __device__ __forceinline__ void operator()(const f32x4 (&acc)[2][2][4][2], const Unit& u, int wr, int wc, int fr, int fq) const {
;     ...
;             for (int m = 0; m < 4; ++m) { const size_t ro = (size_t)(row0 + ai * HALF + m * 16) * 1024 + col0;
; #pragma unroll
;                 for (int bj = 0; bj < 2; ++bj) { const size_t o = ro + bj * HALF;
;                     if (part) *(u32x4*)(pbase + o) = pack8(acc[ai][bj][m][0], acc[ai][bj][m][1]);
;                     else { f32x4 r0, r1;
;                         if (X32) { r0 = *(const f32x4*)(X32 + o); r1 = *(const f32x4*)(X32 + o + 4); }
;                         else { const u32x4 hw = *(const u32x4*)(H + o); r0 = (f32x4){bflo(hw.x), bfhi(hw.x), bflo(hw.y), bfhi(hw.y)}; r1 = (f32x4){bflo(hw.z), bfhi(hw.z), bflo(hw.w), bfhi(hw.w)}; }
; template <class Epi, class Sched, bool ALIGN_EPI = false, bool SP2 = false>
; __device__ __forceinline__ void gemm_phase(PG8_LAS unsigned char* lds, const Gemm g, const Sched& S, const Epi& E) {
;     ...
;             PG8_LDA(At, 1, 1); PG8_STAGE(PG8_SB(1, 0), b3, voffB); PG8_STAGE(PG8_SB(1, 1), b3 + hstep, voffB); PG8_STAGE(PG8_SA(1, 0), a3, voffA);
;             PG8_WAIT_V(8); PG8_WAIT_L(0); PG8_BAR; PG8_MMA(1, 0, At, B0); PG8_MMA(1, 1, At, B1); PG8_BAR; PG8_SCHED;
	s_add_i32 s30, s51, s35
	v_lshl_add_u64 v[150:151], v[150:151], 0, s[56:57]
	s_mov_b32 m0, s30
	ds_read_b128 v[178:181], v156 offset:49152
	ds_read_b128 v[182:185], v156 offset:50176
	ds_read_b128 v[194:197], v156 offset:51200
	ds_read_b128 v[198:201], v156 offset:52224
	ds_read_b128 v[202:205], v156 offset:53248
	ds_read_b128 v[210:213], v156 offset:54272
	ds_read_b128 v[214:217], v156 offset:55296
	ds_read_b128 v[218:221], v156 offset:56320
	global_load_lds_dwordx4 v[150:151], off
	s_add_i32 m0, s30, 0x2000
	s_add_u32 s28, s28, 0x40080
	v_lshl_add_u64 v[150:151], v[186:187], 0, s[56:57]
	s_addc_u32 s29, s29, 0
	s_add_i32 s30, s52, s35
	global_load_lds_dwordx4 v[150:151], off
	v_lshl_add_u64 v[150:151], s[28:29], 0, v[188:189]
	s_mov_b32 m0, s30
	s_nop 0
	global_load_lds_dwordx4 v[150:151], off
	v_lshl_add_u64 v[150:151], s[28:29], 0, v[140:141]
	s_add_i32 m0, s30, 0x2000
	s_nop 0
	global_load_lds_dwordx4 v[150:151], off
	v_lshl_add_u64 v[150:151], v[190:191], 0, s[56:57]
	s_mov_b32 m0, s42
	s_nop 0
	global_load_lds_dwordx4 v[150:151], off
	v_lshl_add_u64 v[150:151], v[222:223], 0, s[56:57]
	s_mov_b32 m0, s43
	s_nop 0
	global_load_lds_dwordx4 v[150:151], off
	s_waitcnt vmcnt(8)
	s_waitcnt lgkmcnt(0)
	s_barrier
	s_setprio 1
	s_waitcnt lgkmcnt(0)
	v_mfma_f32_16x16x32_bf16 v[60:63], v[128:131], v[178:181], v[60:63]
	v_mfma_f32_16x16x32_bf16 v[56:59], v[146:149], v[178:181], v[56:59]
	v_mfma_f32_16x16x32_bf16 v[44:47], v[128:131], v[194:197], v[44:47]
	v_mfma_f32_16x16x32_bf16 v[40:43], v[146:149], v[194:197], v[40:43]
	v_mfma_f32_16x16x32_bf16 v[28:31], v[128:131], v[202:205], v[28:31]
	v_mfma_f32_16x16x32_bf16 v[24:27], v[146:149], v[202:205], v[24:27]
	v_mfma_f32_16x16x32_bf16 v[12:15], v[128:131], v[214:217], v[12:15]
	v_mfma_f32_16x16x32_bf16 v[8:11], v[146:149], v[214:217], v[8:11]
	v_mfma_f32_16x16x32_bf16 v[60:63], v[132:135], v[182:185], v[60:63]
	v_mfma_f32_16x16x32_bf16 v[56:59], v[158:161], v[182:185], v[56:59]
	v_mfma_f32_16x16x32_bf16 v[44:47], v[132:135], v[198:201], v[44:47]
	v_mfma_f32_16x16x32_bf16 v[40:43], v[158:161], v[198:201], v[40:43]
	v_mfma_f32_16x16x32_bf16 v[28:31], v[132:135], v[210:213], v[28:31]
	v_mfma_f32_16x16x32_bf16 v[24:27], v[158:161], v[210:213], v[24:27]
	v_mfma_f32_16x16x32_bf16 v[12:15], v[132:135], v[218:221], v[12:15]
	v_mfma_f32_16x16x32_bf16 v[8:11], v[158:161], v[218:221], v[8:11]
	s_setprio 0
	s_setprio 1
	v_mfma_f32_16x16x32_bf16 v[52:55], v[162:165], v[178:181], v[52:55]
	v_mfma_f32_16x16x32_bf16 v[48:51], v[170:173], v[178:181], v[48:51]
	s_add_i32 s28, s1, 2
	s_add_u32 s26, s26, 0x100
	s_addc_u32 s27, s27, 0
	s_add_u32 s49, s49, 0x100
	s_addc_u32 s50, s50, 0
	s_cmp_ge_u32 s1, s9
	s_mov_b32 s1, s28
	v_mfma_f32_16x16x32_bf16 v[36:39], v[162:165], v[194:197], v[36:39]
	v_mfma_f32_16x16x32_bf16 v[32:35], v[170:173], v[194:197], v[32:35]
	v_mfma_f32_16x16x32_bf16 v[20:23], v[162:165], v[202:205], v[20:23]
	v_mfma_f32_16x16x32_bf16 v[16:19], v[170:173], v[202:205], v[16:19]
	v_mfma_f32_16x16x32_bf16 v[4:7], v[162:165], v[214:217], v[4:7]
	v_mfma_f32_16x16x32_bf16 v[0:3], v[170:173], v[214:217], v[0:3]
	v_mfma_f32_16x16x32_bf16 v[52:55], v[166:169], v[182:185], v[52:55]
	v_mfma_f32_16x16x32_bf16 v[48:51], v[174:177], v[182:185], v[48:51]
	v_mfma_f32_16x16x32_bf16 v[36:39], v[166:169], v[198:201], v[36:39]
	v_mfma_f32_16x16x32_bf16 v[32:35], v[174:177], v[198:201], v[32:35]
	v_mfma_f32_16x16x32_bf16 v[20:23], v[166:169], v[210:213], v[20:23]
	v_mfma_f32_16x16x32_bf16 v[16:19], v[174:177], v[210:213], v[16:19]
	v_mfma_f32_16x16x32_bf16 v[4:7], v[166:169], v[218:221], v[4:7]
	v_mfma_f32_16x16x32_bf16 v[0:3], v[174:177], v[218:221], v[0:3]
	s_setprio 0
	s_barrier
	s_cbranch_scc0 .LBB0_874
	s_cmp_lg_u32 s9, 16
	s_cbranch_scc1 .Lp4_nopre
	v_lshl_add_u32 v150, s0, 8, v153
	v_lshl_or_b32 v151, s8, 8, v155
	v_lshlrev_b32_e32 v150, 11, v150
	v_lshl_add_u32 v150, v151, 1, v150
	v_readlane_b32 s0, v254, 17
	v_readlane_b32 s1, v254, 18
	s_and_b64 vcc, exec, s[14:15]
	s_cbranch_vccz .Lp4_pre_h
	v_lshlrev_b32_e32 v151, 1, v150
	s_add_u32 s26, s2, 0x0
	s_addc_u32 s27, s3, 0
	global_load_dwordx4 v[128:131], v151, s[26:27]
	global_load_dwordx4 v[132:135], v151, s[26:27] offset:16
	global_load_dwordx4 v[146:149], v151, s[26:27] offset:512
	global_load_dwordx4 v[158:161], v151, s[26:27] offset:528
	s_add_u32 s26, s2, 0x10000
	s_addc_u32 s27, s3, 0
	global_load_dwordx4 v[162:165], v151, s[26:27]
	global_load_dwordx4 v[166:169], v151, s[26:27] offset:16
	global_load_dwordx4 v[170:173], v151, s[26:27] offset:512
	global_load_dwordx4 v[174:177], v151, s[26:27] offset:528
	s_add_u32 s26, s2, 0x20000
	s_addc_u32 s27, s3, 0
	global_load_dwordx4 v[178:181], v151, s[26:27]
	global_load_dwordx4 v[182:185], v151, s[26:27] offset:16
	global_load_dwordx4 v[194:197], v151, s[26:27] offset:512
	global_load_dwordx4 v[198:201], v151, s[26:27] offset:528
	s_add_u32 s26, s2, 0x30000
	s_addc_u32 s27, s3, 0
	global_load_dwordx4 v[202:205], v151, s[26:27]
	global_load_dwordx4 v[210:213], v151, s[26:27] offset:16
	global_load_dwordx4 v[214:217], v151, s[26:27] offset:512
	global_load_dwordx4 v[218:221], v151, s[26:27] offset:528
	s_branch .Lp4_nopre

; #define PG8_STAGE(bufoff, gbase, voff) do { _Pragma("unroll") for (int _i = 0; _i < 2; ++_i) \
;         __builtin_amdgcn_global_load_lds((const unsigned*)((const char*)(gbase) + (voff)[_i]), (PG8_LAS unsigned*)(lds + (bufoff) + ldsw + _i * 8192), 16, 0, 0); } while (0)
; #define PG8_LDA(dst, b, h) do { _Pragma("unroll") for (int m = 0; m < 4; ++m) _Pragma("unroll") for (int k = 0; k < 2; ++k) dst[m][k] = *(const PG8_LAS bf16x8*)(lds + PG8_SA(b, h) + aoff + m * 2048 + k * 1024); } while (0)
; #define PG8_LDB(dst, b, h) do { _Pragma("unroll") for (int n = 0; n < 2; ++n) _Pragma("unroll") for (int k = 0; k < 2; ++k) dst[n][k] = *(const PG8_LAS bf16x8*)(lds + PG8_SB(b, h) + boff + n * 2048 + k * 1024); } while (0)
; #define PG8_MMA(ai, bj, At, Bt) do { __builtin_amdgcn_s_setprio(1); _Pragma("unroll") for (int m = 0; m < 4; ++m) _Pragma("unroll") for (int n = 0; n < 2; ++n) _Pragma("unroll") for (int k = 0; k < 2; ++k) \
;         acc[ai][bj][m][n] = __builtin_amdgcn_mfma_f32_16x16x32_bf16(Bt[n][k], At[m][k], acc[ai][bj][m][n], 0, 0, 0); __builtin_amdgcn_s_setprio(0); } while (0)
; #define PG8_WAIT_V(n) asm volatile("s_waitcnt vmcnt(" #n ")" ::: "memory")
; #define PG8_BAR __builtin_amdgcn_s_barrier()
; template <class Epi, class Sched, bool ALIGN_EPI = false, bool SP2 = false>
; __device__ __forceinline__ void gemm_phase(PG8_LAS unsigned char* lds, const Gemm g, const Sched& S, const Epi& E) {
;     ...
;         for (int t = 0; t < nt; t += 2) {
;             const bool last = (t == nt - 2);
;             const char* a1 = cA + (size_t)(t + 1) * kstep;
;             const char* a2 = last ? nA : cA + (size_t)(t + 2) * kstep; const char* b2 = last ? nB : cB + (size_t)(t + 2) * kstep;
;             const char* a3 = a2 + kstep; const char* b3 = b2 + kstep;
;             if (last && has_next) S.a_ready(nxt);
;             if constexpr (SP2) {
;             PG8_LDB(B0, 0, 0); PG8_LDB(B1, 0, 1); PG8_SCHED; PG8_LDA(At, 0, 0); PG8_STAGE(PG8_SA(1, 1), a1 + hstep, voffA);
;             PG8_WAIT_V(8); PG8_WAIT_L(0); PG8_BAR; PG8_MMA(0, 0, At, B0); PG8_MMA(0, 1, At, B1); PG8_BAR; PG8_SCHED;
;             PG8_LDA(At, 0, 1); PG8_STAGE(PG8_SB(0, 0), b2, voffB); PG8_STAGE(PG8_SB(0, 1), b2 + hstep, voffB); PG8_STAGE(PG8_SA(0, 0), a2, voffA);
;             PG8_WAIT_V(8); PG8_WAIT_L(0); PG8_BAR; PG8_MMA(1, 0, At, B0); PG8_MMA(1, 1, At, B1); PG8_BAR; PG8_SCHED;
.LBB0_1120:
	s_add_u32 s20, s18, 0xfffc0080
	s_addc_u32 s21, s19, -1
	s_add_i32 s42, 0, 0x10000
	s_cmp_eq_u32 s41, 12
	s_cselect_b32 s23, s11, s21
	s_cselect_b32 s22, s37, s20
	v_add_u32_e32 v140, s42, v144
	s_cselect_b32 s21, s9, s40
	s_cselect_b32 s20, s38, s39
	s_add_i32 s44, 0, 0x14000
	ds_read_b128 v[146:149], v140
	ds_read_b128 v[150:153], v140 offset:1024
	ds_read_b128 v[154:157], v140 offset:2048
	ds_read_b128 v[158:161], v140 offset:3072
	v_add_u32_e32 v140, s44, v144
	ds_read_b128 v[162:165], v140
	ds_read_b128 v[166:169], v140 offset:1024
	ds_read_b128 v[170:173], v140 offset:2048
	ds_read_b128 v[174:177], v140 offset:3072
	v_lshl_add_u64 v[140:141], s[18:19], 0, v[136:137]
	s_add_i32 m0, s28, 0xc000
	ds_read_b128 v[178:181], v145
	ds_read_b128 v[182:185], v145 offset:1024
	ds_read_b128 v[194:197], v145 offset:2048
	ds_read_b128 v[198:201], v145 offset:3072
	ds_read_b128 v[202:205], v145 offset:4096
	ds_read_b128 v[210:213], v145 offset:5120
	ds_read_b128 v[214:217], v145 offset:6144
	ds_read_b128 v[218:221], v145 offset:7168
	global_load_lds_dwordx4 v[140:141], off
	v_lshl_add_u64 v[140:141], s[18:19], 0, v[138:139]
	s_add_i32 m0, s28, 0xe000
	s_nop 0
	global_load_lds_dwordx4 v[140:141], off
	s_waitcnt vmcnt(8)
	s_waitcnt lgkmcnt(0)
	s_barrier
	s_setprio 1
	s_waitcnt lgkmcnt(0)
	v_mfma_f32_16x16x32_bf16 v[124:127], v[146:149], v[178:181], v[124:127]
	v_mfma_f32_16x16x32_bf16 v[116:119], v[154:157], v[178:181], v[116:119]
	v_mfma_f32_16x16x32_bf16 v[108:111], v[146:149], v[194:197], v[108:111]
	v_mfma_f32_16x16x32_bf16 v[100:103], v[154:157], v[194:197], v[100:103]
	v_mfma_f32_16x16x32_bf16 v[92:95], v[146:149], v[202:205], v[92:95]
	v_mfma_f32_16x16x32_bf16 v[84:87], v[154:157], v[202:205], v[84:87]
	v_mfma_f32_16x16x32_bf16 v[76:79], v[146:149], v[214:217], v[76:79]
	v_mfma_f32_16x16x32_bf16 v[68:71], v[154:157], v[214:217], v[68:71]
	v_mfma_f32_16x16x32_bf16 v[124:127], v[150:153], v[182:185], v[124:127]
	v_mfma_f32_16x16x32_bf16 v[116:119], v[158:161], v[182:185], v[116:119]
	v_mfma_f32_16x16x32_bf16 v[108:111], v[150:153], v[198:201], v[108:111]
	v_mfma_f32_16x16x32_bf16 v[100:103], v[158:161], v[198:201], v[100:103]
	v_mfma_f32_16x16x32_bf16 v[92:95], v[150:153], v[210:213], v[92:95]
	v_mfma_f32_16x16x32_bf16 v[84:87], v[158:161], v[210:213], v[84:87]
	v_mfma_f32_16x16x32_bf16 v[76:79], v[150:153], v[218:221], v[76:79]
	v_mfma_f32_16x16x32_bf16 v[68:71], v[158:161], v[218:221], v[68:71]
	s_setprio 0
	s_setprio 1
	v_mfma_f32_16x16x32_bf16 v[120:123], v[162:165], v[178:181], v[120:123]
	v_mfma_f32_16x16x32_bf16 v[112:115], v[170:173], v[178:181], v[112:115]
	v_mfma_f32_16x16x32_bf16 v[104:107], v[162:165], v[194:197], v[104:107]
	v_mfma_f32_16x16x32_bf16 v[96:99], v[170:173], v[194:197], v[96:99]
	v_mfma_f32_16x16x32_bf16 v[88:91], v[162:165], v[202:205], v[88:91]
	v_mfma_f32_16x16x32_bf16 v[80:83], v[170:173], v[202:205], v[80:83]
	v_mfma_f32_16x16x32_bf16 v[72:75], v[162:165], v[214:217], v[72:75]
	v_mfma_f32_16x16x32_bf16 v[64:67], v[170:173], v[214:217], v[64:67]
	v_mfma_f32_16x16x32_bf16 v[120:123], v[166:169], v[182:185], v[120:123]
	v_mfma_f32_16x16x32_bf16 v[112:115], v[174:177], v[182:185], v[112:115]
	v_mfma_f32_16x16x32_bf16 v[104:107], v[166:169], v[198:201], v[104:107]
	v_mfma_f32_16x16x32_bf16 v[96:99], v[174:177], v[198:201], v[96:99]
	v_mfma_f32_16x16x32_bf16 v[88:91], v[166:169], v[210:213], v[88:91]
	v_mfma_f32_16x16x32_bf16 v[80:83], v[174:177], v[210:213], v[80:83]
	v_mfma_f32_16x16x32_bf16 v[72:75], v[166:169], v[218:221], v[72:75]
	v_mfma_f32_16x16x32_bf16 v[64:67], v[174:177], v[218:221], v[64:67]
	s_setprio 0
	s_barrier
	s_add_i32 s42, s42, s27
	v_lshl_add_u64 v[140:141], s[20:21], 0, v[188:189]
	s_mov_b32 m0, s42
	ds_read_b128 v[178:181], v145 offset:16384
	ds_read_b128 v[182:185], v145 offset:17408
	ds_read_b128 v[194:197], v145 offset:18432
	ds_read_b128 v[198:201], v145 offset:19456
	ds_read_b128 v[202:205], v145 offset:20480
	ds_read_b128 v[210:213], v145 offset:21504
	ds_read_b128 v[214:217], v145 offset:22528
	ds_read_b128 v[218:221], v145 offset:23552
	global_load_lds_dwordx4 v[140:141], off
	s_add_i32 m0, s42, 0x2000
	s_add_u32 s42, s20, 0x40000
	v_lshl_add_u64 v[186:187], s[20:21], 0, v[132:133]
	s_addc_u32 s43, s21, 0
	s_add_i32 s44, s44, s27
	global_load_lds_dwordx4 v[186:187], off
	v_lshl_add_u64 v[190:191], s[42:43], 0, v[188:189]
	s_mov_b32 m0, s44
	v_lshl_add_u64 v[222:223], s[22:23], 0, v[130:131]
	global_load_lds_dwordx4 v[190:191], off
	v_lshl_add_u64 v[190:191], s[42:43], 0, v[132:133]
	s_add_i32 m0, s44, 0x2000
	s_nop 0
	global_load_lds_dwordx4 v[190:191], off
	v_lshl_add_u64 v[190:191], s[22:23], 0, v[128:129]
	s_mov_b32 m0, s28
	s_nop 0
	global_load_lds_dwordx4 v[190:191], off
	s_mov_b32 m0, s29
	s_nop 0
	global_load_lds_dwordx4 v[222:223], off
	s_waitcnt vmcnt(8)
	s_waitcnt lgkmcnt(0)
	s_barrier
; #define PG8_STAGE(bufoff, gbase, voff) do { _Pragma("unroll") for (int _i = 0; _i < 2; ++_i) \
;         __builtin_amdgcn_global_load_lds((const unsigned*)((const char*)(gbase) + (voff)[_i]), (PG8_LAS unsigned*)(lds + (bufoff) + ldsw + _i * 8192), 16, 0, 0); } while (0)
; #define PG8_LDA(dst, b, h) do { _Pragma("unroll") for (int m = 0; m < 4; ++m) _Pragma("unroll") for (int k = 0; k < 2; ++k) dst[m][k] = *(const PG8_LAS bf16x8*)(lds + PG8_SA(b, h) + aoff + m * 2048 + k * 1024); } while (0)
; #define PG8_LDB(dst, b, h) do { _Pragma("unroll") for (int n = 0; n < 2; ++n) _Pragma("unroll") for (int k = 0; k < 2; ++k) dst[n][k] = *(const PG8_LAS bf16x8*)(lds + PG8_SB(b, h) + boff + n * 2048 + k * 1024); } while (0)
; #define PG8_MMA(ai, bj, At, Bt) do { __builtin_amdgcn_s_setprio(1); _Pragma("unroll") for (int m = 0; m < 4; ++m) _Pragma("unroll") for (int n = 0; n < 2; ++n) _Pragma("unroll") for (int k = 0; k < 2; ++k) \
;         acc[ai][bj][m][n] = __builtin_amdgcn_mfma_f32_16x16x32_bf16(Bt[n][k], At[m][k], acc[ai][bj][m][n], 0, 0, 0); __builtin_amdgcn_s_setprio(0); } while (0)
; #define PG8_WAIT_V(n) asm volatile("s_waitcnt vmcnt(" #n ")" ::: "memory")
; #define PG8_WAIT_L(n) asm volatile("s_waitcnt lgkmcnt(" #n ")" ::: "memory")
; #define PG8_BAR __builtin_amdgcn_s_barrier()
; #define PG8_SCHED __builtin_amdgcn_sched_barrier(0)
; template <class Epi, class Sched, bool ALIGN_EPI = false, bool SP2 = false>
; __device__ __forceinline__ void gemm_phase(PG8_LAS unsigned char* lds, const Gemm g, const Sched& S, const Epi& E) {
;     ...
;             PG8_WAIT_V(8); PG8_WAIT_L(0); PG8_BAR; PG8_MMA(1, 0, At, B0); PG8_MMA(1, 1, At, B1); PG8_BAR; PG8_SCHED;
;             PG8_LDB(B0, 1, 0); PG8_LDB(B1, 1, 1); PG8_SCHED; PG8_LDA(At, 1, 0); PG8_STAGE(PG8_SA(0, 1), a2 + hstep, voffA);
;             PG8_WAIT_V(8); PG8_WAIT_L(0); PG8_BAR; PG8_MMA(0, 0, At, B0); PG8_MMA(0, 1, At, B1); PG8_BAR; PG8_SCHED;
	s_setprio 1
	s_waitcnt lgkmcnt(0)
	v_mfma_f32_16x16x32_bf16 v[60:63], v[146:149], v[178:181], v[60:63]
	v_mfma_f32_16x16x32_bf16 v[52:55], v[154:157], v[178:181], v[52:55]
	v_mfma_f32_16x16x32_bf16 v[44:47], v[146:149], v[194:197], v[44:47]
	v_mfma_f32_16x16x32_bf16 v[36:39], v[154:157], v[194:197], v[36:39]
	v_mfma_f32_16x16x32_bf16 v[28:31], v[146:149], v[202:205], v[28:31]
	v_mfma_f32_16x16x32_bf16 v[20:23], v[154:157], v[202:205], v[20:23]
	v_mfma_f32_16x16x32_bf16 v[12:15], v[146:149], v[214:217], v[12:15]
	v_mfma_f32_16x16x32_bf16 v[4:7], v[154:157], v[214:217], v[4:7]
	v_mfma_f32_16x16x32_bf16 v[60:63], v[150:153], v[182:185], v[60:63]
	v_mfma_f32_16x16x32_bf16 v[52:55], v[158:161], v[182:185], v[52:55]
	v_mfma_f32_16x16x32_bf16 v[44:47], v[150:153], v[198:201], v[44:47]
	v_mfma_f32_16x16x32_bf16 v[36:39], v[158:161], v[198:201], v[36:39]
	v_mfma_f32_16x16x32_bf16 v[28:31], v[150:153], v[210:213], v[28:31]
	v_mfma_f32_16x16x32_bf16 v[20:23], v[158:161], v[210:213], v[20:23]
	v_mfma_f32_16x16x32_bf16 v[12:15], v[150:153], v[218:221], v[12:15]
	v_mfma_f32_16x16x32_bf16 v[4:7], v[158:161], v[218:221], v[4:7]
	s_setprio 0
	s_setprio 1
	v_mfma_f32_16x16x32_bf16 v[56:59], v[162:165], v[178:181], v[56:59]
	v_mfma_f32_16x16x32_bf16 v[48:51], v[170:173], v[178:181], v[48:51]
	v_mfma_f32_16x16x32_bf16 v[40:43], v[162:165], v[194:197], v[40:43]
	v_mfma_f32_16x16x32_bf16 v[32:35], v[170:173], v[194:197], v[32:35]
	v_mfma_f32_16x16x32_bf16 v[24:27], v[162:165], v[202:205], v[24:27]
	v_mfma_f32_16x16x32_bf16 v[16:19], v[170:173], v[202:205], v[16:19]
	v_mfma_f32_16x16x32_bf16 v[8:11], v[162:165], v[214:217], v[8:11]
	v_mfma_f32_16x16x32_bf16 v[0:3], v[170:173], v[214:217], v[0:3]
	v_mfma_f32_16x16x32_bf16 v[56:59], v[166:169], v[182:185], v[56:59]
	v_mfma_f32_16x16x32_bf16 v[48:51], v[174:177], v[182:185], v[48:51]
	v_mfma_f32_16x16x32_bf16 v[40:43], v[166:169], v[198:201], v[40:43]
	v_mfma_f32_16x16x32_bf16 v[32:35], v[174:177], v[198:201], v[32:35]
	v_mfma_f32_16x16x32_bf16 v[24:27], v[166:169], v[210:213], v[24:27]
	v_mfma_f32_16x16x32_bf16 v[16:19], v[174:177], v[210:213], v[16:19]
	v_mfma_f32_16x16x32_bf16 v[8:11], v[166:169], v[218:221], v[8:11]
	v_mfma_f32_16x16x32_bf16 v[0:3], v[174:177], v[218:221], v[0:3]
	s_setprio 0
	s_barrier
	s_add_i32 s42, 0, 0x18000
	s_add_i32 s43, 0, 0x1c000
	v_add_u32_e32 v158, s42, v144
	v_add_u32_e32 v174, s43, v144
	ds_read_b128 v[146:149], v158
	ds_read_b128 v[150:153], v158 offset:1024
	ds_read_b128 v[154:157], v158 offset:2048
	ds_read_b128 v[158:161], v158 offset:3072
	ds_read_b128 v[162:165], v174
	ds_read_b128 v[166:169], v174 offset:1024
	ds_read_b128 v[170:173], v174 offset:2048
	ds_read_b128 v[174:177], v174 offset:3072
	s_add_u32 s22, s22, 0x40000
	s_addc_u32 s23, s23, 0
	s_mov_b32 m0, s30
	v_lshl_add_u64 v[224:225], s[22:23], 0, v[128:129]
	ds_read_b128 v[178:181], v145 offset:32768
	ds_read_b128 v[182:185], v145 offset:33792
	ds_read_b128 v[194:197], v145 offset:34816
	ds_read_b128 v[198:201], v145 offset:35840
	ds_read_b128 v[202:205], v145 offset:36864
	ds_read_b128 v[210:213], v145 offset:37888
	ds_read_b128 v[214:217], v145 offset:38912
	ds_read_b128 v[218:221], v145 offset:39936
	global_load_lds_dwordx4 v[224:225], off
	v_lshl_add_u64 v[224:225], s[22:23], 0, v[130:131]
	s_mov_b32 m0, s31
	s_nop 0
	global_load_lds_dwordx4 v[224:225], off
	s_waitcnt vmcnt(8)
	s_waitcnt lgkmcnt(0)
	s_barrier
	s_setprio 1
	s_waitcnt lgkmcnt(0)
	v_mfma_f32_16x16x32_bf16 v[124:127], v[146:149], v[178:181], v[124:127]
	v_mfma_f32_16x16x32_bf16 v[116:119], v[154:157], v[178:181], v[116:119]
	v_mfma_f32_16x16x32_bf16 v[108:111], v[146:149], v[194:197], v[108:111]
	v_mfma_f32_16x16x32_bf16 v[100:103], v[154:157], v[194:197], v[100:103]
	v_mfma_f32_16x16x32_bf16 v[92:95], v[146:149], v[202:205], v[92:95]
	v_mfma_f32_16x16x32_bf16 v[84:87], v[154:157], v[202:205], v[84:87]
	v_mfma_f32_16x16x32_bf16 v[76:79], v[146:149], v[214:217], v[76:79]
	v_mfma_f32_16x16x32_bf16 v[68:71], v[154:157], v[214:217], v[68:71]
	v_mfma_f32_16x16x32_bf16 v[124:127], v[150:153], v[182:185], v[124:127]
	v_mfma_f32_16x16x32_bf16 v[116:119], v[158:161], v[182:185], v[116:119]
	v_mfma_f32_16x16x32_bf16 v[108:111], v[150:153], v[198:201], v[108:111]
	v_mfma_f32_16x16x32_bf16 v[100:103], v[158:161], v[198:201], v[100:103]
	v_mfma_f32_16x16x32_bf16 v[92:95], v[150:153], v[210:213], v[92:95]
	v_mfma_f32_16x16x32_bf16 v[84:87], v[158:161], v[210:213], v[84:87]
	v_mfma_f32_16x16x32_bf16 v[76:79], v[150:153], v[218:221], v[76:79]
	v_mfma_f32_16x16x32_bf16 v[68:71], v[158:161], v[218:221], v[68:71]
	s_setprio 0
	s_setprio 1
	v_mfma_f32_16x16x32_bf16 v[120:123], v[162:165], v[178:181], v[120:123]
	v_mfma_f32_16x16x32_bf16 v[112:115], v[170:173], v[178:181], v[112:115]
	v_mfma_f32_16x16x32_bf16 v[104:107], v[162:165], v[194:197], v[104:107]
	v_mfma_f32_16x16x32_bf16 v[96:99], v[170:173], v[194:197], v[96:99]
	v_mfma_f32_16x16x32_bf16 v[88:91], v[162:165], v[202:205], v[88:91]
	v_mfma_f32_16x16x32_bf16 v[80:83], v[170:173], v[202:205], v[80:83]
	v_mfma_f32_16x16x32_bf16 v[72:75], v[162:165], v[214:217], v[72:75]
	v_mfma_f32_16x16x32_bf16 v[64:67], v[170:173], v[214:217], v[64:67]
	v_mfma_f32_16x16x32_bf16 v[120:123], v[166:169], v[182:185], v[120:123]
	v_mfma_f32_16x16x32_bf16 v[112:115], v[174:177], v[182:185], v[112:115]
	v_mfma_f32_16x16x32_bf16 v[104:107], v[166:169], v[198:201], v[104:107]
	v_mfma_f32_16x16x32_bf16 v[96:99], v[174:177], v[198:201], v[96:99]
	v_mfma_f32_16x16x32_bf16 v[88:91], v[166:169], v[210:213], v[88:91]
	v_mfma_f32_16x16x32_bf16 v[80:83], v[174:177], v[210:213], v[80:83]
	v_mfma_f32_16x16x32_bf16 v[72:75], v[166:169], v[218:221], v[72:75]
	v_mfma_f32_16x16x32_bf16 v[64:67], v[174:177], v[218:221], v[64:67]
	s_setprio 0
	s_barrier
; #define PG8_STAGE(bufoff, gbase, voff) do { _Pragma("unroll") for (int _i = 0; _i < 2; ++_i) \
;         __builtin_amdgcn_global_load_lds((const unsigned*)((const char*)(gbase) + (voff)[_i]), (PG8_LAS unsigned*)(lds + (bufoff) + ldsw + _i * 8192), 16, 0, 0); } while (0)
; #define PG8_LDA(dst, b, h) do { _Pragma("unroll") for (int m = 0; m < 4; ++m) _Pragma("unroll") for (int k = 0; k < 2; ++k) dst[m][k] = *(const PG8_LAS bf16x8*)(lds + PG8_SA(b, h) + aoff + m * 2048 + k * 1024); } while (0)
; #define PG8_MMA(ai, bj, At, Bt) do { __builtin_amdgcn_s_setprio(1); _Pragma("unroll") for (int m = 0; m < 4; ++m) _Pragma("unroll") for (int n = 0; n < 2; ++n) _Pragma("unroll") for (int k = 0; k < 2; ++k) \
;         acc[ai][bj][m][n] = __builtin_amdgcn_mfma_f32_16x16x32_bf16(Bt[n][k], At[m][k], acc[ai][bj][m][n], 0, 0, 0); __builtin_amdgcn_s_setprio(0); } while (0)
; #define PG8_WAIT_V(n) asm volatile("s_waitcnt vmcnt(" #n ")" ::: "memory")
; #define PG8_WAIT_L(n) asm volatile("s_waitcnt lgkmcnt(" #n ")" ::: "memory")
; #define PG8_BAR __builtin_amdgcn_s_barrier()
; #define PG8_SCHED __builtin_amdgcn_sched_barrier(0)
; template <class Epi, class Sched, bool ALIGN_EPI = false, bool SP2 = false>
; __device__ __forceinline__ void gemm_phase(PG8_LAS unsigned char* lds, const Gemm g, const Sched& S, const Epi& E) {
;     ...
;         for (int t = 0; t < nt; t += 2) {
;             const bool last = (t == nt - 2);
;             const char* a1 = cA + (size_t)(t + 1) * kstep;
;             const char* a2 = last ? nA : cA + (size_t)(t + 2) * kstep; const char* b2 = last ? nB : cB + (size_t)(t + 2) * kstep;
;             const char* a3 = a2 + kstep; const char* b3 = b2 + kstep;
;     ...
;             PG8_LDA(At, 1, 1); PG8_STAGE(PG8_SB(1, 0), b3, voffB); PG8_STAGE(PG8_SB(1, 1), b3 + hstep, voffB); PG8_STAGE(PG8_SA(1, 0), a3, voffA);
;             PG8_WAIT_V(8); PG8_WAIT_L(0); PG8_BAR; PG8_MMA(1, 0, At, B0); PG8_MMA(1, 1, At, B1); PG8_BAR; PG8_SCHED;
	s_add_i32 s22, s42, s27
	v_lshl_add_u64 v[140:141], v[140:141], 0, s[48:49]
	s_mov_b32 m0, s22
	ds_read_b128 v[178:181], v145 offset:49152
	ds_read_b128 v[182:185], v145 offset:50176
	ds_read_b128 v[194:197], v145 offset:51200
	ds_read_b128 v[198:201], v145 offset:52224
	ds_read_b128 v[202:205], v145 offset:53248
	ds_read_b128 v[210:213], v145 offset:54272
	ds_read_b128 v[214:217], v145 offset:55296
	ds_read_b128 v[218:221], v145 offset:56320
	global_load_lds_dwordx4 v[140:141], off
	s_add_i32 m0, s22, 0x2000
	s_add_u32 s20, s20, 0x40080
	v_lshl_add_u64 v[140:141], v[186:187], 0, s[48:49]
	s_addc_u32 s21, s21, 0
	s_add_i32 s22, s43, s27
	global_load_lds_dwordx4 v[140:141], off
	v_lshl_add_u64 v[140:141], s[20:21], 0, v[188:189]
	s_mov_b32 m0, s22
	s_nop 0
	global_load_lds_dwordx4 v[140:141], off
	v_lshl_add_u64 v[140:141], s[20:21], 0, v[132:133]
	s_add_i32 m0, s22, 0x2000
	s_nop 0
	global_load_lds_dwordx4 v[140:141], off
	v_lshl_add_u64 v[140:141], v[190:191], 0, s[48:49]
	s_mov_b32 m0, s33
	s_nop 0
	global_load_lds_dwordx4 v[140:141], off
	v_lshl_add_u64 v[140:141], v[222:223], 0, s[48:49]
	s_mov_b32 m0, s34
	s_nop 0
	global_load_lds_dwordx4 v[140:141], off
	s_waitcnt vmcnt(8)
	s_waitcnt lgkmcnt(0)
	s_barrier
	s_setprio 1
	s_waitcnt lgkmcnt(0)
	v_mfma_f32_16x16x32_bf16 v[60:63], v[146:149], v[178:181], v[60:63]
	v_mfma_f32_16x16x32_bf16 v[52:55], v[154:157], v[178:181], v[52:55]
	v_mfma_f32_16x16x32_bf16 v[44:47], v[146:149], v[194:197], v[44:47]
	v_mfma_f32_16x16x32_bf16 v[36:39], v[154:157], v[194:197], v[36:39]
	v_mfma_f32_16x16x32_bf16 v[28:31], v[146:149], v[202:205], v[28:31]
	v_mfma_f32_16x16x32_bf16 v[20:23], v[154:157], v[202:205], v[20:23]
	v_mfma_f32_16x16x32_bf16 v[12:15], v[146:149], v[214:217], v[12:15]
	v_mfma_f32_16x16x32_bf16 v[4:7], v[154:157], v[214:217], v[4:7]
	v_mfma_f32_16x16x32_bf16 v[60:63], v[150:153], v[182:185], v[60:63]
	v_mfma_f32_16x16x32_bf16 v[52:55], v[158:161], v[182:185], v[52:55]
	v_mfma_f32_16x16x32_bf16 v[44:47], v[150:153], v[198:201], v[44:47]
	v_mfma_f32_16x16x32_bf16 v[36:39], v[158:161], v[198:201], v[36:39]
	v_mfma_f32_16x16x32_bf16 v[28:31], v[150:153], v[210:213], v[28:31]
	v_mfma_f32_16x16x32_bf16 v[20:23], v[158:161], v[210:213], v[20:23]
	v_mfma_f32_16x16x32_bf16 v[12:15], v[150:153], v[218:221], v[12:15]
	v_mfma_f32_16x16x32_bf16 v[4:7], v[158:161], v[218:221], v[4:7]
	s_setprio 0
	s_setprio 1
	v_mfma_f32_16x16x32_bf16 v[56:59], v[162:165], v[178:181], v[56:59]
	v_mfma_f32_16x16x32_bf16 v[48:51], v[170:173], v[178:181], v[48:51]
	s_add_i32 s41, s41, 2
	s_add_u32 s18, s18, 0x100
	s_addc_u32 s19, s19, 0
	s_add_u32 s39, s39, 0x100
	s_addc_u32 s40, s40, 0
	s_cmp_gt_u32 s41, 13
	v_mfma_f32_16x16x32_bf16 v[40:43], v[162:165], v[194:197], v[40:43]
	v_mfma_f32_16x16x32_bf16 v[32:35], v[170:173], v[194:197], v[32:35]
	v_mfma_f32_16x16x32_bf16 v[24:27], v[162:165], v[202:205], v[24:27]
	v_mfma_f32_16x16x32_bf16 v[16:19], v[170:173], v[202:205], v[16:19]
	v_mfma_f32_16x16x32_bf16 v[8:11], v[162:165], v[214:217], v[8:11]
	v_mfma_f32_16x16x32_bf16 v[0:3], v[170:173], v[214:217], v[0:3]
	v_mfma_f32_16x16x32_bf16 v[56:59], v[166:169], v[182:185], v[56:59]
	v_mfma_f32_16x16x32_bf16 v[48:51], v[174:177], v[182:185], v[48:51]
	v_mfma_f32_16x16x32_bf16 v[40:43], v[166:169], v[198:201], v[40:43]
	v_mfma_f32_16x16x32_bf16 v[32:35], v[174:177], v[198:201], v[32:35]
	v_mfma_f32_16x16x32_bf16 v[24:27], v[166:169], v[210:213], v[24:27]
	v_mfma_f32_16x16x32_bf16 v[16:19], v[174:177], v[210:213], v[16:19]
	v_mfma_f32_16x16x32_bf16 v[8:11], v[166:169], v[218:221], v[8:11]
	v_mfma_f32_16x16x32_bf16 v[0:3], v[174:177], v[218:221], v[0:3]
	s_setprio 0
	s_barrier
	s_cbranch_scc0 .LBB0_1120
	s_and_b64 vcc, exec, s[2:3]
	s_cbranch_vccz .LBB0_1123
	s_barrier

; #define PG8_STAGE(bufoff, gbase, voff) do { _Pragma("unroll") for (int _i = 0; _i < 2; ++_i) \
;         __builtin_amdgcn_global_load_lds((const unsigned*)((const char*)(gbase) + (voff)[_i]), (PG8_LAS unsigned*)(lds + (bufoff) + ldsw + _i * 8192), 16, 0, 0); } while (0)
; #define PG8_LDA(dst, b, h) do { _Pragma("unroll") for (int m = 0; m < 4; ++m) _Pragma("unroll") for (int k = 0; k < 2; ++k) dst[m][k] = *(const PG8_LAS bf16x8*)(lds + PG8_SA(b, h) + aoff + m * 2048 + k * 1024); } while (0)
; #define PG8_LDB(dst, b, h) do { _Pragma("unroll") for (int n = 0; n < 2; ++n) _Pragma("unroll") for (int k = 0; k < 2; ++k) dst[n][k] = *(const PG8_LAS bf16x8*)(lds + PG8_SB(b, h) + boff + n * 2048 + k * 1024); } while (0)
; #define PG8_MMA(ai, bj, At, Bt) do { __builtin_amdgcn_s_setprio(1); _Pragma("unroll") for (int m = 0; m < 4; ++m) _Pragma("unroll") for (int n = 0; n < 2; ++n) _Pragma("unroll") for (int k = 0; k < 2; ++k) \
;         acc[ai][bj][m][n] = __builtin_amdgcn_mfma_f32_16x16x32_bf16(Bt[n][k], At[m][k], acc[ai][bj][m][n], 0, 0, 0); __builtin_amdgcn_s_setprio(0); } while (0)
; #define PG8_WAIT_V(n) asm volatile("s_waitcnt vmcnt(" #n ")" ::: "memory")
; #define PG8_BAR __builtin_amdgcn_s_barrier()
; template <class Epi, class Sched, bool ALIGN_EPI = false, bool SP2 = false>
; __device__ __forceinline__ void gemm_phase(PG8_LAS unsigned char* lds, const Gemm g, const Sched& S, const Epi& E) {
;     ...
;         for (int t = 0; t < nt; t += 2) {
;             const bool last = (t == nt - 2);
;             const char* a1 = cA + (size_t)(t + 1) * kstep;
;             const char* a2 = last ? nA : cA + (size_t)(t + 2) * kstep; const char* b2 = last ? nB : cB + (size_t)(t + 2) * kstep;
;             const char* a3 = a2 + kstep; const char* b3 = b2 + kstep;
;             if (last && has_next) S.a_ready(nxt);
;             if constexpr (SP2) {
;             PG8_LDB(B0, 0, 0); PG8_LDB(B1, 0, 1); PG8_SCHED; PG8_LDA(At, 0, 0); PG8_STAGE(PG8_SA(1, 1), a1 + hstep, voffA);
;             PG8_WAIT_V(8); PG8_WAIT_L(0); PG8_BAR; PG8_MMA(0, 0, At, B0); PG8_MMA(0, 1, At, B1); PG8_BAR; PG8_SCHED;
;             PG8_LDA(At, 0, 1); PG8_STAGE(PG8_SB(0, 0), b2, voffB); PG8_STAGE(PG8_SB(0, 1), b2 + hstep, voffB); PG8_STAGE(PG8_SA(0, 0), a2, voffA);
;             PG8_WAIT_V(8); PG8_WAIT_L(0); PG8_BAR; PG8_MMA(1, 0, At, B0); PG8_MMA(1, 1, At, B1); PG8_BAR; PG8_SCHED;
.LBB0_1198:
	s_add_u32 s6, s18, 0x100
	s_addc_u32 s7, s19, 0
	s_add_i32 s44, 0, 0x10000
	s_cmp_eq_u32 s42, s43
	s_cselect_b32 s23, s13, s7
	s_cselect_b32 s22, s12, s6
	v_add_u32_e32 v150, s44, v154
	s_cselect_b32 s21, s15, s17
	s_cselect_b32 s20, s14, s11
	s_add_i32 s45, 0, 0x14000
	ds_read_b128 v[128:131], v150
	ds_read_b128 v[142:145], v150 offset:1024
	ds_read_b128 v[146:149], v150 offset:2048
	ds_read_b128 v[158:161], v150 offset:3072
	v_add_u32_e32 v150, s45, v154
	ds_read_b128 v[162:165], v150
	ds_read_b128 v[166:169], v150 offset:1024
	ds_read_b128 v[170:173], v150 offset:2048
	ds_read_b128 v[174:177], v150 offset:3072
	v_lshl_add_u64 v[150:151], s[18:19], 0, v[138:139]
	s_add_i32 m0, s29, 0xc000
	ds_read_b128 v[178:181], v156
	ds_read_b128 v[182:185], v156 offset:1024
	ds_read_b128 v[194:197], v156 offset:2048
	ds_read_b128 v[198:201], v156 offset:3072
	ds_read_b128 v[202:205], v156 offset:4096
	ds_read_b128 v[210:213], v156 offset:5120
	ds_read_b128 v[214:217], v156 offset:6144
	ds_read_b128 v[218:221], v156 offset:7168
	global_load_lds_dwordx4 v[150:151], off
	v_lshl_add_u64 v[150:151], s[18:19], 0, v[140:141]
	s_add_i32 m0, s29, 0xe000
	s_nop 0
	global_load_lds_dwordx4 v[150:151], off
	s_waitcnt vmcnt(8)
	s_waitcnt lgkmcnt(0)
	s_barrier
	s_setprio 1
	s_waitcnt lgkmcnt(0)
	v_mfma_f32_16x16x32_bf16 v[124:127], v[128:131], v[178:181], v[124:127]
	v_mfma_f32_16x16x32_bf16 v[120:123], v[146:149], v[178:181], v[120:123]
	v_mfma_f32_16x16x32_bf16 v[108:111], v[128:131], v[194:197], v[108:111]
	v_mfma_f32_16x16x32_bf16 v[104:107], v[146:149], v[194:197], v[104:107]
	v_mfma_f32_16x16x32_bf16 v[92:95], v[128:131], v[202:205], v[92:95]
	v_mfma_f32_16x16x32_bf16 v[88:91], v[146:149], v[202:205], v[88:91]
	v_mfma_f32_16x16x32_bf16 v[76:79], v[128:131], v[214:217], v[76:79]
	v_mfma_f32_16x16x32_bf16 v[72:75], v[146:149], v[214:217], v[72:75]
	v_mfma_f32_16x16x32_bf16 v[124:127], v[142:145], v[182:185], v[124:127]
	v_mfma_f32_16x16x32_bf16 v[120:123], v[158:161], v[182:185], v[120:123]
	v_mfma_f32_16x16x32_bf16 v[108:111], v[142:145], v[198:201], v[108:111]
	v_mfma_f32_16x16x32_bf16 v[104:107], v[158:161], v[198:201], v[104:107]
	v_mfma_f32_16x16x32_bf16 v[92:95], v[142:145], v[210:213], v[92:95]
	v_mfma_f32_16x16x32_bf16 v[88:91], v[158:161], v[210:213], v[88:91]
	v_mfma_f32_16x16x32_bf16 v[76:79], v[142:145], v[218:221], v[76:79]
	v_mfma_f32_16x16x32_bf16 v[72:75], v[158:161], v[218:221], v[72:75]
	s_setprio 0
	s_setprio 1
	v_mfma_f32_16x16x32_bf16 v[116:119], v[162:165], v[178:181], v[116:119]
	v_mfma_f32_16x16x32_bf16 v[112:115], v[170:173], v[178:181], v[112:115]
	v_mfma_f32_16x16x32_bf16 v[100:103], v[162:165], v[194:197], v[100:103]
	v_mfma_f32_16x16x32_bf16 v[96:99], v[170:173], v[194:197], v[96:99]
	v_mfma_f32_16x16x32_bf16 v[84:87], v[162:165], v[202:205], v[84:87]
	v_mfma_f32_16x16x32_bf16 v[80:83], v[170:173], v[202:205], v[80:83]
	v_mfma_f32_16x16x32_bf16 v[68:71], v[162:165], v[214:217], v[68:71]
	v_mfma_f32_16x16x32_bf16 v[64:67], v[170:173], v[214:217], v[64:67]
	v_mfma_f32_16x16x32_bf16 v[116:119], v[166:169], v[182:185], v[116:119]
	v_mfma_f32_16x16x32_bf16 v[112:115], v[174:177], v[182:185], v[112:115]
	v_mfma_f32_16x16x32_bf16 v[100:103], v[166:169], v[198:201], v[100:103]
	v_mfma_f32_16x16x32_bf16 v[96:99], v[174:177], v[198:201], v[96:99]
	v_mfma_f32_16x16x32_bf16 v[84:87], v[166:169], v[210:213], v[84:87]
	v_mfma_f32_16x16x32_bf16 v[80:83], v[174:177], v[210:213], v[80:83]
	v_mfma_f32_16x16x32_bf16 v[68:71], v[166:169], v[218:221], v[68:71]
	v_mfma_f32_16x16x32_bf16 v[64:67], v[174:177], v[218:221], v[64:67]
	s_setprio 0
	s_barrier
	s_add_i32 s18, s44, s28
	v_lshl_add_u64 v[150:151], s[20:21], 0, v[188:189]
	s_mov_b32 m0, s18
	ds_read_b128 v[178:181], v156 offset:16384
	ds_read_b128 v[182:185], v156 offset:17408
	ds_read_b128 v[194:197], v156 offset:18432
	ds_read_b128 v[198:201], v156 offset:19456
	ds_read_b128 v[202:205], v156 offset:20480
	ds_read_b128 v[210:213], v156 offset:21504
	ds_read_b128 v[214:217], v156 offset:22528
	ds_read_b128 v[218:221], v156 offset:23552
	global_load_lds_dwordx4 v[150:151], off
	s_add_i32 m0, s18, 0x2000
	s_add_u32 s18, s20, 0xb0000
	v_lshl_add_u64 v[186:187], s[20:21], 0, v[136:137]
	s_addc_u32 s19, s21, 0
	s_add_i32 s44, s45, s28
	global_load_lds_dwordx4 v[186:187], off
	v_lshl_add_u64 v[190:191], s[18:19], 0, v[188:189]
	s_mov_b32 m0, s44
	v_lshl_add_u64 v[222:223], s[22:23], 0, v[134:135]
	global_load_lds_dwordx4 v[190:191], off
	v_lshl_add_u64 v[190:191], s[18:19], 0, v[136:137]
	s_add_i32 m0, s44, 0x2000
	s_nop 0
	global_load_lds_dwordx4 v[190:191], off
	v_lshl_add_u64 v[190:191], s[22:23], 0, v[132:133]
	s_mov_b32 m0, s29
	s_nop 0
	global_load_lds_dwordx4 v[190:191], off
	s_mov_b32 m0, s30
	s_nop 0
	global_load_lds_dwordx4 v[222:223], off
	s_waitcnt vmcnt(8)
	s_waitcnt lgkmcnt(0)
	s_barrier
; #define PG8_STAGE(bufoff, gbase, voff) do { _Pragma("unroll") for (int _i = 0; _i < 2; ++_i) \
;         __builtin_amdgcn_global_load_lds((const unsigned*)((const char*)(gbase) + (voff)[_i]), (PG8_LAS unsigned*)(lds + (bufoff) + ldsw + _i * 8192), 16, 0, 0); } while (0)
; #define PG8_LDA(dst, b, h) do { _Pragma("unroll") for (int m = 0; m < 4; ++m) _Pragma("unroll") for (int k = 0; k < 2; ++k) dst[m][k] = *(const PG8_LAS bf16x8*)(lds + PG8_SA(b, h) + aoff + m * 2048 + k * 1024); } while (0)
; #define PG8_LDB(dst, b, h) do { _Pragma("unroll") for (int n = 0; n < 2; ++n) _Pragma("unroll") for (int k = 0; k < 2; ++k) dst[n][k] = *(const PG8_LAS bf16x8*)(lds + PG8_SB(b, h) + boff + n * 2048 + k * 1024); } while (0)
; #define PG8_MMA(ai, bj, At, Bt) do { __builtin_amdgcn_s_setprio(1); _Pragma("unroll") for (int m = 0; m < 4; ++m) _Pragma("unroll") for (int n = 0; n < 2; ++n) _Pragma("unroll") for (int k = 0; k < 2; ++k) \
;         acc[ai][bj][m][n] = __builtin_amdgcn_mfma_f32_16x16x32_bf16(Bt[n][k], At[m][k], acc[ai][bj][m][n], 0, 0, 0); __builtin_amdgcn_s_setprio(0); } while (0)
; #define PG8_WAIT_V(n) asm volatile("s_waitcnt vmcnt(" #n ")" ::: "memory")
; #define PG8_WAIT_L(n) asm volatile("s_waitcnt lgkmcnt(" #n ")" ::: "memory")
; #define PG8_BAR __builtin_amdgcn_s_barrier()
; #define PG8_SCHED __builtin_amdgcn_sched_barrier(0)
; template <class Epi, class Sched, bool ALIGN_EPI = false, bool SP2 = false>
; __device__ __forceinline__ void gemm_phase(PG8_LAS unsigned char* lds, const Gemm g, const Sched& S, const Epi& E) {
;     ...
;             PG8_WAIT_V(8); PG8_WAIT_L(0); PG8_BAR; PG8_MMA(1, 0, At, B0); PG8_MMA(1, 1, At, B1); PG8_BAR; PG8_SCHED;
;             PG8_LDB(B0, 1, 0); PG8_LDB(B1, 1, 1); PG8_SCHED; PG8_LDA(At, 1, 0); PG8_STAGE(PG8_SA(0, 1), a2 + hstep, voffA);
;             PG8_WAIT_V(8); PG8_WAIT_L(0); PG8_BAR; PG8_MMA(0, 0, At, B0); PG8_MMA(0, 1, At, B1); PG8_BAR; PG8_SCHED;
	s_setprio 1
	s_waitcnt lgkmcnt(0)
	v_mfma_f32_16x16x32_bf16 v[60:63], v[128:131], v[178:181], v[60:63]
	v_mfma_f32_16x16x32_bf16 v[56:59], v[146:149], v[178:181], v[56:59]
	v_mfma_f32_16x16x32_bf16 v[44:47], v[128:131], v[194:197], v[44:47]
	v_mfma_f32_16x16x32_bf16 v[40:43], v[146:149], v[194:197], v[40:43]
	v_mfma_f32_16x16x32_bf16 v[28:31], v[128:131], v[202:205], v[28:31]
	v_mfma_f32_16x16x32_bf16 v[24:27], v[146:149], v[202:205], v[24:27]
	v_mfma_f32_16x16x32_bf16 v[12:15], v[128:131], v[214:217], v[12:15]
	v_mfma_f32_16x16x32_bf16 v[8:11], v[146:149], v[214:217], v[8:11]
	v_mfma_f32_16x16x32_bf16 v[60:63], v[142:145], v[182:185], v[60:63]
	v_mfma_f32_16x16x32_bf16 v[56:59], v[158:161], v[182:185], v[56:59]
	v_mfma_f32_16x16x32_bf16 v[44:47], v[142:145], v[198:201], v[44:47]
	v_mfma_f32_16x16x32_bf16 v[40:43], v[158:161], v[198:201], v[40:43]
	v_mfma_f32_16x16x32_bf16 v[28:31], v[142:145], v[210:213], v[28:31]
	v_mfma_f32_16x16x32_bf16 v[24:27], v[158:161], v[210:213], v[24:27]
	v_mfma_f32_16x16x32_bf16 v[12:15], v[142:145], v[218:221], v[12:15]
	v_mfma_f32_16x16x32_bf16 v[8:11], v[158:161], v[218:221], v[8:11]
	s_setprio 0
	s_setprio 1
	v_mfma_f32_16x16x32_bf16 v[52:55], v[162:165], v[178:181], v[52:55]
	v_mfma_f32_16x16x32_bf16 v[48:51], v[170:173], v[178:181], v[48:51]
	v_mfma_f32_16x16x32_bf16 v[36:39], v[162:165], v[194:197], v[36:39]
	v_mfma_f32_16x16x32_bf16 v[32:35], v[170:173], v[194:197], v[32:35]
	v_mfma_f32_16x16x32_bf16 v[20:23], v[162:165], v[202:205], v[20:23]
	v_mfma_f32_16x16x32_bf16 v[16:19], v[170:173], v[202:205], v[16:19]
	v_mfma_f32_16x16x32_bf16 v[4:7], v[162:165], v[214:217], v[4:7]
	v_mfma_f32_16x16x32_bf16 v[0:3], v[170:173], v[214:217], v[0:3]
	v_mfma_f32_16x16x32_bf16 v[52:55], v[166:169], v[182:185], v[52:55]
	v_mfma_f32_16x16x32_bf16 v[48:51], v[174:177], v[182:185], v[48:51]
	v_mfma_f32_16x16x32_bf16 v[36:39], v[166:169], v[198:201], v[36:39]
	v_mfma_f32_16x16x32_bf16 v[32:35], v[174:177], v[198:201], v[32:35]
	v_mfma_f32_16x16x32_bf16 v[20:23], v[166:169], v[210:213], v[20:23]
	v_mfma_f32_16x16x32_bf16 v[16:19], v[174:177], v[210:213], v[16:19]
	v_mfma_f32_16x16x32_bf16 v[4:7], v[166:169], v[218:221], v[4:7]
	v_mfma_f32_16x16x32_bf16 v[0:3], v[174:177], v[218:221], v[0:3]
	s_setprio 0
	s_barrier
	s_add_i32 s44, 0, 0x18000
	v_add_u32_e32 v157, s44, v154
	s_add_i32 s45, 0, 0x1c000
	ds_read_b128 v[128:131], v157
	ds_read_b128 v[142:145], v157 offset:1024
	ds_read_b128 v[146:149], v157 offset:2048
	ds_read_b128 v[158:161], v157 offset:3072
	v_add_u32_e32 v157, s45, v154
	ds_read_b128 v[162:165], v157
	ds_read_b128 v[166:169], v157 offset:1024
	ds_read_b128 v[170:173], v157 offset:2048
	ds_read_b128 v[174:177], v157 offset:3072
	s_add_u32 s18, s22, 0xb0000
	s_addc_u32 s19, s23, 0
	s_mov_b32 m0, s31
	v_lshl_add_u64 v[224:225], s[18:19], 0, v[132:133]
	ds_read_b128 v[178:181], v156 offset:32768
	ds_read_b128 v[182:185], v156 offset:33792
	ds_read_b128 v[194:197], v156 offset:34816
	ds_read_b128 v[198:201], v156 offset:35840
	ds_read_b128 v[202:205], v156 offset:36864
	ds_read_b128 v[210:213], v156 offset:37888
	ds_read_b128 v[214:217], v156 offset:38912
	ds_read_b128 v[218:221], v156 offset:39936
	global_load_lds_dwordx4 v[224:225], off
	v_lshl_add_u64 v[224:225], s[18:19], 0, v[134:135]
	s_mov_b32 m0, s33
	s_nop 0
	global_load_lds_dwordx4 v[224:225], off
	s_waitcnt vmcnt(8)
	s_waitcnt lgkmcnt(0)
	s_barrier
	s_setprio 1
	s_waitcnt lgkmcnt(0)
	v_mfma_f32_16x16x32_bf16 v[124:127], v[128:131], v[178:181], v[124:127]
	v_mfma_f32_16x16x32_bf16 v[120:123], v[146:149], v[178:181], v[120:123]
	v_mfma_f32_16x16x32_bf16 v[108:111], v[128:131], v[194:197], v[108:111]
	v_mfma_f32_16x16x32_bf16 v[104:107], v[146:149], v[194:197], v[104:107]
	v_mfma_f32_16x16x32_bf16 v[92:95], v[128:131], v[202:205], v[92:95]
	v_mfma_f32_16x16x32_bf16 v[88:91], v[146:149], v[202:205], v[88:91]
	v_mfma_f32_16x16x32_bf16 v[76:79], v[128:131], v[214:217], v[76:79]
	v_mfma_f32_16x16x32_bf16 v[72:75], v[146:149], v[214:217], v[72:75]
	v_mfma_f32_16x16x32_bf16 v[124:127], v[142:145], v[182:185], v[124:127]
	v_mfma_f32_16x16x32_bf16 v[120:123], v[158:161], v[182:185], v[120:123]
	v_mfma_f32_16x16x32_bf16 v[108:111], v[142:145], v[198:201], v[108:111]
	v_mfma_f32_16x16x32_bf16 v[104:107], v[158:161], v[198:201], v[104:107]
	v_mfma_f32_16x16x32_bf16 v[92:95], v[142:145], v[210:213], v[92:95]
	v_mfma_f32_16x16x32_bf16 v[88:91], v[158:161], v[210:213], v[88:91]
	v_mfma_f32_16x16x32_bf16 v[76:79], v[142:145], v[218:221], v[76:79]
	v_mfma_f32_16x16x32_bf16 v[72:75], v[158:161], v[218:221], v[72:75]
	s_setprio 0
	s_setprio 1
	v_mfma_f32_16x16x32_bf16 v[116:119], v[162:165], v[178:181], v[116:119]
	v_mfma_f32_16x16x32_bf16 v[112:115], v[170:173], v[178:181], v[112:115]
	v_mfma_f32_16x16x32_bf16 v[100:103], v[162:165], v[194:197], v[100:103]
	v_mfma_f32_16x16x32_bf16 v[96:99], v[170:173], v[194:197], v[96:99]
	v_mfma_f32_16x16x32_bf16 v[84:87], v[162:165], v[202:205], v[84:87]
	v_mfma_f32_16x16x32_bf16 v[80:83], v[170:173], v[202:205], v[80:83]
	v_mfma_f32_16x16x32_bf16 v[68:71], v[162:165], v[214:217], v[68:71]
	v_mfma_f32_16x16x32_bf16 v[64:67], v[170:173], v[214:217], v[64:67]
	v_mfma_f32_16x16x32_bf16 v[116:119], v[166:169], v[182:185], v[116:119]
	v_mfma_f32_16x16x32_bf16 v[112:115], v[174:177], v[182:185], v[112:115]
	v_mfma_f32_16x16x32_bf16 v[100:103], v[166:169], v[198:201], v[100:103]
	v_mfma_f32_16x16x32_bf16 v[96:99], v[174:177], v[198:201], v[96:99]
	v_mfma_f32_16x16x32_bf16 v[84:87], v[166:169], v[210:213], v[84:87]
	v_mfma_f32_16x16x32_bf16 v[80:83], v[174:177], v[210:213], v[80:83]
	v_mfma_f32_16x16x32_bf16 v[68:71], v[166:169], v[218:221], v[68:71]
	v_mfma_f32_16x16x32_bf16 v[64:67], v[174:177], v[218:221], v[64:67]
	s_setprio 0
	s_barrier
; __device__ __forceinline__ u32x4 pack8(const f32x4 a, const f32x4 b) { u32x4 w; w.x = cvt_pk_bf16(a[0], a[1]); w.y = cvt_pk_bf16(a[2], a[3]); w.z = cvt_pk_bf16(b[0], b[1]); w.w = cvt_pk_bf16(b[2], b[3]); return w; }
; #define PG8_STAGE(bufoff, gbase, voff) do { _Pragma("unroll") for (int _i = 0; _i < 2; ++_i) \
;         __builtin_amdgcn_global_load_lds((const unsigned*)((const char*)(gbase) + (voff)[_i]), (PG8_LAS unsigned*)(lds + (bufoff) + ldsw + _i * 8192), 16, 0, 0); } while (0)
; #define PG8_LDA(dst, b, h) do { _Pragma("unroll") for (int m = 0; m < 4; ++m) _Pragma("unroll") for (int k = 0; k < 2; ++k) dst[m][k] = *(const PG8_LAS bf16x8*)(lds + PG8_SA(b, h) + aoff + m * 2048 + k * 1024); } while (0)
; #define PG8_MMA(ai, bj, At, Bt) do { __builtin_amdgcn_s_setprio(1); _Pragma("unroll") for (int m = 0; m < 4; ++m) _Pragma("unroll") for (int n = 0; n < 2; ++n) _Pragma("unroll") for (int k = 0; k < 2; ++k) \
;         acc[ai][bj][m][n] = __builtin_amdgcn_mfma_f32_16x16x32_bf16(Bt[n][k], At[m][k], acc[ai][bj][m][n], 0, 0, 0); __builtin_amdgcn_s_setprio(0); } while (0)
; #define PG8_BAR __builtin_amdgcn_s_barrier()
;     __device__ __forceinline__ void operator()(const f32x4 (&acc)[2][2][4][2], const Unit& u, int wr, int wc, int fr, int fq) const {
;     ...
;             for (int m = 0; m < 4; ++m) { const size_t ro = (size_t)(row0 + ai * HALF + m * 16) * 1024 + col0;
; #pragma unroll
;                 for (int bj = 0; bj < 2; ++bj) { const size_t o = ro + bj * HALF;
;                     if (part) *(u32x4*)(pbase + o) = pack8(acc[ai][bj][m][0], acc[ai][bj][m][1]);
;                     else { f32x4 r0, r1;
;                         if (X32) { r0 = *(const f32x4*)(X32 + o); r1 = *(const f32x4*)(X32 + o + 4); }
;                         else { const u32x4 hw = *(const u32x4*)(H + o); r0 = (f32x4){bflo(hw.x), bfhi(hw.x), bflo(hw.y), bfhi(hw.y)}; r1 = (f32x4){bflo(hw.z), bfhi(hw.z), bflo(hw.w), bfhi(hw.w)}; }
; template <class Epi, class Sched, bool ALIGN_EPI = false, bool SP2 = false>
; __device__ __forceinline__ void gemm_phase(PG8_LAS unsigned char* lds, const Gemm g, const Sched& S, const Epi& E) {
;     ...
;             PG8_LDA(At, 1, 1); PG8_STAGE(PG8_SB(1, 0), b3, voffB); PG8_STAGE(PG8_SB(1, 1), b3 + hstep, voffB); PG8_STAGE(PG8_SA(1, 0), a3, voffA);
;             PG8_WAIT_V(8); PG8_WAIT_L(0); PG8_BAR; PG8_MMA(1, 0, At, B0); PG8_MMA(1, 1, At, B1); PG8_BAR; PG8_SCHED;
	s_add_i32 s18, s44, s28
	v_lshl_add_u64 v[150:151], v[150:151], 0, s[48:49]
	s_mov_b32 m0, s18
	ds_read_b128 v[178:181], v156 offset:49152
	ds_read_b128 v[182:185], v156 offset:50176
	ds_read_b128 v[194:197], v156 offset:51200
	ds_read_b128 v[198:201], v156 offset:52224
	ds_read_b128 v[202:205], v156 offset:53248
	ds_read_b128 v[210:213], v156 offset:54272
	ds_read_b128 v[214:217], v156 offset:55296
	ds_read_b128 v[218:221], v156 offset:56320
	global_load_lds_dwordx4 v[150:151], off
	s_add_i32 m0, s18, 0x2000
	s_add_u32 s18, s20, 0xb0080
	v_lshl_add_u64 v[150:151], v[186:187], 0, s[48:49]
	s_addc_u32 s19, s21, 0
	s_add_i32 s20, s45, s28
	global_load_lds_dwordx4 v[150:151], off
	v_lshl_add_u64 v[150:151], s[18:19], 0, v[188:189]
	s_mov_b32 m0, s20
	s_nop 0
	global_load_lds_dwordx4 v[150:151], off
	v_lshl_add_u64 v[150:151], s[18:19], 0, v[136:137]
	s_add_i32 m0, s20, 0x2000
	s_nop 0
	global_load_lds_dwordx4 v[150:151], off
	v_lshl_add_u64 v[150:151], v[190:191], 0, s[48:49]
	s_mov_b32 m0, s34
	s_nop 0
	global_load_lds_dwordx4 v[150:151], off
	v_lshl_add_u64 v[150:151], v[222:223], 0, s[48:49]
	s_mov_b32 m0, s35
	s_nop 0
	global_load_lds_dwordx4 v[150:151], off
	s_waitcnt vmcnt(8)
	s_waitcnt lgkmcnt(0)
	s_barrier
	s_setprio 1
	s_waitcnt lgkmcnt(0)
	v_mfma_f32_16x16x32_bf16 v[60:63], v[128:131], v[178:181], v[60:63]
	v_mfma_f32_16x16x32_bf16 v[56:59], v[146:149], v[178:181], v[56:59]
	v_mfma_f32_16x16x32_bf16 v[44:47], v[128:131], v[194:197], v[44:47]
	v_mfma_f32_16x16x32_bf16 v[40:43], v[146:149], v[194:197], v[40:43]
	v_mfma_f32_16x16x32_bf16 v[28:31], v[128:131], v[202:205], v[28:31]
	v_mfma_f32_16x16x32_bf16 v[24:27], v[146:149], v[202:205], v[24:27]
	v_mfma_f32_16x16x32_bf16 v[12:15], v[128:131], v[214:217], v[12:15]
	v_mfma_f32_16x16x32_bf16 v[8:11], v[146:149], v[214:217], v[8:11]
	v_mfma_f32_16x16x32_bf16 v[60:63], v[142:145], v[182:185], v[60:63]
	v_mfma_f32_16x16x32_bf16 v[56:59], v[158:161], v[182:185], v[56:59]
	v_mfma_f32_16x16x32_bf16 v[44:47], v[142:145], v[198:201], v[44:47]
	v_mfma_f32_16x16x32_bf16 v[40:43], v[158:161], v[198:201], v[40:43]
	v_mfma_f32_16x16x32_bf16 v[28:31], v[142:145], v[210:213], v[28:31]
	v_mfma_f32_16x16x32_bf16 v[24:27], v[158:161], v[210:213], v[24:27]
	v_mfma_f32_16x16x32_bf16 v[12:15], v[142:145], v[218:221], v[12:15]
	v_mfma_f32_16x16x32_bf16 v[8:11], v[158:161], v[218:221], v[8:11]
	s_setprio 0
	s_setprio 1
	v_mfma_f32_16x16x32_bf16 v[52:55], v[162:165], v[178:181], v[52:55]
	v_mfma_f32_16x16x32_bf16 v[48:51], v[170:173], v[178:181], v[48:51]
	s_add_i32 s20, s43, 2
	s_add_u32 s11, s11, 0x100
	s_addc_u32 s17, s17, 0
	s_cmp_ge_u32 s43, s42
	s_mov_b64 s[18:19], s[6:7]
	s_mov_b32 s43, s20
	v_mfma_f32_16x16x32_bf16 v[36:39], v[162:165], v[194:197], v[36:39]
	v_mfma_f32_16x16x32_bf16 v[32:35], v[170:173], v[194:197], v[32:35]
	v_mfma_f32_16x16x32_bf16 v[20:23], v[162:165], v[202:205], v[20:23]
	v_mfma_f32_16x16x32_bf16 v[16:19], v[170:173], v[202:205], v[16:19]
	v_mfma_f32_16x16x32_bf16 v[4:7], v[162:165], v[214:217], v[4:7]
	v_mfma_f32_16x16x32_bf16 v[0:3], v[170:173], v[214:217], v[0:3]
	v_mfma_f32_16x16x32_bf16 v[52:55], v[166:169], v[182:185], v[52:55]
	v_mfma_f32_16x16x32_bf16 v[48:51], v[174:177], v[182:185], v[48:51]
	v_mfma_f32_16x16x32_bf16 v[36:39], v[166:169], v[198:201], v[36:39]
	v_mfma_f32_16x16x32_bf16 v[32:35], v[174:177], v[198:201], v[32:35]
	v_mfma_f32_16x16x32_bf16 v[20:23], v[166:169], v[210:213], v[20:23]
	v_mfma_f32_16x16x32_bf16 v[16:19], v[174:177], v[210:213], v[16:19]
	v_mfma_f32_16x16x32_bf16 v[4:7], v[166:169], v[218:221], v[4:7]
	v_mfma_f32_16x16x32_bf16 v[0:3], v[174:177], v[218:221], v[0:3]
	s_setprio 0
	s_barrier
	s_cbranch_scc0 .LBB0_1198
	s_cmp_lg_u32 s42, 44
	s_cbranch_scc1 .Lp7_nopre
	v_readlane_b32 s16, v254, 17
	v_readlane_b32 s17, v254, 18
	v_lshl_add_u32 v150, s40, 8, v153
	v_lshl_or_b32 v151, s41, 8, v155
	v_lshlrev_b32_e32 v150, 11, v150
	v_lshl_add_u32 v150, v151, 1, v150
	s_mov_b64 s[6:7], s[16:17]
	global_load_dwordx4 v[128:131], v150, s[6:7]
	global_load_dwordx4 v[142:145], v150, s[6:7] offset:256
	s_add_u32 s6, s16, 0x8000
	s_addc_u32 s7, s17, 0
	global_load_dwordx4 v[146:149], v150, s[6:7]
	global_load_dwordx4 v[158:161], v150, s[6:7] offset:256
	s_add_u32 s6, s16, 0x10000
	s_addc_u32 s7, s17, 0
	global_load_dwordx4 v[162:165], v150, s[6:7]
	global_load_dwordx4 v[166:169], v150, s[6:7] offset:256
	s_add_u32 s6, s16, 0x18000
	s_addc_u32 s7, s17, 0
	global_load_dwordx4 v[170:173], v150, s[6:7]
	global_load_dwordx4 v[174:177], v150, s[6:7] offset:256
	s_add_u32 s6, s16, 0x40000
	s_addc_u32 s7, s17, 0
	global_load_dwordx4 v[178:181], v150, s[6:7]
	global_load_dwordx4 v[182:185], v150, s[6:7] offset:256
	s_add_u32 s6, s16, 0x48000
	s_addc_u32 s7, s17, 0
	global_load_dwordx4 v[194:197], v150, s[6:7]
	global_load_dwordx4 v[198:201], v150, s[6:7] offset:256
	s_add_u32 s6, s16, 0x50000
	s_addc_u32 s7, s17, 0
	global_load_dwordx4 v[202:205], v150, s[6:7]
	global_load_dwordx4 v[210:213], v150, s[6:7] offset:256
	s_add_u32 s6, s16, 0x58000
	s_addc_u32 s7, s17, 0
	global_load_dwordx4 v[214:217], v150, s[6:7]
	global_load_dwordx4 v[218:221], v150, s[6:7] offset:256
